# v30 plus snake ordering of the 8 MFMAs per k-group in GEMM K-loops (exactly one source operand changes between consecutive MFMAs)
# speedup vs baseline: 1.0066x; 1.0010x over previous
; #define PG8_STAGE(bufoff, gbase, voff) do { _Pragma("unroll") for (int _i = 0; _i < 2; ++_i) \
;         __builtin_amdgcn_global_load_lds((const unsigned*)((const char*)(gbase) + (voff)[_i]), (LAS unsigned*)(lds + (bufoff) + ldsw + _i * 8192), 16, 0, 0); } while (0)
; #define PG8_LDA(dst, b, h) do { _Pragma("unroll") for (int m = 0; m < 4; ++m) _Pragma("unroll") for (int k = 0; k < 2; ++k) dst[m][k] = *(const LAS bf16x8*)(lds + PG8_SA(b, h) + aoff + m * 2048 + k * 1024); } while (0)
; #define PG8_LDB(dst, b, h) do { _Pragma("unroll") for (int n = 0; n < 2; ++n) _Pragma("unroll") for (int k = 0; k < 2; ++k) dst[n][k] = *(const LAS bf16x8*)(lds + PG8_SB(b, h) + boff + n * 2048 + k * 1024); } while (0)
; #define PG8_MMA(ai, bj, At, Bt) do { __builtin_amdgcn_s_setprio(1); _Pragma("unroll") for (int m = 0; m < 4; ++m) _Pragma("unroll") for (int n = 0; n < 2; ++n) _Pragma("unroll") for (int k = 0; k < 2; ++k) \
;         acc[ai][bj][m][n] = __builtin_amdgcn_mfma_f32_16x16x32_bf16(Bt[n][k], At[m][k], acc[ai][bj][m][n], 0, 0, 0); __builtin_amdgcn_s_setprio(0); } while (0)
; #define PG8_WAIT_L(n) asm volatile("s_waitcnt lgkmcnt(" #n ")" ::: "memory")
; #define PG8_BAR __builtin_amdgcn_s_barrier()
; #define PG8_SCHED __builtin_amdgcn_sched_barrier(0)
; template <class Epi>
; DEVI void gemm_phase(LAS unsigned char* lds, const bf16_t* gA, const bf16_t* gBt, const int lda, const int ldb, const int K, const StaticOrder S_, const Epi E) {
;     ...
;             PG8_LDB(B0, 0, 0); PG8_SCHED; PG8_LDA(At, 0, 0); PG8_STAGE(PG8_SA(1, 1), a1 + hstepA, voffA);
;             PG8_WAIT_L(8); PG8_BAR; PG8_WAIT_L(0); PG8_MMA(0, 0, At, B0); PG8_BAR; PG8_SCHED;
;             PG8_LDB(B1, 0, 1); PG8_STAGE(PG8_SB(0, 0), b2, voffB);
;             PG8_BAR; PG8_WAIT_L(0); PG8_MMA(0, 1, At, B1); PG8_BAR;
;             PG8_LDA(At, 0, 1); PG8_STAGE(PG8_SA(0, 0), a2, voffA);
;             PG8_BAR; PG8_WAIT_L(0); PG8_MMA(1, 0, At, B0); PG8_BAR; PG8_SCHED;
.LBB0_259:
	ds_read_b128 v[158:161], v151
	ds_read_b128 v[162:165], v151 offset:1024
	ds_read_b128 v[166:169], v151 offset:2048
	ds_read_b128 v[170:173], v151 offset:3072
	s_add_i32 s79, s26, 2
	s_add_u32 s28, s24, 0x80
	s_addc_u32 s27, s25, 0
	s_cmp_eq_u32 s96, s26
	s_cselect_b32 s26, s4, s28
	s_cselect_b32 s27, s5, s27
	s_cselect_b32 s29, s23, s78
	s_cselect_b32 s28, s22, s77
	v_lshl_add_u64 v[144:145], s[24:25], 0, v[138:139]
	s_add_i32 m0, s37, 0xc000
	ds_read_b128 v[174:177], v152
	ds_read_b128 v[178:181], v152 offset:1024
	ds_read_b128 v[182:185], v152 offset:2048
	ds_read_b128 v[186:189], v152 offset:3072
	ds_read_b128 v[190:193], v152 offset:4096
	ds_read_b128 v[198:201], v152 offset:5120
	ds_read_b128 v[202:205], v152 offset:6144
	ds_read_b128 v[206:209], v152 offset:7168
	global_load_lds_dwordx4 v[144:145], off
	v_lshl_add_u64 v[144:145], s[24:25], 0, v[140:141]
	s_add_i32 m0, s37, 0xe000
	s_nop 0
	global_load_lds_dwordx4 v[144:145], off
	s_waitcnt lgkmcnt(8)
	s_barrier
	s_waitcnt lgkmcnt(0)
	s_waitcnt lgkmcnt(0)
	v_mfma_f32_16x16x32_bf16 v[120:123], v[158:161], v[174:177], v[120:123]
	v_mfma_f32_16x16x32_bf16 v[116:119], v[166:169], v[174:177], v[116:119]
	v_mfma_f32_16x16x32_bf16 v[100:103], v[166:169], v[182:185], v[100:103]
	v_mfma_f32_16x16x32_bf16 v[108:111], v[158:161], v[182:185], v[108:111]
	v_mfma_f32_16x16x32_bf16 v[92:95], v[158:161], v[190:193], v[92:95]
	v_mfma_f32_16x16x32_bf16 v[84:87], v[166:169], v[190:193], v[84:87]
	v_mfma_f32_16x16x32_bf16 v[68:71], v[166:169], v[202:205], v[68:71]
	v_mfma_f32_16x16x32_bf16 v[76:79], v[158:161], v[202:205], v[76:79]
	v_mfma_f32_16x16x32_bf16 v[120:123], v[162:165], v[178:181], v[120:123]
	v_mfma_f32_16x16x32_bf16 v[116:119], v[170:173], v[178:181], v[116:119]
	v_mfma_f32_16x16x32_bf16 v[100:103], v[170:173], v[186:189], v[100:103]
	v_mfma_f32_16x16x32_bf16 v[108:111], v[162:165], v[186:189], v[108:111]
	v_mfma_f32_16x16x32_bf16 v[92:95], v[162:165], v[198:201], v[92:95]
	v_mfma_f32_16x16x32_bf16 v[84:87], v[170:173], v[198:201], v[84:87]
	v_mfma_f32_16x16x32_bf16 v[68:71], v[170:173], v[206:209], v[68:71]
	v_mfma_f32_16x16x32_bf16 v[76:79], v[162:165], v[206:209], v[76:79]
	s_barrier
	s_add_i32 vcc_lo, s41, s36
	v_lshl_add_u64 v[144:145], s[28:29], 0, v[130:131]
	s_mov_b32 m0, vcc_lo
	ds_read_b128 v[210:213], v153
	ds_read_b128 v[214:217], v153 offset:1024
	ds_read_b128 v[218:221], v153 offset:2048
	ds_read_b128 v[222:225], v153 offset:3072
	global_load_lds_dwordx4 v[144:145], off
	v_lshl_add_u64 v[194:195], s[28:29], 0, v[134:135]
	s_add_i32 m0, vcc_lo, 0x2000
	s_nop 0
	global_load_lds_dwordx4 v[194:195], off
	s_barrier
	s_waitcnt lgkmcnt(0)
	s_waitcnt lgkmcnt(0)
	v_mfma_f32_16x16x32_bf16 v[124:127], v[210:213], v[174:177], v[124:127]
	v_mfma_f32_16x16x32_bf16 v[112:115], v[218:221], v[174:177], v[112:115]
	v_mfma_f32_16x16x32_bf16 v[96:99], v[218:221], v[182:185], v[96:99]
	v_mfma_f32_16x16x32_bf16 v[104:107], v[210:213], v[182:185], v[104:107]
	v_mfma_f32_16x16x32_bf16 v[88:91], v[210:213], v[190:193], v[88:91]
	v_mfma_f32_16x16x32_bf16 v[80:83], v[218:221], v[190:193], v[80:83]
	v_mfma_f32_16x16x32_bf16 v[64:67], v[218:221], v[202:205], v[64:67]
	v_mfma_f32_16x16x32_bf16 v[72:75], v[210:213], v[202:205], v[72:75]
	v_mfma_f32_16x16x32_bf16 v[124:127], v[214:217], v[178:181], v[124:127]
	v_mfma_f32_16x16x32_bf16 v[112:115], v[222:225], v[178:181], v[112:115]
	v_mfma_f32_16x16x32_bf16 v[96:99], v[222:225], v[186:189], v[96:99]
	v_mfma_f32_16x16x32_bf16 v[104:107], v[214:217], v[186:189], v[104:107]
	v_mfma_f32_16x16x32_bf16 v[88:91], v[214:217], v[198:201], v[88:91]
	v_mfma_f32_16x16x32_bf16 v[80:83], v[222:225], v[198:201], v[80:83]
	v_mfma_f32_16x16x32_bf16 v[64:67], v[222:225], v[206:209], v[64:67]
	v_mfma_f32_16x16x32_bf16 v[72:75], v[214:217], v[206:209], v[72:75]
	s_mov_b32 m0, s37
	v_lshl_add_u64 v[226:227], s[26:27], 0, v[128:129]
	s_barrier
	ds_read_b128 v[174:177], v152 offset:16384
	ds_read_b128 v[178:181], v152 offset:17408
	ds_read_b128 v[182:185], v152 offset:18432
	ds_read_b128 v[186:189], v152 offset:19456
	ds_read_b128 v[190:193], v152 offset:20480
	ds_read_b128 v[198:201], v152 offset:21504
	ds_read_b128 v[202:205], v152 offset:22528
	ds_read_b128 v[206:209], v152 offset:23552
	global_load_lds_dwordx4 v[226:227], off
	v_lshl_add_u64 v[228:229], s[26:27], 0, v[132:133]
	s_mov_b32 m0, s48
	s_nop 0
	global_load_lds_dwordx4 v[228:229], off
	s_barrier
	s_waitcnt lgkmcnt(0)
	s_waitcnt lgkmcnt(0)
	v_mfma_f32_16x16x32_bf16 v[60:63], v[158:161], v[174:177], v[60:63]
	v_mfma_f32_16x16x32_bf16 v[56:59], v[166:169], v[174:177], v[56:59]
	v_mfma_f32_16x16x32_bf16 v[40:43], v[166:169], v[182:185], v[40:43]
	v_mfma_f32_16x16x32_bf16 v[44:47], v[158:161], v[182:185], v[44:47]
	v_mfma_f32_16x16x32_bf16 v[28:31], v[158:161], v[190:193], v[28:31]
	v_mfma_f32_16x16x32_bf16 v[24:27], v[166:169], v[190:193], v[24:27]
	v_mfma_f32_16x16x32_bf16 v[8:11], v[166:169], v[202:205], v[8:11]
	v_mfma_f32_16x16x32_bf16 v[12:15], v[158:161], v[202:205], v[12:15]
	v_mfma_f32_16x16x32_bf16 v[60:63], v[162:165], v[178:181], v[60:63]
	v_mfma_f32_16x16x32_bf16 v[56:59], v[170:173], v[178:181], v[56:59]
	v_mfma_f32_16x16x32_bf16 v[40:43], v[170:173], v[186:189], v[40:43]
	v_mfma_f32_16x16x32_bf16 v[44:47], v[162:165], v[186:189], v[44:47]
	v_mfma_f32_16x16x32_bf16 v[28:31], v[162:165], v[198:201], v[28:31]
	v_mfma_f32_16x16x32_bf16 v[24:27], v[170:173], v[198:201], v[24:27]
	v_mfma_f32_16x16x32_bf16 v[8:11], v[170:173], v[206:209], v[8:11]
	v_mfma_f32_16x16x32_bf16 v[12:15], v[162:165], v[206:209], v[12:15]
	s_barrier
; #define PG8_STAGE(bufoff, gbase, voff) do { _Pragma("unroll") for (int _i = 0; _i < 2; ++_i) \
;         __builtin_amdgcn_global_load_lds((const unsigned*)((const char*)(gbase) + (voff)[_i]), (LAS unsigned*)(lds + (bufoff) + ldsw + _i * 8192), 16, 0, 0); } while (0)
; #define PG8_LDA(dst, b, h) do { _Pragma("unroll") for (int m = 0; m < 4; ++m) _Pragma("unroll") for (int k = 0; k < 2; ++k) dst[m][k] = *(const LAS bf16x8*)(lds + PG8_SA(b, h) + aoff + m * 2048 + k * 1024); } while (0)
; #define PG8_LDB(dst, b, h) do { _Pragma("unroll") for (int n = 0; n < 2; ++n) _Pragma("unroll") for (int k = 0; k < 2; ++k) dst[n][k] = *(const LAS bf16x8*)(lds + PG8_SB(b, h) + boff + n * 2048 + k * 1024); } while (0)
; #define PG8_MMA(ai, bj, At, Bt) do { __builtin_amdgcn_s_setprio(1); _Pragma("unroll") for (int m = 0; m < 4; ++m) _Pragma("unroll") for (int n = 0; n < 2; ++n) _Pragma("unroll") for (int k = 0; k < 2; ++k) \
;         acc[ai][bj][m][n] = __builtin_amdgcn_mfma_f32_16x16x32_bf16(Bt[n][k], At[m][k], acc[ai][bj][m][n], 0, 0, 0); __builtin_amdgcn_s_setprio(0); } while (0)
; #define PG8_WAIT_V(n) asm volatile("s_waitcnt vmcnt(" #n ")" ::: "memory")
; #define PG8_WAIT_L(n) asm volatile("s_waitcnt lgkmcnt(" #n ")" ::: "memory")
; #define PG8_BAR __builtin_amdgcn_s_barrier()
; #define PG8_SCHED __builtin_amdgcn_sched_barrier(0)
; template <class Epi>
; DEVI void gemm_phase(LAS unsigned char* lds, const bf16_t* gA, const bf16_t* gBt, const int lda, const int ldb, const int K, const StaticOrder S_, const Epi E) {
;     ...
;             PG8_STAGE(PG8_SB(0, 1), b2 + hstepB, voffB);
;             PG8_WAIT_V(6); PG8_BAR; PG8_MMA(1, 1, At, B1); PG8_BAR;
;             PG8_LDB(B0, 1, 0); PG8_SCHED; PG8_LDA(At, 1, 0); PG8_STAGE(PG8_SA(0, 1), a2 + hstepA, voffA);
;             PG8_WAIT_L(8); PG8_BAR; PG8_WAIT_L(0); PG8_MMA(0, 0, At, B0); PG8_BAR; PG8_SCHED;
;             PG8_LDB(B1, 1, 1); PG8_STAGE(PG8_SB(1, 0), b3, voffB);
	s_add_u32 s28, s28, s8
	s_addc_u32 s29, s29, s9
	s_add_i32 vcc_lo, s0, s36
	v_lshl_add_u64 v[230:231], s[28:29], 0, v[130:131]
	s_mov_b32 m0, vcc_lo
	v_lshl_add_u64 v[232:233], s[28:29], 0, v[134:135]
	global_load_lds_dwordx4 v[230:231], off
	s_add_i32 m0, vcc_lo, 0x2000
	s_nop 0
	global_load_lds_dwordx4 v[232:233], off
	s_waitcnt vmcnt(6)
	s_barrier
	v_mfma_f32_16x16x32_bf16 v[52:55], v[210:213], v[174:177], v[52:55]
	v_mfma_f32_16x16x32_bf16 v[48:51], v[218:221], v[174:177], v[48:51]
	v_mfma_f32_16x16x32_bf16 v[32:35], v[218:221], v[182:185], v[32:35]
	v_mfma_f32_16x16x32_bf16 v[36:39], v[210:213], v[182:185], v[36:39]
	v_mfma_f32_16x16x32_bf16 v[20:23], v[210:213], v[190:193], v[20:23]
	v_mfma_f32_16x16x32_bf16 v[16:19], v[218:221], v[190:193], v[16:19]
	v_mfma_f32_16x16x32_bf16 v[0:3], v[218:221], v[202:205], v[0:3]
	v_mfma_f32_16x16x32_bf16 v[4:7], v[210:213], v[202:205], v[4:7]
	v_mfma_f32_16x16x32_bf16 v[52:55], v[214:217], v[178:181], v[52:55]
	v_mfma_f32_16x16x32_bf16 v[48:51], v[222:225], v[178:181], v[48:51]
	v_mfma_f32_16x16x32_bf16 v[32:35], v[222:225], v[186:189], v[32:35]
	v_mfma_f32_16x16x32_bf16 v[36:39], v[214:217], v[186:189], v[36:39]
	v_mfma_f32_16x16x32_bf16 v[20:23], v[214:217], v[198:201], v[20:23]
	v_mfma_f32_16x16x32_bf16 v[16:19], v[222:225], v[198:201], v[16:19]
	v_mfma_f32_16x16x32_bf16 v[0:3], v[222:225], v[206:209], v[0:3]
	v_mfma_f32_16x16x32_bf16 v[4:7], v[214:217], v[206:209], v[4:7]
	s_barrier
	ds_read_b128 v[158:161], v154
	ds_read_b128 v[162:165], v154 offset:1024
	ds_read_b128 v[166:169], v154 offset:2048
	ds_read_b128 v[170:173], v154 offset:3072
	s_add_u32 s26, s26, s2
	s_addc_u32 s27, s27, s3
	s_mov_b32 m0, s49
	v_lshl_add_u64 v[210:211], s[26:27], 0, v[128:129]
	ds_read_b128 v[174:177], v152 offset:32768
	ds_read_b128 v[178:181], v152 offset:33792
	ds_read_b128 v[182:185], v152 offset:34816
	ds_read_b128 v[186:189], v152 offset:35840
	ds_read_b128 v[190:193], v152 offset:36864
	ds_read_b128 v[198:201], v152 offset:37888
	ds_read_b128 v[202:205], v152 offset:38912
	ds_read_b128 v[206:209], v152 offset:39936
	global_load_lds_dwordx4 v[210:211], off
	v_lshl_add_u64 v[210:211], s[26:27], 0, v[132:133]
	s_mov_b32 m0, s51
	s_nop 0
	global_load_lds_dwordx4 v[210:211], off
	s_waitcnt lgkmcnt(8)
	s_barrier
	s_waitcnt lgkmcnt(0)
	s_waitcnt lgkmcnt(0)
	v_mfma_f32_16x16x32_bf16 v[120:123], v[158:161], v[174:177], v[120:123]
	v_mfma_f32_16x16x32_bf16 v[116:119], v[166:169], v[174:177], v[116:119]
	v_mfma_f32_16x16x32_bf16 v[100:103], v[166:169], v[182:185], v[100:103]
	v_mfma_f32_16x16x32_bf16 v[108:111], v[158:161], v[182:185], v[108:111]
	v_mfma_f32_16x16x32_bf16 v[92:95], v[158:161], v[190:193], v[92:95]
	v_mfma_f32_16x16x32_bf16 v[84:87], v[166:169], v[190:193], v[84:87]
	v_mfma_f32_16x16x32_bf16 v[68:71], v[166:169], v[202:205], v[68:71]
	v_mfma_f32_16x16x32_bf16 v[76:79], v[158:161], v[202:205], v[76:79]
	v_mfma_f32_16x16x32_bf16 v[120:123], v[162:165], v[178:181], v[120:123]
	v_mfma_f32_16x16x32_bf16 v[116:119], v[170:173], v[178:181], v[116:119]
	v_mfma_f32_16x16x32_bf16 v[100:103], v[170:173], v[186:189], v[100:103]
	v_mfma_f32_16x16x32_bf16 v[108:111], v[162:165], v[186:189], v[108:111]
	v_mfma_f32_16x16x32_bf16 v[92:95], v[162:165], v[198:201], v[92:95]
	v_mfma_f32_16x16x32_bf16 v[84:87], v[170:173], v[198:201], v[84:87]
	v_mfma_f32_16x16x32_bf16 v[68:71], v[170:173], v[206:209], v[68:71]
	v_mfma_f32_16x16x32_bf16 v[76:79], v[162:165], v[206:209], v[76:79]
	s_barrier
	s_add_i32 s26, s1, s36
	v_lshl_add_u64 v[144:145], v[144:145], 0, s[20:21]
	s_mov_b32 m0, s26
	ds_read_b128 v[210:213], v155
	ds_read_b128 v[214:217], v155 offset:1024
	ds_read_b128 v[218:221], v155 offset:2048
	ds_read_b128 v[222:225], v155 offset:3072
	global_load_lds_dwordx4 v[144:145], off
	v_lshl_add_u64 v[144:145], v[194:195], 0, s[20:21]
	s_add_i32 m0, s26, 0x2000
	s_nop 0
	global_load_lds_dwordx4 v[144:145], off
	s_barrier
; #define PG8_STAGE(bufoff, gbase, voff) do { _Pragma("unroll") for (int _i = 0; _i < 2; ++_i) \
;         __builtin_amdgcn_global_load_lds((const unsigned*)((const char*)(gbase) + (voff)[_i]), (LAS unsigned*)(lds + (bufoff) + ldsw + _i * 8192), 16, 0, 0); } while (0)
; #define PG8_LDA(dst, b, h) do { _Pragma("unroll") for (int m = 0; m < 4; ++m) _Pragma("unroll") for (int k = 0; k < 2; ++k) dst[m][k] = *(const LAS bf16x8*)(lds + PG8_SA(b, h) + aoff + m * 2048 + k * 1024); } while (0)
; #define PG8_MMA(ai, bj, At, Bt) do { __builtin_amdgcn_s_setprio(1); _Pragma("unroll") for (int m = 0; m < 4; ++m) _Pragma("unroll") for (int n = 0; n < 2; ++n) _Pragma("unroll") for (int k = 0; k < 2; ++k) \
;         acc[ai][bj][m][n] = __builtin_amdgcn_mfma_f32_16x16x32_bf16(Bt[n][k], At[m][k], acc[ai][bj][m][n], 0, 0, 0); __builtin_amdgcn_s_setprio(0); } while (0)
; #define PG8_WAIT_V(n) asm volatile("s_waitcnt vmcnt(" #n ")" ::: "memory")
; #define PG8_WAIT_L(n) asm volatile("s_waitcnt lgkmcnt(" #n ")" ::: "memory")
; #define PG8_BAR __builtin_amdgcn_s_barrier()
; #define PG8_SCHED __builtin_amdgcn_sched_barrier(0)
; template <class Epi>
; DEVI void gemm_phase(LAS unsigned char* lds, const bf16_t* gA, const bf16_t* gBt, const int lda, const int ldb, const int K, const StaticOrder S_, const Epi E) {
;     ...
;             PG8_BAR; PG8_WAIT_L(0); PG8_MMA(0, 1, At, B1); PG8_BAR;
;             PG8_LDA(At, 1, 1); PG8_STAGE(PG8_SA(1, 0), a3, voffA);
;             PG8_BAR; PG8_WAIT_L(0); PG8_MMA(1, 0, At, B0); PG8_BAR; PG8_SCHED;
;             PG8_STAGE(PG8_SB(1, 1), b3 + hstepB, voffB);
;             PG8_WAIT_V(6); PG8_BAR; PG8_MMA(1, 1, At, B1); PG8_BAR;
;         }
	s_waitcnt lgkmcnt(0)
	s_waitcnt lgkmcnt(0)
	v_mfma_f32_16x16x32_bf16 v[124:127], v[210:213], v[174:177], v[124:127]
	v_mfma_f32_16x16x32_bf16 v[112:115], v[218:221], v[174:177], v[112:115]
	v_mfma_f32_16x16x32_bf16 v[96:99], v[218:221], v[182:185], v[96:99]
	v_mfma_f32_16x16x32_bf16 v[104:107], v[210:213], v[182:185], v[104:107]
	v_mfma_f32_16x16x32_bf16 v[88:91], v[210:213], v[190:193], v[88:91]
	v_mfma_f32_16x16x32_bf16 v[80:83], v[218:221], v[190:193], v[80:83]
	v_mfma_f32_16x16x32_bf16 v[64:67], v[218:221], v[202:205], v[64:67]
	v_mfma_f32_16x16x32_bf16 v[72:75], v[210:213], v[202:205], v[72:75]
	v_mfma_f32_16x16x32_bf16 v[124:127], v[214:217], v[178:181], v[124:127]
	v_mfma_f32_16x16x32_bf16 v[112:115], v[222:225], v[178:181], v[112:115]
	v_mfma_f32_16x16x32_bf16 v[96:99], v[222:225], v[186:189], v[96:99]
	v_mfma_f32_16x16x32_bf16 v[104:107], v[214:217], v[186:189], v[104:107]
	v_mfma_f32_16x16x32_bf16 v[88:91], v[214:217], v[198:201], v[88:91]
	v_mfma_f32_16x16x32_bf16 v[80:83], v[222:225], v[198:201], v[80:83]
	v_mfma_f32_16x16x32_bf16 v[64:67], v[222:225], v[206:209], v[64:67]
	v_mfma_f32_16x16x32_bf16 v[72:75], v[214:217], v[206:209], v[72:75]
	s_mov_b32 m0, s50
	v_lshl_add_u64 v[144:145], v[226:227], 0, s[20:21]
	s_barrier
	ds_read_b128 v[174:177], v152 offset:49152
	ds_read_b128 v[178:181], v152 offset:50176
	ds_read_b128 v[182:185], v152 offset:51200
	ds_read_b128 v[186:189], v152 offset:52224
	ds_read_b128 v[190:193], v152 offset:53248
	ds_read_b128 v[198:201], v152 offset:54272
	ds_read_b128 v[202:205], v152 offset:55296
	ds_read_b128 v[206:209], v152 offset:56320
	global_load_lds_dwordx4 v[144:145], off
	v_lshl_add_u64 v[144:145], v[228:229], 0, s[20:21]
	s_mov_b32 m0, s60
	s_nop 0
	global_load_lds_dwordx4 v[144:145], off
	s_barrier
	s_waitcnt lgkmcnt(0)
	s_waitcnt lgkmcnt(0)
	v_mfma_f32_16x16x32_bf16 v[60:63], v[158:161], v[174:177], v[60:63]
	v_mfma_f32_16x16x32_bf16 v[56:59], v[166:169], v[174:177], v[56:59]
	v_mfma_f32_16x16x32_bf16 v[40:43], v[166:169], v[182:185], v[40:43]
	v_mfma_f32_16x16x32_bf16 v[44:47], v[158:161], v[182:185], v[44:47]
	v_mfma_f32_16x16x32_bf16 v[28:31], v[158:161], v[190:193], v[28:31]
	v_mfma_f32_16x16x32_bf16 v[24:27], v[166:169], v[190:193], v[24:27]
	v_mfma_f32_16x16x32_bf16 v[8:11], v[166:169], v[202:205], v[8:11]
	v_mfma_f32_16x16x32_bf16 v[12:15], v[158:161], v[202:205], v[12:15]
	v_mfma_f32_16x16x32_bf16 v[60:63], v[162:165], v[178:181], v[60:63]
	v_mfma_f32_16x16x32_bf16 v[56:59], v[170:173], v[178:181], v[56:59]
	v_mfma_f32_16x16x32_bf16 v[40:43], v[170:173], v[186:189], v[40:43]
	v_mfma_f32_16x16x32_bf16 v[44:47], v[162:165], v[186:189], v[44:47]
	v_mfma_f32_16x16x32_bf16 v[28:31], v[162:165], v[198:201], v[28:31]
	v_mfma_f32_16x16x32_bf16 v[24:27], v[170:173], v[198:201], v[24:27]
	v_mfma_f32_16x16x32_bf16 v[8:11], v[170:173], v[206:209], v[8:11]
	v_mfma_f32_16x16x32_bf16 v[12:15], v[162:165], v[206:209], v[12:15]
	s_barrier
	s_add_i32 s26, s31, s36
	v_lshl_add_u64 v[144:145], v[230:231], 0, s[20:21]
	s_mov_b32 m0, s26
	s_nop 0
	global_load_lds_dwordx4 v[144:145], off
	v_lshl_add_u64 v[144:145], v[232:233], 0, s[20:21]
	s_add_i32 m0, s26, 0x2000
	s_nop 0
	global_load_lds_dwordx4 v[144:145], off
	s_waitcnt vmcnt(6)
	s_barrier
	v_mfma_f32_16x16x32_bf16 v[52:55], v[210:213], v[174:177], v[52:55]
	v_mfma_f32_16x16x32_bf16 v[48:51], v[218:221], v[174:177], v[48:51]
	v_mfma_f32_16x16x32_bf16 v[32:35], v[218:221], v[182:185], v[32:35]
	v_mfma_f32_16x16x32_bf16 v[36:39], v[210:213], v[182:185], v[36:39]
	v_mfma_f32_16x16x32_bf16 v[20:23], v[210:213], v[190:193], v[20:23]
	v_mfma_f32_16x16x32_bf16 v[16:19], v[218:221], v[190:193], v[16:19]
	v_mfma_f32_16x16x32_bf16 v[0:3], v[218:221], v[202:205], v[0:3]
	v_mfma_f32_16x16x32_bf16 v[4:7], v[210:213], v[202:205], v[4:7]
	v_mfma_f32_16x16x32_bf16 v[52:55], v[214:217], v[178:181], v[52:55]
	v_mfma_f32_16x16x32_bf16 v[48:51], v[222:225], v[178:181], v[48:51]
	v_mfma_f32_16x16x32_bf16 v[32:35], v[222:225], v[186:189], v[32:35]
	v_mfma_f32_16x16x32_bf16 v[36:39], v[214:217], v[186:189], v[36:39]
	v_mfma_f32_16x16x32_bf16 v[20:23], v[214:217], v[198:201], v[20:23]
	v_mfma_f32_16x16x32_bf16 v[16:19], v[222:225], v[198:201], v[16:19]
	v_mfma_f32_16x16x32_bf16 v[0:3], v[222:225], v[206:209], v[0:3]
	v_mfma_f32_16x16x32_bf16 v[4:7], v[214:217], v[206:209], v[4:7]
	s_add_u32 s24, s24, 0x100
	s_addc_u32 s25, s25, 0
	s_add_u32 s77, s77, 0x100
	s_addc_u32 s78, s78, 0
	s_cmp_ge_i32 s79, s61
	s_mov_b32 s26, s79
	s_barrier
	s_cbranch_scc0 .LBB0_259

; #define PG8_STAGE(bufoff, gbase, voff) do { _Pragma("unroll") for (int _i = 0; _i < 2; ++_i) \
;         __builtin_amdgcn_global_load_lds((const unsigned*)((const char*)(gbase) + (voff)[_i]), (LAS unsigned*)(lds + (bufoff) + ldsw + _i * 8192), 16, 0, 0); } while (0)
; #define PG8_LDA(dst, b, h) do { _Pragma("unroll") for (int m = 0; m < 4; ++m) _Pragma("unroll") for (int k = 0; k < 2; ++k) dst[m][k] = *(const LAS bf16x8*)(lds + PG8_SA(b, h) + aoff + m * 2048 + k * 1024); } while (0)
; #define PG8_LDB(dst, b, h) do { _Pragma("unroll") for (int n = 0; n < 2; ++n) _Pragma("unroll") for (int k = 0; k < 2; ++k) dst[n][k] = *(const LAS bf16x8*)(lds + PG8_SB(b, h) + boff + n * 2048 + k * 1024); } while (0)
; #define PG8_MMA(ai, bj, At, Bt) do { __builtin_amdgcn_s_setprio(1); _Pragma("unroll") for (int m = 0; m < 4; ++m) _Pragma("unroll") for (int n = 0; n < 2; ++n) _Pragma("unroll") for (int k = 0; k < 2; ++k) \
;         acc[ai][bj][m][n] = __builtin_amdgcn_mfma_f32_16x16x32_bf16(Bt[n][k], At[m][k], acc[ai][bj][m][n], 0, 0, 0); __builtin_amdgcn_s_setprio(0); } while (0)
; #define PG8_WAIT_L(n) asm volatile("s_waitcnt lgkmcnt(" #n ")" ::: "memory")
; #define PG8_BAR __builtin_amdgcn_s_barrier()
; #define PG8_SCHED __builtin_amdgcn_sched_barrier(0)
; template <class Epi>
; DEVI void gemm_phase(LAS unsigned char* lds, const bf16_t* gA, const bf16_t* gBt, const int lda, const int ldb, const int K, const StaticOrder S_, const Epi E) {
;     ...
;             PG8_LDB(B0, 0, 0); PG8_SCHED; PG8_LDA(At, 0, 0); PG8_STAGE(PG8_SA(1, 1), a1 + hstepA, voffA);
;             PG8_WAIT_L(8); PG8_BAR; PG8_WAIT_L(0); PG8_MMA(0, 0, At, B0); PG8_BAR; PG8_SCHED;
;             PG8_LDB(B1, 0, 1); PG8_STAGE(PG8_SB(0, 0), b2, voffB);
;             PG8_BAR; PG8_WAIT_L(0); PG8_MMA(0, 1, At, B1); PG8_BAR;
;             PG8_LDA(At, 0, 1); PG8_STAGE(PG8_SA(0, 0), a2, voffA);
;             PG8_BAR; PG8_WAIT_L(0); PG8_MMA(1, 0, At, B0); PG8_BAR; PG8_SCHED;
.LBB0_388:
	ds_read_b128 v[128:131], v201
	ds_read_b128 v[132:135], v201 offset:1024
	ds_read_b128 v[136:139], v201 offset:2048
	ds_read_b128 v[140:143], v201 offset:3072
	s_add_i32 s74, s16, 2
	s_add_u32 s40, s14, 0x80
	s_addc_u32 s17, s15, 0
	s_cmp_eq_u32 s29, s16
	s_cselect_b32 s16, s12, s40
	s_cselect_b32 s17, s13, s17
	s_cselect_b32 s41, s43, s73
	s_cselect_b32 s40, s42, s72
	v_lshl_add_u64 v[164:165], s[14:15], 0, v[174:175]
	s_add_i32 m0, s24, 0xc000
	ds_read_b128 v[144:147], v202
	ds_read_b128 v[148:151], v202 offset:1024
	ds_read_b128 v[152:155], v202 offset:2048
	ds_read_b128 v[156:159], v202 offset:3072
	ds_read_b128 v[160:163], v202 offset:4096
	ds_read_b128 v[180:183], v202 offset:5120
	ds_read_b128 v[184:187], v202 offset:6144
	ds_read_b128 v[188:191], v202 offset:7168
	global_load_lds_dwordx4 v[164:165], off
	v_lshl_add_u64 v[164:165], s[14:15], 0, v[176:177]
	s_add_i32 m0, s24, 0xe000
	s_nop 0
	global_load_lds_dwordx4 v[164:165], off
	s_waitcnt lgkmcnt(8)
	s_barrier
	s_waitcnt lgkmcnt(0)
	s_waitcnt lgkmcnt(0)
	v_mfma_f32_16x16x32_bf16 v[124:127], v[128:131], v[144:147], v[124:127]
	v_mfma_f32_16x16x32_bf16 v[120:123], v[136:139], v[144:147], v[120:123]
	v_mfma_f32_16x16x32_bf16 v[104:107], v[136:139], v[152:155], v[104:107]
	v_mfma_f32_16x16x32_bf16 v[108:111], v[128:131], v[152:155], v[108:111]
	v_mfma_f32_16x16x32_bf16 v[92:95], v[128:131], v[160:163], v[92:95]
	v_mfma_f32_16x16x32_bf16 v[88:91], v[136:139], v[160:163], v[88:91]
	v_mfma_f32_16x16x32_bf16 v[72:75], v[136:139], v[184:187], v[72:75]
	v_mfma_f32_16x16x32_bf16 v[76:79], v[128:131], v[184:187], v[76:79]
	v_mfma_f32_16x16x32_bf16 v[124:127], v[132:135], v[148:151], v[124:127]
	v_mfma_f32_16x16x32_bf16 v[120:123], v[140:143], v[148:151], v[120:123]
	v_mfma_f32_16x16x32_bf16 v[104:107], v[140:143], v[156:159], v[104:107]
	v_mfma_f32_16x16x32_bf16 v[108:111], v[132:135], v[156:159], v[108:111]
	v_mfma_f32_16x16x32_bf16 v[92:95], v[132:135], v[180:183], v[92:95]
	v_mfma_f32_16x16x32_bf16 v[88:91], v[140:143], v[180:183], v[88:91]
	v_mfma_f32_16x16x32_bf16 v[72:75], v[140:143], v[188:191], v[72:75]
	v_mfma_f32_16x16x32_bf16 v[76:79], v[132:135], v[188:191], v[76:79]
	s_barrier
	s_add_i32 s75, s97, s22
	v_lshl_add_u64 v[164:165], s[40:41], 0, v[168:169]
	s_mov_b32 m0, s75
	ds_read_b128 v[192:195], v203
	ds_read_b128 v[206:209], v203 offset:1024
	ds_read_b128 v[210:213], v203 offset:2048
	ds_read_b128 v[214:217], v203 offset:3072
	global_load_lds_dwordx4 v[164:165], off
	v_lshl_add_u64 v[218:219], s[40:41], 0, v[172:173]
	s_add_i32 m0, s75, 0x2000
	s_nop 0
	global_load_lds_dwordx4 v[218:219], off
	s_barrier
	s_waitcnt lgkmcnt(0)
	s_waitcnt lgkmcnt(0)
	v_mfma_f32_16x16x32_bf16 v[116:119], v[192:195], v[144:147], v[116:119]
	v_mfma_f32_16x16x32_bf16 v[112:115], v[210:213], v[144:147], v[112:115]
	v_mfma_f32_16x16x32_bf16 v[96:99], v[210:213], v[152:155], v[96:99]
	v_mfma_f32_16x16x32_bf16 v[100:103], v[192:195], v[152:155], v[100:103]
	v_mfma_f32_16x16x32_bf16 v[84:87], v[192:195], v[160:163], v[84:87]
	v_mfma_f32_16x16x32_bf16 v[80:83], v[210:213], v[160:163], v[80:83]
	v_mfma_f32_16x16x32_bf16 v[64:67], v[210:213], v[184:187], v[64:67]
	v_mfma_f32_16x16x32_bf16 v[68:71], v[192:195], v[184:187], v[68:71]
	v_mfma_f32_16x16x32_bf16 v[116:119], v[206:209], v[148:151], v[116:119]
	v_mfma_f32_16x16x32_bf16 v[112:115], v[214:217], v[148:151], v[112:115]
	v_mfma_f32_16x16x32_bf16 v[96:99], v[214:217], v[156:159], v[96:99]
	v_mfma_f32_16x16x32_bf16 v[100:103], v[206:209], v[156:159], v[100:103]
	v_mfma_f32_16x16x32_bf16 v[84:87], v[206:209], v[180:183], v[84:87]
	v_mfma_f32_16x16x32_bf16 v[80:83], v[214:217], v[180:183], v[80:83]
	v_mfma_f32_16x16x32_bf16 v[64:67], v[214:217], v[188:191], v[64:67]
	v_mfma_f32_16x16x32_bf16 v[68:71], v[206:209], v[188:191], v[68:71]
	s_mov_b32 m0, s24
	v_lshl_add_u64 v[220:221], s[16:17], 0, v[166:167]
	s_barrier
	ds_read_b128 v[144:147], v202 offset:16384
	ds_read_b128 v[148:151], v202 offset:17408
	ds_read_b128 v[152:155], v202 offset:18432
	ds_read_b128 v[156:159], v202 offset:19456
	ds_read_b128 v[160:163], v202 offset:20480
	ds_read_b128 v[180:183], v202 offset:21504
	ds_read_b128 v[184:187], v202 offset:22528
	ds_read_b128 v[188:191], v202 offset:23552
	global_load_lds_dwordx4 v[220:221], off
	v_lshl_add_u64 v[222:223], s[16:17], 0, v[170:171]
	s_mov_b32 m0, s25
	s_nop 0
	global_load_lds_dwordx4 v[222:223], off
	s_barrier
	s_waitcnt lgkmcnt(0)
	s_waitcnt lgkmcnt(0)
	v_mfma_f32_16x16x32_bf16 v[60:63], v[128:131], v[144:147], v[60:63]
	v_mfma_f32_16x16x32_bf16 v[56:59], v[136:139], v[144:147], v[56:59]
	v_mfma_f32_16x16x32_bf16 v[40:43], v[136:139], v[152:155], v[40:43]
	v_mfma_f32_16x16x32_bf16 v[44:47], v[128:131], v[152:155], v[44:47]
	v_mfma_f32_16x16x32_bf16 v[28:31], v[128:131], v[160:163], v[28:31]
	v_mfma_f32_16x16x32_bf16 v[24:27], v[136:139], v[160:163], v[24:27]
	v_mfma_f32_16x16x32_bf16 v[8:11], v[136:139], v[184:187], v[8:11]
	v_mfma_f32_16x16x32_bf16 v[12:15], v[128:131], v[184:187], v[12:15]
	v_mfma_f32_16x16x32_bf16 v[60:63], v[132:135], v[148:151], v[60:63]
	v_mfma_f32_16x16x32_bf16 v[56:59], v[140:143], v[148:151], v[56:59]
	v_mfma_f32_16x16x32_bf16 v[40:43], v[140:143], v[156:159], v[40:43]
	v_mfma_f32_16x16x32_bf16 v[44:47], v[132:135], v[156:159], v[44:47]
	v_mfma_f32_16x16x32_bf16 v[28:31], v[132:135], v[180:183], v[28:31]
	v_mfma_f32_16x16x32_bf16 v[24:27], v[140:143], v[180:183], v[24:27]
	v_mfma_f32_16x16x32_bf16 v[8:11], v[140:143], v[188:191], v[8:11]
	v_mfma_f32_16x16x32_bf16 v[12:15], v[132:135], v[188:191], v[12:15]
	s_barrier
; #define PG8_STAGE(bufoff, gbase, voff) do { _Pragma("unroll") for (int _i = 0; _i < 2; ++_i) \
;         __builtin_amdgcn_global_load_lds((const unsigned*)((const char*)(gbase) + (voff)[_i]), (LAS unsigned*)(lds + (bufoff) + ldsw + _i * 8192), 16, 0, 0); } while (0)
; #define PG8_LDA(dst, b, h) do { _Pragma("unroll") for (int m = 0; m < 4; ++m) _Pragma("unroll") for (int k = 0; k < 2; ++k) dst[m][k] = *(const LAS bf16x8*)(lds + PG8_SA(b, h) + aoff + m * 2048 + k * 1024); } while (0)
; #define PG8_LDB(dst, b, h) do { _Pragma("unroll") for (int n = 0; n < 2; ++n) _Pragma("unroll") for (int k = 0; k < 2; ++k) dst[n][k] = *(const LAS bf16x8*)(lds + PG8_SB(b, h) + boff + n * 2048 + k * 1024); } while (0)
; #define PG8_MMA(ai, bj, At, Bt) do { __builtin_amdgcn_s_setprio(1); _Pragma("unroll") for (int m = 0; m < 4; ++m) _Pragma("unroll") for (int n = 0; n < 2; ++n) _Pragma("unroll") for (int k = 0; k < 2; ++k) \
;         acc[ai][bj][m][n] = __builtin_amdgcn_mfma_f32_16x16x32_bf16(Bt[n][k], At[m][k], acc[ai][bj][m][n], 0, 0, 0); __builtin_amdgcn_s_setprio(0); } while (0)
; #define PG8_WAIT_V(n) asm volatile("s_waitcnt vmcnt(" #n ")" ::: "memory")
; #define PG8_WAIT_L(n) asm volatile("s_waitcnt lgkmcnt(" #n ")" ::: "memory")
; #define PG8_BAR __builtin_amdgcn_s_barrier()
; #define PG8_SCHED __builtin_amdgcn_sched_barrier(0)
; template <class Epi>
; DEVI void gemm_phase(LAS unsigned char* lds, const bf16_t* gA, const bf16_t* gBt, const int lda, const int ldb, const int K, const StaticOrder S_, const Epi E) {
;     ...
;             PG8_STAGE(PG8_SB(0, 1), b2 + hstepB, voffB);
;             PG8_WAIT_V(6); PG8_BAR; PG8_MMA(1, 1, At, B1); PG8_BAR;
;             PG8_LDB(B0, 1, 0); PG8_SCHED; PG8_LDA(At, 1, 0); PG8_STAGE(PG8_SA(0, 1), a2 + hstepA, voffA);
;             PG8_WAIT_L(8); PG8_BAR; PG8_WAIT_L(0); PG8_MMA(0, 0, At, B0); PG8_BAR; PG8_SCHED;
;             PG8_LDB(B1, 1, 1); PG8_STAGE(PG8_SB(1, 0), b3, voffB);
	s_add_u32 s40, s40, s0
	s_addc_u32 s41, s41, s1
	s_add_i32 s75, s50, s22
	v_lshl_add_u64 v[224:225], s[40:41], 0, v[168:169]
	s_mov_b32 m0, s75
	v_lshl_add_u64 v[226:227], s[40:41], 0, v[172:173]
	global_load_lds_dwordx4 v[224:225], off
	s_add_i32 m0, s75, 0x2000
	s_nop 0
	global_load_lds_dwordx4 v[226:227], off
	s_waitcnt vmcnt(6)
	s_barrier
	v_mfma_f32_16x16x32_bf16 v[52:55], v[192:195], v[144:147], v[52:55]
	v_mfma_f32_16x16x32_bf16 v[48:51], v[210:213], v[144:147], v[48:51]
	v_mfma_f32_16x16x32_bf16 v[32:35], v[210:213], v[152:155], v[32:35]
	v_mfma_f32_16x16x32_bf16 v[36:39], v[192:195], v[152:155], v[36:39]
	v_mfma_f32_16x16x32_bf16 v[20:23], v[192:195], v[160:163], v[20:23]
	v_mfma_f32_16x16x32_bf16 v[16:19], v[210:213], v[160:163], v[16:19]
	v_mfma_f32_16x16x32_bf16 v[0:3], v[210:213], v[184:187], v[0:3]
	v_mfma_f32_16x16x32_bf16 v[4:7], v[192:195], v[184:187], v[4:7]
	v_mfma_f32_16x16x32_bf16 v[52:55], v[206:209], v[148:151], v[52:55]
	v_mfma_f32_16x16x32_bf16 v[48:51], v[214:217], v[148:151], v[48:51]
	v_mfma_f32_16x16x32_bf16 v[32:35], v[214:217], v[156:159], v[32:35]
	v_mfma_f32_16x16x32_bf16 v[36:39], v[206:209], v[156:159], v[36:39]
	v_mfma_f32_16x16x32_bf16 v[20:23], v[206:209], v[180:183], v[20:23]
	v_mfma_f32_16x16x32_bf16 v[16:19], v[214:217], v[180:183], v[16:19]
	v_mfma_f32_16x16x32_bf16 v[0:3], v[214:217], v[188:191], v[0:3]
	v_mfma_f32_16x16x32_bf16 v[4:7], v[206:209], v[188:191], v[4:7]
	s_add_i32 s40, 0, 0x18000
	v_add_u32_e32 v140, s40, v199
	s_barrier
	ds_read_b128 v[128:131], v140
	ds_read_b128 v[132:135], v140 offset:1024
	ds_read_b128 v[136:139], v140 offset:2048
	ds_read_b128 v[140:143], v140 offset:3072
	s_add_u32 s16, s16, s48
	s_addc_u32 s17, s17, s49
	s_mov_b32 m0, s26
	v_lshl_add_u64 v[192:193], s[16:17], 0, v[166:167]
	ds_read_b128 v[144:147], v202 offset:32768
	ds_read_b128 v[148:151], v202 offset:33792
	ds_read_b128 v[152:155], v202 offset:34816
	ds_read_b128 v[156:159], v202 offset:35840
	ds_read_b128 v[160:163], v202 offset:36864
	ds_read_b128 v[180:183], v202 offset:37888
	ds_read_b128 v[184:187], v202 offset:38912
	ds_read_b128 v[188:191], v202 offset:39936
	global_load_lds_dwordx4 v[192:193], off
	v_lshl_add_u64 v[192:193], s[16:17], 0, v[170:171]
	s_mov_b32 m0, s27
	s_nop 0
	global_load_lds_dwordx4 v[192:193], off
	s_waitcnt lgkmcnt(8)
	s_barrier
	s_waitcnt lgkmcnt(0)
	s_waitcnt lgkmcnt(0)
	v_mfma_f32_16x16x32_bf16 v[124:127], v[128:131], v[144:147], v[124:127]
	v_mfma_f32_16x16x32_bf16 v[120:123], v[136:139], v[144:147], v[120:123]
	v_mfma_f32_16x16x32_bf16 v[104:107], v[136:139], v[152:155], v[104:107]
	v_mfma_f32_16x16x32_bf16 v[108:111], v[128:131], v[152:155], v[108:111]
	v_mfma_f32_16x16x32_bf16 v[92:95], v[128:131], v[160:163], v[92:95]
	v_mfma_f32_16x16x32_bf16 v[88:91], v[136:139], v[160:163], v[88:91]
	v_mfma_f32_16x16x32_bf16 v[72:75], v[136:139], v[184:187], v[72:75]
	v_mfma_f32_16x16x32_bf16 v[76:79], v[128:131], v[184:187], v[76:79]
	v_mfma_f32_16x16x32_bf16 v[124:127], v[132:135], v[148:151], v[124:127]
	v_mfma_f32_16x16x32_bf16 v[120:123], v[140:143], v[148:151], v[120:123]
	v_mfma_f32_16x16x32_bf16 v[104:107], v[140:143], v[156:159], v[104:107]
	v_mfma_f32_16x16x32_bf16 v[108:111], v[132:135], v[156:159], v[108:111]
	v_mfma_f32_16x16x32_bf16 v[92:95], v[132:135], v[180:183], v[92:95]
	v_mfma_f32_16x16x32_bf16 v[88:91], v[140:143], v[180:183], v[88:91]
	v_mfma_f32_16x16x32_bf16 v[72:75], v[140:143], v[188:191], v[72:75]
	v_mfma_f32_16x16x32_bf16 v[76:79], v[132:135], v[188:191], v[76:79]
	s_barrier
	s_add_i32 s16, 0, 0x1c000
	s_add_i32 s17, s40, s22
	v_add_u32_e32 v214, s16, v199
	v_lshl_add_u64 v[164:165], v[164:165], 0, s[10:11]
	s_mov_b32 m0, s17
	ds_read_b128 v[192:195], v214
	ds_read_b128 v[206:209], v214 offset:1024
	ds_read_b128 v[210:213], v214 offset:2048
	ds_read_b128 v[214:217], v214 offset:3072
	global_load_lds_dwordx4 v[164:165], off
	v_lshl_add_u64 v[164:165], v[218:219], 0, s[10:11]
	s_add_i32 m0, s17, 0x2000
	s_nop 0
	global_load_lds_dwordx4 v[164:165], off
	s_barrier
; #define PG8_STAGE(bufoff, gbase, voff) do { _Pragma("unroll") for (int _i = 0; _i < 2; ++_i) \
;         __builtin_amdgcn_global_load_lds((const unsigned*)((const char*)(gbase) + (voff)[_i]), (LAS unsigned*)(lds + (bufoff) + ldsw + _i * 8192), 16, 0, 0); } while (0)
; #define PG8_LDA(dst, b, h) do { _Pragma("unroll") for (int m = 0; m < 4; ++m) _Pragma("unroll") for (int k = 0; k < 2; ++k) dst[m][k] = *(const LAS bf16x8*)(lds + PG8_SA(b, h) + aoff + m * 2048 + k * 1024); } while (0)
; #define PG8_MMA(ai, bj, At, Bt) do { __builtin_amdgcn_s_setprio(1); _Pragma("unroll") for (int m = 0; m < 4; ++m) _Pragma("unroll") for (int n = 0; n < 2; ++n) _Pragma("unroll") for (int k = 0; k < 2; ++k) \
;         acc[ai][bj][m][n] = __builtin_amdgcn_mfma_f32_16x16x32_bf16(Bt[n][k], At[m][k], acc[ai][bj][m][n], 0, 0, 0); __builtin_amdgcn_s_setprio(0); } while (0)
; #define PG8_WAIT_V(n) asm volatile("s_waitcnt vmcnt(" #n ")" ::: "memory")
; #define PG8_WAIT_L(n) asm volatile("s_waitcnt lgkmcnt(" #n ")" ::: "memory")
; #define PG8_BAR __builtin_amdgcn_s_barrier()
; #define PG8_SCHED __builtin_amdgcn_sched_barrier(0)
; template <class Epi>
; DEVI void gemm_phase(LAS unsigned char* lds, const bf16_t* gA, const bf16_t* gBt, const int lda, const int ldb, const int K, const StaticOrder S_, const Epi E) {
;     ...
;             PG8_BAR; PG8_WAIT_L(0); PG8_MMA(0, 1, At, B1); PG8_BAR;
;             PG8_LDA(At, 1, 1); PG8_STAGE(PG8_SA(1, 0), a3, voffA);
;             PG8_BAR; PG8_WAIT_L(0); PG8_MMA(1, 0, At, B0); PG8_BAR; PG8_SCHED;
;             PG8_STAGE(PG8_SB(1, 1), b3 + hstepB, voffB);
;             PG8_WAIT_V(6); PG8_BAR; PG8_MMA(1, 1, At, B1); PG8_BAR;
;         }
	s_waitcnt lgkmcnt(0)
	s_waitcnt lgkmcnt(0)
	v_mfma_f32_16x16x32_bf16 v[116:119], v[192:195], v[144:147], v[116:119]
	v_mfma_f32_16x16x32_bf16 v[112:115], v[210:213], v[144:147], v[112:115]
	v_mfma_f32_16x16x32_bf16 v[96:99], v[210:213], v[152:155], v[96:99]
	v_mfma_f32_16x16x32_bf16 v[100:103], v[192:195], v[152:155], v[100:103]
	v_mfma_f32_16x16x32_bf16 v[84:87], v[192:195], v[160:163], v[84:87]
	v_mfma_f32_16x16x32_bf16 v[80:83], v[210:213], v[160:163], v[80:83]
	v_mfma_f32_16x16x32_bf16 v[64:67], v[210:213], v[184:187], v[64:67]
	v_mfma_f32_16x16x32_bf16 v[68:71], v[192:195], v[184:187], v[68:71]
	v_mfma_f32_16x16x32_bf16 v[116:119], v[206:209], v[148:151], v[116:119]
	v_mfma_f32_16x16x32_bf16 v[112:115], v[214:217], v[148:151], v[112:115]
	v_mfma_f32_16x16x32_bf16 v[96:99], v[214:217], v[156:159], v[96:99]
	v_mfma_f32_16x16x32_bf16 v[100:103], v[206:209], v[156:159], v[100:103]
	v_mfma_f32_16x16x32_bf16 v[84:87], v[206:209], v[180:183], v[84:87]
	v_mfma_f32_16x16x32_bf16 v[80:83], v[214:217], v[180:183], v[80:83]
	v_mfma_f32_16x16x32_bf16 v[64:67], v[214:217], v[188:191], v[64:67]
	v_mfma_f32_16x16x32_bf16 v[68:71], v[206:209], v[188:191], v[68:71]
	s_mov_b32 m0, s18
	v_lshl_add_u64 v[164:165], v[220:221], 0, s[10:11]
	s_barrier
	ds_read_b128 v[144:147], v202 offset:49152
	ds_read_b128 v[148:151], v202 offset:50176
	ds_read_b128 v[152:155], v202 offset:51200
	ds_read_b128 v[156:159], v202 offset:52224
	ds_read_b128 v[160:163], v202 offset:53248
	ds_read_b128 v[180:183], v202 offset:54272
	ds_read_b128 v[184:187], v202 offset:55296
	ds_read_b128 v[188:191], v202 offset:56320
	global_load_lds_dwordx4 v[164:165], off
	v_lshl_add_u64 v[164:165], v[222:223], 0, s[10:11]
	s_mov_b32 m0, s19
	s_nop 0
	global_load_lds_dwordx4 v[164:165], off
	s_barrier
	s_waitcnt lgkmcnt(0)
	s_waitcnt lgkmcnt(0)
	v_mfma_f32_16x16x32_bf16 v[60:63], v[128:131], v[144:147], v[60:63]
	v_mfma_f32_16x16x32_bf16 v[56:59], v[136:139], v[144:147], v[56:59]
	v_mfma_f32_16x16x32_bf16 v[40:43], v[136:139], v[152:155], v[40:43]
	v_mfma_f32_16x16x32_bf16 v[44:47], v[128:131], v[152:155], v[44:47]
	v_mfma_f32_16x16x32_bf16 v[28:31], v[128:131], v[160:163], v[28:31]
	v_mfma_f32_16x16x32_bf16 v[24:27], v[136:139], v[160:163], v[24:27]
	v_mfma_f32_16x16x32_bf16 v[8:11], v[136:139], v[184:187], v[8:11]
	v_mfma_f32_16x16x32_bf16 v[12:15], v[128:131], v[184:187], v[12:15]
	v_mfma_f32_16x16x32_bf16 v[60:63], v[132:135], v[148:151], v[60:63]
	v_mfma_f32_16x16x32_bf16 v[56:59], v[140:143], v[148:151], v[56:59]
	v_mfma_f32_16x16x32_bf16 v[40:43], v[140:143], v[156:159], v[40:43]
	v_mfma_f32_16x16x32_bf16 v[44:47], v[132:135], v[156:159], v[44:47]
	v_mfma_f32_16x16x32_bf16 v[28:31], v[132:135], v[180:183], v[28:31]
	v_mfma_f32_16x16x32_bf16 v[24:27], v[140:143], v[180:183], v[24:27]
	v_mfma_f32_16x16x32_bf16 v[8:11], v[140:143], v[188:191], v[8:11]
	v_mfma_f32_16x16x32_bf16 v[12:15], v[132:135], v[188:191], v[12:15]
	s_barrier
	s_add_i32 s16, s16, s22
	v_lshl_add_u64 v[128:129], v[224:225], 0, s[10:11]
	s_mov_b32 m0, s16
	s_nop 0
	global_load_lds_dwordx4 v[128:129], off
	v_lshl_add_u64 v[128:129], v[226:227], 0, s[10:11]
	s_add_i32 m0, s16, 0x2000
	s_nop 0
	global_load_lds_dwordx4 v[128:129], off
	s_waitcnt vmcnt(6)
	s_barrier
	v_mfma_f32_16x16x32_bf16 v[52:55], v[192:195], v[144:147], v[52:55]
	v_mfma_f32_16x16x32_bf16 v[48:51], v[210:213], v[144:147], v[48:51]
	v_mfma_f32_16x16x32_bf16 v[32:35], v[210:213], v[152:155], v[32:35]
	v_mfma_f32_16x16x32_bf16 v[36:39], v[192:195], v[152:155], v[36:39]
	v_mfma_f32_16x16x32_bf16 v[20:23], v[192:195], v[160:163], v[20:23]
	v_mfma_f32_16x16x32_bf16 v[16:19], v[210:213], v[160:163], v[16:19]
	v_mfma_f32_16x16x32_bf16 v[0:3], v[210:213], v[184:187], v[0:3]
	v_mfma_f32_16x16x32_bf16 v[4:7], v[192:195], v[184:187], v[4:7]
	v_mfma_f32_16x16x32_bf16 v[52:55], v[206:209], v[148:151], v[52:55]
	v_mfma_f32_16x16x32_bf16 v[48:51], v[214:217], v[148:151], v[48:51]
	v_mfma_f32_16x16x32_bf16 v[32:35], v[214:217], v[156:159], v[32:35]
	v_mfma_f32_16x16x32_bf16 v[36:39], v[206:209], v[156:159], v[36:39]
	v_mfma_f32_16x16x32_bf16 v[20:23], v[206:209], v[180:183], v[20:23]
	v_mfma_f32_16x16x32_bf16 v[16:19], v[214:217], v[180:183], v[16:19]
	v_mfma_f32_16x16x32_bf16 v[0:3], v[214:217], v[188:191], v[0:3]
	v_mfma_f32_16x16x32_bf16 v[4:7], v[206:209], v[188:191], v[4:7]
	s_add_u32 s14, s14, 0x100
	s_addc_u32 s15, s15, 0
	s_add_u32 s72, s72, 0x100
	s_addc_u32 s73, s73, 0
	s_cmp_ge_i32 s74, s28
	s_mov_b32 s16, s74
	s_barrier
	s_cbranch_scc0 .LBB0_388

; #define PG8_STAGE(bufoff, gbase, voff) do { _Pragma("unroll") for (int _i = 0; _i < 2; ++_i) \
;         __builtin_amdgcn_global_load_lds((const unsigned*)((const char*)(gbase) + (voff)[_i]), (LAS unsigned*)(lds + (bufoff) + ldsw + _i * 8192), 16, 0, 0); } while (0)
; #define PG8_LDA(dst, b, h) do { _Pragma("unroll") for (int m = 0; m < 4; ++m) _Pragma("unroll") for (int k = 0; k < 2; ++k) dst[m][k] = *(const LAS bf16x8*)(lds + PG8_SA(b, h) + aoff + m * 2048 + k * 1024); } while (0)
; #define PG8_LDB(dst, b, h) do { _Pragma("unroll") for (int n = 0; n < 2; ++n) _Pragma("unroll") for (int k = 0; k < 2; ++k) dst[n][k] = *(const LAS bf16x8*)(lds + PG8_SB(b, h) + boff + n * 2048 + k * 1024); } while (0)
; #define PG8_MMA(ai, bj, At, Bt) do { __builtin_amdgcn_s_setprio(1); _Pragma("unroll") for (int m = 0; m < 4; ++m) _Pragma("unroll") for (int n = 0; n < 2; ++n) _Pragma("unroll") for (int k = 0; k < 2; ++k) \
;         acc[ai][bj][m][n] = __builtin_amdgcn_mfma_f32_16x16x32_bf16(Bt[n][k], At[m][k], acc[ai][bj][m][n], 0, 0, 0); __builtin_amdgcn_s_setprio(0); } while (0)
; #define PG8_WAIT_L(n) asm volatile("s_waitcnt lgkmcnt(" #n ")" ::: "memory")
; #define PG8_BAR __builtin_amdgcn_s_barrier()
; #define PG8_SCHED __builtin_amdgcn_sched_barrier(0)
; template <class Epi>
; DEVI void gemm_phase(LAS unsigned char* lds, const bf16_t* gA, const bf16_t* gBt, const int lda, const int ldb, const int K, const StaticOrder S_, const Epi E) {
;     ...
;             PG8_LDB(B0, 0, 0); PG8_SCHED; PG8_LDA(At, 0, 0); PG8_STAGE(PG8_SA(1, 1), a1 + hstepA, voffA);
;             PG8_WAIT_L(8); PG8_BAR; PG8_WAIT_L(0); PG8_MMA(0, 0, At, B0); PG8_BAR; PG8_SCHED;
;             PG8_LDB(B1, 0, 1); PG8_STAGE(PG8_SB(0, 0), b2, voffB);
;             PG8_BAR; PG8_WAIT_L(0); PG8_MMA(0, 1, At, B1); PG8_BAR;
;             PG8_LDA(At, 0, 1); PG8_STAGE(PG8_SA(0, 0), a2, voffA);
;             PG8_BAR; PG8_WAIT_L(0); PG8_MMA(1, 0, At, B0); PG8_BAR; PG8_SCHED;
.LBB0_519:
	ds_read_b128 v[160:163], v153
	ds_read_b128 v[164:167], v153 offset:1024
	ds_read_b128 v[168:171], v153 offset:2048
	ds_read_b128 v[172:175], v153 offset:3072
	s_add_i32 s77, s16, 2
	s_add_u32 s40, s14, 0x80
	s_addc_u32 s17, s15, 0
	s_cmp_eq_u32 s26, s16
	s_cselect_b32 s16, s48, s40
	s_cselect_b32 s17, s49, s17
	s_cselect_b32 s41, s61, s69
	s_cselect_b32 s40, s60, s68
	v_lshl_add_u64 v[144:145], s[14:15], 0, v[138:139]
	s_add_i32 m0, s19, 0xc000
	ds_read_b128 v[176:179], v154
	ds_read_b128 v[180:183], v154 offset:1024
	ds_read_b128 v[184:187], v154 offset:2048
	ds_read_b128 v[188:191], v154 offset:3072
	ds_read_b128 v[192:195], v154 offset:4096
	ds_read_b128 v[198:201], v154 offset:5120
	ds_read_b128 v[202:205], v154 offset:6144
	ds_read_b128 v[206:209], v154 offset:7168
	global_load_lds_dwordx4 v[144:145], off
	v_lshl_add_u64 v[144:145], s[14:15], 0, v[140:141]
	s_add_i32 m0, s19, 0xe000
	s_nop 0
	global_load_lds_dwordx4 v[144:145], off
	s_waitcnt lgkmcnt(8)
	s_barrier
	s_waitcnt lgkmcnt(0)
	s_waitcnt lgkmcnt(0)
	v_mfma_f32_16x16x32_bf16 v[124:127], v[160:163], v[176:179], v[124:127]
	v_mfma_f32_16x16x32_bf16 v[120:123], v[168:171], v[176:179], v[120:123]
	v_mfma_f32_16x16x32_bf16 v[104:107], v[168:171], v[184:187], v[104:107]
	v_mfma_f32_16x16x32_bf16 v[108:111], v[160:163], v[184:187], v[108:111]
	v_mfma_f32_16x16x32_bf16 v[92:95], v[160:163], v[192:195], v[92:95]
	v_mfma_f32_16x16x32_bf16 v[88:91], v[168:171], v[192:195], v[88:91]
	v_mfma_f32_16x16x32_bf16 v[72:75], v[168:171], v[202:205], v[72:75]
	v_mfma_f32_16x16x32_bf16 v[76:79], v[160:163], v[202:205], v[76:79]
	v_mfma_f32_16x16x32_bf16 v[124:127], v[164:167], v[180:183], v[124:127]
	v_mfma_f32_16x16x32_bf16 v[120:123], v[172:175], v[180:183], v[120:123]
	v_mfma_f32_16x16x32_bf16 v[104:107], v[172:175], v[188:191], v[104:107]
	v_mfma_f32_16x16x32_bf16 v[108:111], v[164:167], v[188:191], v[108:111]
	v_mfma_f32_16x16x32_bf16 v[92:95], v[164:167], v[198:201], v[92:95]
	v_mfma_f32_16x16x32_bf16 v[88:91], v[172:175], v[198:201], v[88:91]
	v_mfma_f32_16x16x32_bf16 v[72:75], v[172:175], v[206:209], v[72:75]
	v_mfma_f32_16x16x32_bf16 v[76:79], v[164:167], v[206:209], v[76:79]
	s_barrier
	s_add_i32 s78, s31, s18
	v_lshl_add_u64 v[144:145], s[40:41], 0, v[130:131]
	s_mov_b32 m0, s78
	ds_read_b128 v[210:213], v155
	ds_read_b128 v[214:217], v155 offset:1024
	ds_read_b128 v[218:221], v155 offset:2048
	ds_read_b128 v[222:225], v155 offset:3072
	global_load_lds_dwordx4 v[144:145], off
	v_lshl_add_u64 v[226:227], s[40:41], 0, v[134:135]
	s_add_i32 m0, s78, 0x2000
	s_nop 0
	global_load_lds_dwordx4 v[226:227], off
	s_barrier
	s_waitcnt lgkmcnt(0)
	s_waitcnt lgkmcnt(0)
	v_mfma_f32_16x16x32_bf16 v[116:119], v[210:213], v[176:179], v[116:119]
	v_mfma_f32_16x16x32_bf16 v[112:115], v[218:221], v[176:179], v[112:115]
	v_mfma_f32_16x16x32_bf16 v[96:99], v[218:221], v[184:187], v[96:99]
	v_mfma_f32_16x16x32_bf16 v[100:103], v[210:213], v[184:187], v[100:103]
	v_mfma_f32_16x16x32_bf16 v[84:87], v[210:213], v[192:195], v[84:87]
	v_mfma_f32_16x16x32_bf16 v[80:83], v[218:221], v[192:195], v[80:83]
	v_mfma_f32_16x16x32_bf16 v[64:67], v[218:221], v[202:205], v[64:67]
	v_mfma_f32_16x16x32_bf16 v[68:71], v[210:213], v[202:205], v[68:71]
	v_mfma_f32_16x16x32_bf16 v[116:119], v[214:217], v[180:183], v[116:119]
	v_mfma_f32_16x16x32_bf16 v[112:115], v[222:225], v[180:183], v[112:115]
	v_mfma_f32_16x16x32_bf16 v[96:99], v[222:225], v[188:191], v[96:99]
	v_mfma_f32_16x16x32_bf16 v[100:103], v[214:217], v[188:191], v[100:103]
	v_mfma_f32_16x16x32_bf16 v[84:87], v[214:217], v[198:201], v[84:87]
	v_mfma_f32_16x16x32_bf16 v[80:83], v[222:225], v[198:201], v[80:83]
	v_mfma_f32_16x16x32_bf16 v[64:67], v[222:225], v[206:209], v[64:67]
	v_mfma_f32_16x16x32_bf16 v[68:71], v[214:217], v[206:209], v[68:71]
	s_mov_b32 m0, s19
	v_lshl_add_u64 v[228:229], s[16:17], 0, v[128:129]
	s_barrier
	ds_read_b128 v[176:179], v154 offset:16384
	ds_read_b128 v[180:183], v154 offset:17408
	ds_read_b128 v[184:187], v154 offset:18432
	ds_read_b128 v[188:191], v154 offset:19456
	ds_read_b128 v[192:195], v154 offset:20480
	ds_read_b128 v[198:201], v154 offset:21504
	ds_read_b128 v[202:205], v154 offset:22528
	ds_read_b128 v[206:209], v154 offset:23552
	global_load_lds_dwordx4 v[228:229], off
	v_lshl_add_u64 v[230:231], s[16:17], 0, v[132:133]
	s_mov_b32 m0, s20
	s_nop 0
	global_load_lds_dwordx4 v[230:231], off
	s_barrier
	s_waitcnt lgkmcnt(0)
	s_waitcnt lgkmcnt(0)
	v_mfma_f32_16x16x32_bf16 v[60:63], v[160:163], v[176:179], v[60:63]
	v_mfma_f32_16x16x32_bf16 v[56:59], v[168:171], v[176:179], v[56:59]
	v_mfma_f32_16x16x32_bf16 v[40:43], v[168:171], v[184:187], v[40:43]
	v_mfma_f32_16x16x32_bf16 v[44:47], v[160:163], v[184:187], v[44:47]
	v_mfma_f32_16x16x32_bf16 v[28:31], v[160:163], v[192:195], v[28:31]
	v_mfma_f32_16x16x32_bf16 v[24:27], v[168:171], v[192:195], v[24:27]
	v_mfma_f32_16x16x32_bf16 v[8:11], v[168:171], v[202:205], v[8:11]
	v_mfma_f32_16x16x32_bf16 v[12:15], v[160:163], v[202:205], v[12:15]
	v_mfma_f32_16x16x32_bf16 v[60:63], v[164:167], v[180:183], v[60:63]
	v_mfma_f32_16x16x32_bf16 v[56:59], v[172:175], v[180:183], v[56:59]
	v_mfma_f32_16x16x32_bf16 v[40:43], v[172:175], v[188:191], v[40:43]
	v_mfma_f32_16x16x32_bf16 v[44:47], v[164:167], v[188:191], v[44:47]
	v_mfma_f32_16x16x32_bf16 v[28:31], v[164:167], v[198:201], v[28:31]
	v_mfma_f32_16x16x32_bf16 v[24:27], v[172:175], v[198:201], v[24:27]
	v_mfma_f32_16x16x32_bf16 v[8:11], v[172:175], v[206:209], v[8:11]
	v_mfma_f32_16x16x32_bf16 v[12:15], v[164:167], v[206:209], v[12:15]
	s_barrier
; #define PG8_STAGE(bufoff, gbase, voff) do { _Pragma("unroll") for (int _i = 0; _i < 2; ++_i) \
;         __builtin_amdgcn_global_load_lds((const unsigned*)((const char*)(gbase) + (voff)[_i]), (LAS unsigned*)(lds + (bufoff) + ldsw + _i * 8192), 16, 0, 0); } while (0)
; #define PG8_LDA(dst, b, h) do { _Pragma("unroll") for (int m = 0; m < 4; ++m) _Pragma("unroll") for (int k = 0; k < 2; ++k) dst[m][k] = *(const LAS bf16x8*)(lds + PG8_SA(b, h) + aoff + m * 2048 + k * 1024); } while (0)
; #define PG8_LDB(dst, b, h) do { _Pragma("unroll") for (int n = 0; n < 2; ++n) _Pragma("unroll") for (int k = 0; k < 2; ++k) dst[n][k] = *(const LAS bf16x8*)(lds + PG8_SB(b, h) + boff + n * 2048 + k * 1024); } while (0)
; #define PG8_MMA(ai, bj, At, Bt) do { __builtin_amdgcn_s_setprio(1); _Pragma("unroll") for (int m = 0; m < 4; ++m) _Pragma("unroll") for (int n = 0; n < 2; ++n) _Pragma("unroll") for (int k = 0; k < 2; ++k) \
;         acc[ai][bj][m][n] = __builtin_amdgcn_mfma_f32_16x16x32_bf16(Bt[n][k], At[m][k], acc[ai][bj][m][n], 0, 0, 0); __builtin_amdgcn_s_setprio(0); } while (0)
; #define PG8_WAIT_V(n) asm volatile("s_waitcnt vmcnt(" #n ")" ::: "memory")
; #define PG8_WAIT_L(n) asm volatile("s_waitcnt lgkmcnt(" #n ")" ::: "memory")
; #define PG8_BAR __builtin_amdgcn_s_barrier()
; #define PG8_SCHED __builtin_amdgcn_sched_barrier(0)
; template <class Epi>
; DEVI void gemm_phase(LAS unsigned char* lds, const bf16_t* gA, const bf16_t* gBt, const int lda, const int ldb, const int K, const StaticOrder S_, const Epi E) {
;     ...
;             PG8_STAGE(PG8_SB(0, 1), b2 + hstepB, voffB);
;             PG8_WAIT_V(6); PG8_BAR; PG8_MMA(1, 1, At, B1); PG8_BAR;
;             PG8_LDB(B0, 1, 0); PG8_SCHED; PG8_LDA(At, 1, 0); PG8_STAGE(PG8_SA(0, 1), a2 + hstepA, voffA);
;             PG8_WAIT_L(8); PG8_BAR; PG8_WAIT_L(0); PG8_MMA(0, 0, At, B0); PG8_BAR; PG8_SCHED;
;             PG8_LDB(B1, 1, 1); PG8_STAGE(PG8_SB(1, 0), b3, voffB);
	s_add_u32 s40, s40, s2
	s_addc_u32 s41, s41, s3
	s_add_i32 s78, s34, s18
	v_lshl_add_u64 v[232:233], s[40:41], 0, v[130:131]
	s_mov_b32 m0, s78
	v_lshl_add_u64 v[234:235], s[40:41], 0, v[134:135]
	global_load_lds_dwordx4 v[232:233], off
	s_add_i32 m0, s78, 0x2000
	s_nop 0
	global_load_lds_dwordx4 v[234:235], off
	s_waitcnt vmcnt(6)
	s_barrier
	v_mfma_f32_16x16x32_bf16 v[52:55], v[210:213], v[176:179], v[52:55]
	v_mfma_f32_16x16x32_bf16 v[48:51], v[218:221], v[176:179], v[48:51]
	v_mfma_f32_16x16x32_bf16 v[32:35], v[218:221], v[184:187], v[32:35]
	v_mfma_f32_16x16x32_bf16 v[36:39], v[210:213], v[184:187], v[36:39]
	v_mfma_f32_16x16x32_bf16 v[20:23], v[210:213], v[192:195], v[20:23]
	v_mfma_f32_16x16x32_bf16 v[16:19], v[218:221], v[192:195], v[16:19]
	v_mfma_f32_16x16x32_bf16 v[0:3], v[218:221], v[202:205], v[0:3]
	v_mfma_f32_16x16x32_bf16 v[4:7], v[210:213], v[202:205], v[4:7]
	v_mfma_f32_16x16x32_bf16 v[52:55], v[214:217], v[180:183], v[52:55]
	v_mfma_f32_16x16x32_bf16 v[48:51], v[222:225], v[180:183], v[48:51]
	v_mfma_f32_16x16x32_bf16 v[32:35], v[222:225], v[188:191], v[32:35]
	v_mfma_f32_16x16x32_bf16 v[36:39], v[214:217], v[188:191], v[36:39]
	v_mfma_f32_16x16x32_bf16 v[20:23], v[214:217], v[198:201], v[20:23]
	v_mfma_f32_16x16x32_bf16 v[16:19], v[222:225], v[198:201], v[16:19]
	v_mfma_f32_16x16x32_bf16 v[0:3], v[222:225], v[206:209], v[0:3]
	v_mfma_f32_16x16x32_bf16 v[4:7], v[214:217], v[206:209], v[4:7]
	s_barrier
	ds_read_b128 v[160:163], v156
	ds_read_b128 v[164:167], v156 offset:1024
	ds_read_b128 v[168:171], v156 offset:2048
	ds_read_b128 v[172:175], v156 offset:3072
	s_add_u32 s16, s16, s0
	s_addc_u32 s17, s17, s1
	s_mov_b32 m0, s21
	v_lshl_add_u64 v[210:211], s[16:17], 0, v[128:129]
	ds_read_b128 v[176:179], v154 offset:32768
	ds_read_b128 v[180:183], v154 offset:33792
	ds_read_b128 v[184:187], v154 offset:34816
	ds_read_b128 v[188:191], v154 offset:35840
	ds_read_b128 v[192:195], v154 offset:36864
	ds_read_b128 v[198:201], v154 offset:37888
	ds_read_b128 v[202:205], v154 offset:38912
	ds_read_b128 v[206:209], v154 offset:39936
	global_load_lds_dwordx4 v[210:211], off
	v_lshl_add_u64 v[210:211], s[16:17], 0, v[132:133]
	s_mov_b32 m0, s22
	s_nop 0
	global_load_lds_dwordx4 v[210:211], off
	s_waitcnt lgkmcnt(8)
	s_barrier
	s_waitcnt lgkmcnt(0)
	s_waitcnt lgkmcnt(0)
	v_mfma_f32_16x16x32_bf16 v[124:127], v[160:163], v[176:179], v[124:127]
	v_mfma_f32_16x16x32_bf16 v[120:123], v[168:171], v[176:179], v[120:123]
	v_mfma_f32_16x16x32_bf16 v[104:107], v[168:171], v[184:187], v[104:107]
	v_mfma_f32_16x16x32_bf16 v[108:111], v[160:163], v[184:187], v[108:111]
	v_mfma_f32_16x16x32_bf16 v[92:95], v[160:163], v[192:195], v[92:95]
	v_mfma_f32_16x16x32_bf16 v[88:91], v[168:171], v[192:195], v[88:91]
	v_mfma_f32_16x16x32_bf16 v[72:75], v[168:171], v[202:205], v[72:75]
	v_mfma_f32_16x16x32_bf16 v[76:79], v[160:163], v[202:205], v[76:79]
	v_mfma_f32_16x16x32_bf16 v[124:127], v[164:167], v[180:183], v[124:127]
	v_mfma_f32_16x16x32_bf16 v[120:123], v[172:175], v[180:183], v[120:123]
	v_mfma_f32_16x16x32_bf16 v[104:107], v[172:175], v[188:191], v[104:107]
	v_mfma_f32_16x16x32_bf16 v[108:111], v[164:167], v[188:191], v[108:111]
	v_mfma_f32_16x16x32_bf16 v[92:95], v[164:167], v[198:201], v[92:95]
	v_mfma_f32_16x16x32_bf16 v[88:91], v[172:175], v[198:201], v[88:91]
	v_mfma_f32_16x16x32_bf16 v[72:75], v[172:175], v[206:209], v[72:75]
	v_mfma_f32_16x16x32_bf16 v[76:79], v[164:167], v[206:209], v[76:79]
	s_barrier
	s_add_i32 s16, s35, s18
	v_lshl_add_u64 v[144:145], v[144:145], 0, s[46:47]
	s_mov_b32 m0, s16
	ds_read_b128 v[210:213], v157
	ds_read_b128 v[214:217], v157 offset:1024
	ds_read_b128 v[218:221], v157 offset:2048
	ds_read_b128 v[222:225], v157 offset:3072
	global_load_lds_dwordx4 v[144:145], off
	v_lshl_add_u64 v[144:145], v[226:227], 0, s[46:47]
	s_add_i32 m0, s16, 0x2000
	s_nop 0
	global_load_lds_dwordx4 v[144:145], off
	s_barrier
; #define PG8_STAGE(bufoff, gbase, voff) do { _Pragma("unroll") for (int _i = 0; _i < 2; ++_i) \
;         __builtin_amdgcn_global_load_lds((const unsigned*)((const char*)(gbase) + (voff)[_i]), (LAS unsigned*)(lds + (bufoff) + ldsw + _i * 8192), 16, 0, 0); } while (0)
; #define PG8_LDA(dst, b, h) do { _Pragma("unroll") for (int m = 0; m < 4; ++m) _Pragma("unroll") for (int k = 0; k < 2; ++k) dst[m][k] = *(const LAS bf16x8*)(lds + PG8_SA(b, h) + aoff + m * 2048 + k * 1024); } while (0)
; #define PG8_MMA(ai, bj, At, Bt) do { __builtin_amdgcn_s_setprio(1); _Pragma("unroll") for (int m = 0; m < 4; ++m) _Pragma("unroll") for (int n = 0; n < 2; ++n) _Pragma("unroll") for (int k = 0; k < 2; ++k) \
;         acc[ai][bj][m][n] = __builtin_amdgcn_mfma_f32_16x16x32_bf16(Bt[n][k], At[m][k], acc[ai][bj][m][n], 0, 0, 0); __builtin_amdgcn_s_setprio(0); } while (0)
; #define PG8_WAIT_V(n) asm volatile("s_waitcnt vmcnt(" #n ")" ::: "memory")
; #define PG8_WAIT_L(n) asm volatile("s_waitcnt lgkmcnt(" #n ")" ::: "memory")
; #define PG8_BAR __builtin_amdgcn_s_barrier()
; #define PG8_SCHED __builtin_amdgcn_sched_barrier(0)
; template <class Epi>
; DEVI void gemm_phase(LAS unsigned char* lds, const bf16_t* gA, const bf16_t* gBt, const int lda, const int ldb, const int K, const StaticOrder S_, const Epi E) {
;     ...
;             PG8_BAR; PG8_WAIT_L(0); PG8_MMA(0, 1, At, B1); PG8_BAR;
;             PG8_LDA(At, 1, 1); PG8_STAGE(PG8_SA(1, 0), a3, voffA);
;             PG8_BAR; PG8_WAIT_L(0); PG8_MMA(1, 0, At, B0); PG8_BAR; PG8_SCHED;
;             PG8_STAGE(PG8_SB(1, 1), b3 + hstepB, voffB);
;             PG8_WAIT_V(6); PG8_BAR; PG8_MMA(1, 1, At, B1); PG8_BAR;
	s_waitcnt lgkmcnt(0)
	s_waitcnt lgkmcnt(0)
	v_mfma_f32_16x16x32_bf16 v[116:119], v[210:213], v[176:179], v[116:119]
	v_mfma_f32_16x16x32_bf16 v[112:115], v[218:221], v[176:179], v[112:115]
	v_mfma_f32_16x16x32_bf16 v[96:99], v[218:221], v[184:187], v[96:99]
	v_mfma_f32_16x16x32_bf16 v[100:103], v[210:213], v[184:187], v[100:103]
	v_mfma_f32_16x16x32_bf16 v[84:87], v[210:213], v[192:195], v[84:87]
	v_mfma_f32_16x16x32_bf16 v[80:83], v[218:221], v[192:195], v[80:83]
	v_mfma_f32_16x16x32_bf16 v[64:67], v[218:221], v[202:205], v[64:67]
	v_mfma_f32_16x16x32_bf16 v[68:71], v[210:213], v[202:205], v[68:71]
	v_mfma_f32_16x16x32_bf16 v[116:119], v[214:217], v[180:183], v[116:119]
	v_mfma_f32_16x16x32_bf16 v[112:115], v[222:225], v[180:183], v[112:115]
	v_mfma_f32_16x16x32_bf16 v[96:99], v[222:225], v[188:191], v[96:99]
	v_mfma_f32_16x16x32_bf16 v[100:103], v[214:217], v[188:191], v[100:103]
	v_mfma_f32_16x16x32_bf16 v[84:87], v[214:217], v[198:201], v[84:87]
	v_mfma_f32_16x16x32_bf16 v[80:83], v[222:225], v[198:201], v[80:83]
	v_mfma_f32_16x16x32_bf16 v[64:67], v[222:225], v[206:209], v[64:67]
	v_mfma_f32_16x16x32_bf16 v[68:71], v[214:217], v[206:209], v[68:71]
	s_mov_b32 m0, s23
	v_lshl_add_u64 v[144:145], v[228:229], 0, s[46:47]
	s_barrier
	ds_read_b128 v[176:179], v154 offset:49152
	ds_read_b128 v[180:183], v154 offset:50176
	ds_read_b128 v[184:187], v154 offset:51200
	ds_read_b128 v[188:191], v154 offset:52224
	ds_read_b128 v[192:195], v154 offset:53248
	ds_read_b128 v[198:201], v154 offset:54272
	ds_read_b128 v[202:205], v154 offset:55296
	ds_read_b128 v[206:209], v154 offset:56320
	global_load_lds_dwordx4 v[144:145], off
	v_lshl_add_u64 v[144:145], v[230:231], 0, s[46:47]
	s_mov_b32 m0, s24
	s_nop 0
	global_load_lds_dwordx4 v[144:145], off
	s_barrier
	s_waitcnt lgkmcnt(0)
	s_waitcnt lgkmcnt(0)
	v_mfma_f32_16x16x32_bf16 v[60:63], v[160:163], v[176:179], v[60:63]
	v_mfma_f32_16x16x32_bf16 v[56:59], v[168:171], v[176:179], v[56:59]
	v_mfma_f32_16x16x32_bf16 v[40:43], v[168:171], v[184:187], v[40:43]
	v_mfma_f32_16x16x32_bf16 v[44:47], v[160:163], v[184:187], v[44:47]
	v_mfma_f32_16x16x32_bf16 v[28:31], v[160:163], v[192:195], v[28:31]
	v_mfma_f32_16x16x32_bf16 v[24:27], v[168:171], v[192:195], v[24:27]
	v_mfma_f32_16x16x32_bf16 v[8:11], v[168:171], v[202:205], v[8:11]
	v_mfma_f32_16x16x32_bf16 v[12:15], v[160:163], v[202:205], v[12:15]
	v_mfma_f32_16x16x32_bf16 v[60:63], v[164:167], v[180:183], v[60:63]
	v_mfma_f32_16x16x32_bf16 v[56:59], v[172:175], v[180:183], v[56:59]
	v_mfma_f32_16x16x32_bf16 v[40:43], v[172:175], v[188:191], v[40:43]
	v_mfma_f32_16x16x32_bf16 v[44:47], v[164:167], v[188:191], v[44:47]
	v_mfma_f32_16x16x32_bf16 v[28:31], v[164:167], v[198:201], v[28:31]
	v_mfma_f32_16x16x32_bf16 v[24:27], v[172:175], v[198:201], v[24:27]
	v_mfma_f32_16x16x32_bf16 v[8:11], v[172:175], v[206:209], v[8:11]
	v_mfma_f32_16x16x32_bf16 v[12:15], v[164:167], v[206:209], v[12:15]
	s_barrier
	s_add_i32 s16, s50, s18
	v_lshl_add_u64 v[144:145], v[232:233], 0, s[46:47]
	s_mov_b32 m0, s16
	s_nop 0
	global_load_lds_dwordx4 v[144:145], off
	v_lshl_add_u64 v[144:145], v[234:235], 0, s[46:47]
	s_add_i32 m0, s16, 0x2000
	s_nop 0
	global_load_lds_dwordx4 v[144:145], off
	s_waitcnt vmcnt(6)
	s_barrier
	v_mfma_f32_16x16x32_bf16 v[52:55], v[210:213], v[176:179], v[52:55]
	v_mfma_f32_16x16x32_bf16 v[48:51], v[218:221], v[176:179], v[48:51]
	v_mfma_f32_16x16x32_bf16 v[32:35], v[218:221], v[184:187], v[32:35]
	v_mfma_f32_16x16x32_bf16 v[36:39], v[210:213], v[184:187], v[36:39]
	v_mfma_f32_16x16x32_bf16 v[20:23], v[210:213], v[192:195], v[20:23]
	v_mfma_f32_16x16x32_bf16 v[16:19], v[218:221], v[192:195], v[16:19]
	v_mfma_f32_16x16x32_bf16 v[0:3], v[218:221], v[202:205], v[0:3]
	v_mfma_f32_16x16x32_bf16 v[4:7], v[210:213], v[202:205], v[4:7]
	v_mfma_f32_16x16x32_bf16 v[52:55], v[214:217], v[180:183], v[52:55]
	v_mfma_f32_16x16x32_bf16 v[48:51], v[222:225], v[180:183], v[48:51]
	v_mfma_f32_16x16x32_bf16 v[32:35], v[222:225], v[188:191], v[32:35]
	v_mfma_f32_16x16x32_bf16 v[36:39], v[214:217], v[188:191], v[36:39]
	v_mfma_f32_16x16x32_bf16 v[20:23], v[214:217], v[198:201], v[20:23]
	v_mfma_f32_16x16x32_bf16 v[16:19], v[222:225], v[198:201], v[16:19]
	v_mfma_f32_16x16x32_bf16 v[0:3], v[222:225], v[206:209], v[0:3]
	v_mfma_f32_16x16x32_bf16 v[4:7], v[214:217], v[206:209], v[4:7]
	s_add_u32 s14, s14, 0x100
	s_addc_u32 s15, s15, 0
	s_add_u32 s68, s68, 0x100
	s_addc_u32 s69, s69, 0
	s_cmp_ge_i32 s77, s25
	s_mov_b32 s16, s77
	s_barrier
	s_cbranch_scc0 .LBB0_519
	v_readlane_b32 s78, v240, 54
	v_readlane_b32 s79, v240, 55

; #define PG8_STAGE(bufoff, gbase, voff) do { _Pragma("unroll") for (int _i = 0; _i < 2; ++_i) \
;         __builtin_amdgcn_global_load_lds((const unsigned*)((const char*)(gbase) + (voff)[_i]), (LAS unsigned*)(lds + (bufoff) + ldsw + _i * 8192), 16, 0, 0); } while (0)
; #define PG8_LDA(dst, b, h) do { _Pragma("unroll") for (int m = 0; m < 4; ++m) _Pragma("unroll") for (int k = 0; k < 2; ++k) dst[m][k] = *(const LAS bf16x8*)(lds + PG8_SA(b, h) + aoff + m * 2048 + k * 1024); } while (0)
; #define PG8_LDB(dst, b, h) do { _Pragma("unroll") for (int n = 0; n < 2; ++n) _Pragma("unroll") for (int k = 0; k < 2; ++k) dst[n][k] = *(const LAS bf16x8*)(lds + PG8_SB(b, h) + boff + n * 2048 + k * 1024); } while (0)
; #define PG8_MMA(ai, bj, At, Bt) do { __builtin_amdgcn_s_setprio(1); _Pragma("unroll") for (int m = 0; m < 4; ++m) _Pragma("unroll") for (int n = 0; n < 2; ++n) _Pragma("unroll") for (int k = 0; k < 2; ++k) \
;         acc[ai][bj][m][n] = __builtin_amdgcn_mfma_f32_16x16x32_bf16(Bt[n][k], At[m][k], acc[ai][bj][m][n], 0, 0, 0); __builtin_amdgcn_s_setprio(0); } while (0)
; #define PG8_WAIT_L(n) asm volatile("s_waitcnt lgkmcnt(" #n ")" ::: "memory")
; #define PG8_BAR __builtin_amdgcn_s_barrier()
; #define PG8_SCHED __builtin_amdgcn_sched_barrier(0)
; template <class Epi>
; DEVI void gemm_phase(LAS unsigned char* lds, const bf16_t* gA, const bf16_t* gBt, const int lda, const int ldb, const int K, const StaticOrder S_, const Epi E) {
;     ...
;             PG8_LDB(B0, 0, 0); PG8_SCHED; PG8_LDA(At, 0, 0); PG8_STAGE(PG8_SA(1, 1), a1 + hstepA, voffA);
;             PG8_WAIT_L(8); PG8_BAR; PG8_WAIT_L(0); PG8_MMA(0, 0, At, B0); PG8_BAR; PG8_SCHED;
;             PG8_LDB(B1, 0, 1); PG8_STAGE(PG8_SB(0, 0), b2, voffB);
;             PG8_BAR; PG8_WAIT_L(0); PG8_MMA(0, 1, At, B1); PG8_BAR;
;             PG8_LDA(At, 0, 1); PG8_STAGE(PG8_SA(0, 0), a2, voffA);
;             PG8_BAR; PG8_WAIT_L(0); PG8_MMA(1, 0, At, B0); PG8_BAR; PG8_SCHED;
.LBB0_744:
	ds_read_b128 v[160:163], v153
	ds_read_b128 v[164:167], v153 offset:1024
	ds_read_b128 v[168:171], v153 offset:2048
	ds_read_b128 v[172:175], v153 offset:3072
	s_add_i32 s77, s16, 2
	s_add_u32 s40, s14, 0x80
	s_addc_u32 s17, s15, 0
	s_cmp_eq_u32 s26, s16
	s_cselect_b32 s16, s48, s40
	s_cselect_b32 s17, s49, s17
	s_cselect_b32 s41, s61, s65
	s_cselect_b32 s40, s60, s64
	v_lshl_add_u64 v[144:145], s[14:15], 0, v[138:139]
	s_add_i32 m0, s19, 0xc000
	ds_read_b128 v[176:179], v154
	ds_read_b128 v[180:183], v154 offset:1024
	ds_read_b128 v[184:187], v154 offset:2048
	ds_read_b128 v[188:191], v154 offset:3072
	ds_read_b128 v[192:195], v154 offset:4096
	ds_read_b128 v[198:201], v154 offset:5120
	ds_read_b128 v[202:205], v154 offset:6144
	ds_read_b128 v[206:209], v154 offset:7168
	global_load_lds_dwordx4 v[144:145], off
	v_lshl_add_u64 v[144:145], s[14:15], 0, v[140:141]
	s_add_i32 m0, s19, 0xe000
	s_nop 0
	global_load_lds_dwordx4 v[144:145], off
	s_waitcnt lgkmcnt(8)
	s_barrier
	s_waitcnt lgkmcnt(0)
	s_waitcnt lgkmcnt(0)
	v_mfma_f32_16x16x32_bf16 v[124:127], v[160:163], v[176:179], v[124:127]
	v_mfma_f32_16x16x32_bf16 v[120:123], v[168:171], v[176:179], v[120:123]
	v_mfma_f32_16x16x32_bf16 v[104:107], v[168:171], v[184:187], v[104:107]
	v_mfma_f32_16x16x32_bf16 v[108:111], v[160:163], v[184:187], v[108:111]
	v_mfma_f32_16x16x32_bf16 v[92:95], v[160:163], v[192:195], v[92:95]
	v_mfma_f32_16x16x32_bf16 v[88:91], v[168:171], v[192:195], v[88:91]
	v_mfma_f32_16x16x32_bf16 v[72:75], v[168:171], v[202:205], v[72:75]
	v_mfma_f32_16x16x32_bf16 v[76:79], v[160:163], v[202:205], v[76:79]
	v_mfma_f32_16x16x32_bf16 v[124:127], v[164:167], v[180:183], v[124:127]
	v_mfma_f32_16x16x32_bf16 v[120:123], v[172:175], v[180:183], v[120:123]
	v_mfma_f32_16x16x32_bf16 v[104:107], v[172:175], v[188:191], v[104:107]
	v_mfma_f32_16x16x32_bf16 v[108:111], v[164:167], v[188:191], v[108:111]
	v_mfma_f32_16x16x32_bf16 v[92:95], v[164:167], v[198:201], v[92:95]
	v_mfma_f32_16x16x32_bf16 v[88:91], v[172:175], v[198:201], v[88:91]
	v_mfma_f32_16x16x32_bf16 v[72:75], v[172:175], v[206:209], v[72:75]
	v_mfma_f32_16x16x32_bf16 v[76:79], v[164:167], v[206:209], v[76:79]
	s_barrier
	s_add_i32 s78, s31, s18
	v_lshl_add_u64 v[144:145], s[40:41], 0, v[130:131]
	s_mov_b32 m0, s78
	ds_read_b128 v[210:213], v155
	ds_read_b128 v[214:217], v155 offset:1024
	ds_read_b128 v[218:221], v155 offset:2048
	ds_read_b128 v[222:225], v155 offset:3072
	global_load_lds_dwordx4 v[144:145], off
	v_lshl_add_u64 v[226:227], s[40:41], 0, v[134:135]
	s_add_i32 m0, s78, 0x2000
	s_nop 0
	global_load_lds_dwordx4 v[226:227], off
	s_barrier
	s_waitcnt lgkmcnt(0)
	s_waitcnt lgkmcnt(0)
	v_mfma_f32_16x16x32_bf16 v[116:119], v[210:213], v[176:179], v[116:119]
	v_mfma_f32_16x16x32_bf16 v[112:115], v[218:221], v[176:179], v[112:115]
	v_mfma_f32_16x16x32_bf16 v[96:99], v[218:221], v[184:187], v[96:99]
	v_mfma_f32_16x16x32_bf16 v[100:103], v[210:213], v[184:187], v[100:103]
	v_mfma_f32_16x16x32_bf16 v[84:87], v[210:213], v[192:195], v[84:87]
	v_mfma_f32_16x16x32_bf16 v[80:83], v[218:221], v[192:195], v[80:83]
	v_mfma_f32_16x16x32_bf16 v[64:67], v[218:221], v[202:205], v[64:67]
	v_mfma_f32_16x16x32_bf16 v[68:71], v[210:213], v[202:205], v[68:71]
	v_mfma_f32_16x16x32_bf16 v[116:119], v[214:217], v[180:183], v[116:119]
	v_mfma_f32_16x16x32_bf16 v[112:115], v[222:225], v[180:183], v[112:115]
	v_mfma_f32_16x16x32_bf16 v[96:99], v[222:225], v[188:191], v[96:99]
	v_mfma_f32_16x16x32_bf16 v[100:103], v[214:217], v[188:191], v[100:103]
	v_mfma_f32_16x16x32_bf16 v[84:87], v[214:217], v[198:201], v[84:87]
	v_mfma_f32_16x16x32_bf16 v[80:83], v[222:225], v[198:201], v[80:83]
	v_mfma_f32_16x16x32_bf16 v[64:67], v[222:225], v[206:209], v[64:67]
	v_mfma_f32_16x16x32_bf16 v[68:71], v[214:217], v[206:209], v[68:71]
	s_mov_b32 m0, s19
	v_lshl_add_u64 v[228:229], s[16:17], 0, v[128:129]
	s_barrier
	ds_read_b128 v[176:179], v154 offset:16384
	ds_read_b128 v[180:183], v154 offset:17408
	ds_read_b128 v[184:187], v154 offset:18432
	ds_read_b128 v[188:191], v154 offset:19456
	ds_read_b128 v[192:195], v154 offset:20480
	ds_read_b128 v[198:201], v154 offset:21504
	ds_read_b128 v[202:205], v154 offset:22528
	ds_read_b128 v[206:209], v154 offset:23552
	global_load_lds_dwordx4 v[228:229], off
	v_lshl_add_u64 v[230:231], s[16:17], 0, v[132:133]
	s_mov_b32 m0, s20
	s_nop 0
	global_load_lds_dwordx4 v[230:231], off
	s_barrier
	s_waitcnt lgkmcnt(0)
	s_waitcnt lgkmcnt(0)
	v_mfma_f32_16x16x32_bf16 v[60:63], v[160:163], v[176:179], v[60:63]
	v_mfma_f32_16x16x32_bf16 v[56:59], v[168:171], v[176:179], v[56:59]
	v_mfma_f32_16x16x32_bf16 v[40:43], v[168:171], v[184:187], v[40:43]
	v_mfma_f32_16x16x32_bf16 v[44:47], v[160:163], v[184:187], v[44:47]
	v_mfma_f32_16x16x32_bf16 v[28:31], v[160:163], v[192:195], v[28:31]
	v_mfma_f32_16x16x32_bf16 v[24:27], v[168:171], v[192:195], v[24:27]
	v_mfma_f32_16x16x32_bf16 v[8:11], v[168:171], v[202:205], v[8:11]
	v_mfma_f32_16x16x32_bf16 v[12:15], v[160:163], v[202:205], v[12:15]
	v_mfma_f32_16x16x32_bf16 v[60:63], v[164:167], v[180:183], v[60:63]
	v_mfma_f32_16x16x32_bf16 v[56:59], v[172:175], v[180:183], v[56:59]
	v_mfma_f32_16x16x32_bf16 v[40:43], v[172:175], v[188:191], v[40:43]
	v_mfma_f32_16x16x32_bf16 v[44:47], v[164:167], v[188:191], v[44:47]
	v_mfma_f32_16x16x32_bf16 v[28:31], v[164:167], v[198:201], v[28:31]
	v_mfma_f32_16x16x32_bf16 v[24:27], v[172:175], v[198:201], v[24:27]
	v_mfma_f32_16x16x32_bf16 v[8:11], v[172:175], v[206:209], v[8:11]
	v_mfma_f32_16x16x32_bf16 v[12:15], v[164:167], v[206:209], v[12:15]
	s_barrier
; #define PG8_STAGE(bufoff, gbase, voff) do { _Pragma("unroll") for (int _i = 0; _i < 2; ++_i) \
;         __builtin_amdgcn_global_load_lds((const unsigned*)((const char*)(gbase) + (voff)[_i]), (LAS unsigned*)(lds + (bufoff) + ldsw + _i * 8192), 16, 0, 0); } while (0)
; #define PG8_LDA(dst, b, h) do { _Pragma("unroll") for (int m = 0; m < 4; ++m) _Pragma("unroll") for (int k = 0; k < 2; ++k) dst[m][k] = *(const LAS bf16x8*)(lds + PG8_SA(b, h) + aoff + m * 2048 + k * 1024); } while (0)
; #define PG8_LDB(dst, b, h) do { _Pragma("unroll") for (int n = 0; n < 2; ++n) _Pragma("unroll") for (int k = 0; k < 2; ++k) dst[n][k] = *(const LAS bf16x8*)(lds + PG8_SB(b, h) + boff + n * 2048 + k * 1024); } while (0)
; #define PG8_MMA(ai, bj, At, Bt) do { __builtin_amdgcn_s_setprio(1); _Pragma("unroll") for (int m = 0; m < 4; ++m) _Pragma("unroll") for (int n = 0; n < 2; ++n) _Pragma("unroll") for (int k = 0; k < 2; ++k) \
;         acc[ai][bj][m][n] = __builtin_amdgcn_mfma_f32_16x16x32_bf16(Bt[n][k], At[m][k], acc[ai][bj][m][n], 0, 0, 0); __builtin_amdgcn_s_setprio(0); } while (0)
; #define PG8_WAIT_V(n) asm volatile("s_waitcnt vmcnt(" #n ")" ::: "memory")
; #define PG8_WAIT_L(n) asm volatile("s_waitcnt lgkmcnt(" #n ")" ::: "memory")
; #define PG8_BAR __builtin_amdgcn_s_barrier()
; #define PG8_SCHED __builtin_amdgcn_sched_barrier(0)
; template <class Epi>
; DEVI void gemm_phase(LAS unsigned char* lds, const bf16_t* gA, const bf16_t* gBt, const int lda, const int ldb, const int K, const StaticOrder S_, const Epi E) {
;     ...
;             PG8_STAGE(PG8_SB(0, 1), b2 + hstepB, voffB);
;             PG8_WAIT_V(6); PG8_BAR; PG8_MMA(1, 1, At, B1); PG8_BAR;
;             PG8_LDB(B0, 1, 0); PG8_SCHED; PG8_LDA(At, 1, 0); PG8_STAGE(PG8_SA(0, 1), a2 + hstepA, voffA);
;             PG8_WAIT_L(8); PG8_BAR; PG8_WAIT_L(0); PG8_MMA(0, 0, At, B0); PG8_BAR; PG8_SCHED;
;             PG8_LDB(B1, 1, 1); PG8_STAGE(PG8_SB(1, 0), b3, voffB);
	s_add_u32 s40, s40, s2
	s_addc_u32 s41, s41, s3
	s_add_i32 s78, s34, s18
	v_lshl_add_u64 v[232:233], s[40:41], 0, v[130:131]
	s_mov_b32 m0, s78
	v_lshl_add_u64 v[234:235], s[40:41], 0, v[134:135]
	global_load_lds_dwordx4 v[232:233], off
	s_add_i32 m0, s78, 0x2000
	s_nop 0
	global_load_lds_dwordx4 v[234:235], off
	s_waitcnt vmcnt(6)
	s_barrier
	v_mfma_f32_16x16x32_bf16 v[52:55], v[210:213], v[176:179], v[52:55]
	v_mfma_f32_16x16x32_bf16 v[48:51], v[218:221], v[176:179], v[48:51]
	v_mfma_f32_16x16x32_bf16 v[32:35], v[218:221], v[184:187], v[32:35]
	v_mfma_f32_16x16x32_bf16 v[36:39], v[210:213], v[184:187], v[36:39]
	v_mfma_f32_16x16x32_bf16 v[20:23], v[210:213], v[192:195], v[20:23]
	v_mfma_f32_16x16x32_bf16 v[16:19], v[218:221], v[192:195], v[16:19]
	v_mfma_f32_16x16x32_bf16 v[0:3], v[218:221], v[202:205], v[0:3]
	v_mfma_f32_16x16x32_bf16 v[4:7], v[210:213], v[202:205], v[4:7]
	v_mfma_f32_16x16x32_bf16 v[52:55], v[214:217], v[180:183], v[52:55]
	v_mfma_f32_16x16x32_bf16 v[48:51], v[222:225], v[180:183], v[48:51]
	v_mfma_f32_16x16x32_bf16 v[32:35], v[222:225], v[188:191], v[32:35]
	v_mfma_f32_16x16x32_bf16 v[36:39], v[214:217], v[188:191], v[36:39]
	v_mfma_f32_16x16x32_bf16 v[20:23], v[214:217], v[198:201], v[20:23]
	v_mfma_f32_16x16x32_bf16 v[16:19], v[222:225], v[198:201], v[16:19]
	v_mfma_f32_16x16x32_bf16 v[0:3], v[222:225], v[206:209], v[0:3]
	v_mfma_f32_16x16x32_bf16 v[4:7], v[214:217], v[206:209], v[4:7]
	s_barrier
	ds_read_b128 v[160:163], v156
	ds_read_b128 v[164:167], v156 offset:1024
	ds_read_b128 v[168:171], v156 offset:2048
	ds_read_b128 v[172:175], v156 offset:3072
	s_add_u32 s16, s16, s0
	s_addc_u32 s17, s17, s1
	s_mov_b32 m0, s21
	v_lshl_add_u64 v[210:211], s[16:17], 0, v[128:129]
	ds_read_b128 v[176:179], v154 offset:32768
	ds_read_b128 v[180:183], v154 offset:33792
	ds_read_b128 v[184:187], v154 offset:34816
	ds_read_b128 v[188:191], v154 offset:35840
	ds_read_b128 v[192:195], v154 offset:36864
	ds_read_b128 v[198:201], v154 offset:37888
	ds_read_b128 v[202:205], v154 offset:38912
	ds_read_b128 v[206:209], v154 offset:39936
	global_load_lds_dwordx4 v[210:211], off
	v_lshl_add_u64 v[210:211], s[16:17], 0, v[132:133]
	s_mov_b32 m0, s22
	s_nop 0
	global_load_lds_dwordx4 v[210:211], off
	s_waitcnt lgkmcnt(8)
	s_barrier
	s_waitcnt lgkmcnt(0)
	s_waitcnt lgkmcnt(0)
	v_mfma_f32_16x16x32_bf16 v[124:127], v[160:163], v[176:179], v[124:127]
	v_mfma_f32_16x16x32_bf16 v[120:123], v[168:171], v[176:179], v[120:123]
	v_mfma_f32_16x16x32_bf16 v[104:107], v[168:171], v[184:187], v[104:107]
	v_mfma_f32_16x16x32_bf16 v[108:111], v[160:163], v[184:187], v[108:111]
	v_mfma_f32_16x16x32_bf16 v[92:95], v[160:163], v[192:195], v[92:95]
	v_mfma_f32_16x16x32_bf16 v[88:91], v[168:171], v[192:195], v[88:91]
	v_mfma_f32_16x16x32_bf16 v[72:75], v[168:171], v[202:205], v[72:75]
	v_mfma_f32_16x16x32_bf16 v[76:79], v[160:163], v[202:205], v[76:79]
	v_mfma_f32_16x16x32_bf16 v[124:127], v[164:167], v[180:183], v[124:127]
	v_mfma_f32_16x16x32_bf16 v[120:123], v[172:175], v[180:183], v[120:123]
	v_mfma_f32_16x16x32_bf16 v[104:107], v[172:175], v[188:191], v[104:107]
	v_mfma_f32_16x16x32_bf16 v[108:111], v[164:167], v[188:191], v[108:111]
	v_mfma_f32_16x16x32_bf16 v[92:95], v[164:167], v[198:201], v[92:95]
	v_mfma_f32_16x16x32_bf16 v[88:91], v[172:175], v[198:201], v[88:91]
	v_mfma_f32_16x16x32_bf16 v[72:75], v[172:175], v[206:209], v[72:75]
	v_mfma_f32_16x16x32_bf16 v[76:79], v[164:167], v[206:209], v[76:79]
	s_barrier
	s_add_i32 s16, s35, s18
	v_lshl_add_u64 v[144:145], v[144:145], 0, s[46:47]
	s_mov_b32 m0, s16
	ds_read_b128 v[210:213], v157
	ds_read_b128 v[214:217], v157 offset:1024
	ds_read_b128 v[218:221], v157 offset:2048
	ds_read_b128 v[222:225], v157 offset:3072
	global_load_lds_dwordx4 v[144:145], off
	v_lshl_add_u64 v[144:145], v[226:227], 0, s[46:47]
	s_add_i32 m0, s16, 0x2000
	s_nop 0
	global_load_lds_dwordx4 v[144:145], off
	s_barrier
; #define PG8_STAGE(bufoff, gbase, voff) do { _Pragma("unroll") for (int _i = 0; _i < 2; ++_i) \
;         __builtin_amdgcn_global_load_lds((const unsigned*)((const char*)(gbase) + (voff)[_i]), (LAS unsigned*)(lds + (bufoff) + ldsw + _i * 8192), 16, 0, 0); } while (0)
; #define PG8_LDA(dst, b, h) do { _Pragma("unroll") for (int m = 0; m < 4; ++m) _Pragma("unroll") for (int k = 0; k < 2; ++k) dst[m][k] = *(const LAS bf16x8*)(lds + PG8_SA(b, h) + aoff + m * 2048 + k * 1024); } while (0)
; #define PG8_MMA(ai, bj, At, Bt) do { __builtin_amdgcn_s_setprio(1); _Pragma("unroll") for (int m = 0; m < 4; ++m) _Pragma("unroll") for (int n = 0; n < 2; ++n) _Pragma("unroll") for (int k = 0; k < 2; ++k) \
;         acc[ai][bj][m][n] = __builtin_amdgcn_mfma_f32_16x16x32_bf16(Bt[n][k], At[m][k], acc[ai][bj][m][n], 0, 0, 0); __builtin_amdgcn_s_setprio(0); } while (0)
; #define PG8_WAIT_V(n) asm volatile("s_waitcnt vmcnt(" #n ")" ::: "memory")
; #define PG8_WAIT_L(n) asm volatile("s_waitcnt lgkmcnt(" #n ")" ::: "memory")
; #define PG8_BAR __builtin_amdgcn_s_barrier()
; #define PG8_SCHED __builtin_amdgcn_sched_barrier(0)
; template <class Epi>
; DEVI void gemm_phase(LAS unsigned char* lds, const bf16_t* gA, const bf16_t* gBt, const int lda, const int ldb, const int K, const StaticOrder S_, const Epi E) {
;     ...
;             PG8_BAR; PG8_WAIT_L(0); PG8_MMA(0, 1, At, B1); PG8_BAR;
;             PG8_LDA(At, 1, 1); PG8_STAGE(PG8_SA(1, 0), a3, voffA);
;             PG8_BAR; PG8_WAIT_L(0); PG8_MMA(1, 0, At, B0); PG8_BAR; PG8_SCHED;
;             PG8_STAGE(PG8_SB(1, 1), b3 + hstepB, voffB);
;             PG8_WAIT_V(6); PG8_BAR; PG8_MMA(1, 1, At, B1); PG8_BAR;
	s_waitcnt lgkmcnt(0)
	s_waitcnt lgkmcnt(0)
	v_mfma_f32_16x16x32_bf16 v[116:119], v[210:213], v[176:179], v[116:119]
	v_mfma_f32_16x16x32_bf16 v[112:115], v[218:221], v[176:179], v[112:115]
	v_mfma_f32_16x16x32_bf16 v[96:99], v[218:221], v[184:187], v[96:99]
	v_mfma_f32_16x16x32_bf16 v[100:103], v[210:213], v[184:187], v[100:103]
	v_mfma_f32_16x16x32_bf16 v[84:87], v[210:213], v[192:195], v[84:87]
	v_mfma_f32_16x16x32_bf16 v[80:83], v[218:221], v[192:195], v[80:83]
	v_mfma_f32_16x16x32_bf16 v[64:67], v[218:221], v[202:205], v[64:67]
	v_mfma_f32_16x16x32_bf16 v[68:71], v[210:213], v[202:205], v[68:71]
	v_mfma_f32_16x16x32_bf16 v[116:119], v[214:217], v[180:183], v[116:119]
	v_mfma_f32_16x16x32_bf16 v[112:115], v[222:225], v[180:183], v[112:115]
	v_mfma_f32_16x16x32_bf16 v[96:99], v[222:225], v[188:191], v[96:99]
	v_mfma_f32_16x16x32_bf16 v[100:103], v[214:217], v[188:191], v[100:103]
	v_mfma_f32_16x16x32_bf16 v[84:87], v[214:217], v[198:201], v[84:87]
	v_mfma_f32_16x16x32_bf16 v[80:83], v[222:225], v[198:201], v[80:83]
	v_mfma_f32_16x16x32_bf16 v[64:67], v[222:225], v[206:209], v[64:67]
	v_mfma_f32_16x16x32_bf16 v[68:71], v[214:217], v[206:209], v[68:71]
	s_mov_b32 m0, s23
	v_lshl_add_u64 v[144:145], v[228:229], 0, s[46:47]
	s_barrier
	ds_read_b128 v[176:179], v154 offset:49152
	ds_read_b128 v[180:183], v154 offset:50176
	ds_read_b128 v[184:187], v154 offset:51200
	ds_read_b128 v[188:191], v154 offset:52224
	ds_read_b128 v[192:195], v154 offset:53248
	ds_read_b128 v[198:201], v154 offset:54272
	ds_read_b128 v[202:205], v154 offset:55296
	ds_read_b128 v[206:209], v154 offset:56320
	global_load_lds_dwordx4 v[144:145], off
	v_lshl_add_u64 v[144:145], v[230:231], 0, s[46:47]
	s_mov_b32 m0, s24
	s_nop 0
	global_load_lds_dwordx4 v[144:145], off
	s_barrier
	s_waitcnt lgkmcnt(0)
	s_waitcnt lgkmcnt(0)
	v_mfma_f32_16x16x32_bf16 v[60:63], v[160:163], v[176:179], v[60:63]
	v_mfma_f32_16x16x32_bf16 v[56:59], v[168:171], v[176:179], v[56:59]
	v_mfma_f32_16x16x32_bf16 v[40:43], v[168:171], v[184:187], v[40:43]
	v_mfma_f32_16x16x32_bf16 v[44:47], v[160:163], v[184:187], v[44:47]
	v_mfma_f32_16x16x32_bf16 v[28:31], v[160:163], v[192:195], v[28:31]
	v_mfma_f32_16x16x32_bf16 v[24:27], v[168:171], v[192:195], v[24:27]
	v_mfma_f32_16x16x32_bf16 v[8:11], v[168:171], v[202:205], v[8:11]
	v_mfma_f32_16x16x32_bf16 v[12:15], v[160:163], v[202:205], v[12:15]
	v_mfma_f32_16x16x32_bf16 v[60:63], v[164:167], v[180:183], v[60:63]
	v_mfma_f32_16x16x32_bf16 v[56:59], v[172:175], v[180:183], v[56:59]
	v_mfma_f32_16x16x32_bf16 v[40:43], v[172:175], v[188:191], v[40:43]
	v_mfma_f32_16x16x32_bf16 v[44:47], v[164:167], v[188:191], v[44:47]
	v_mfma_f32_16x16x32_bf16 v[28:31], v[164:167], v[198:201], v[28:31]
	v_mfma_f32_16x16x32_bf16 v[24:27], v[172:175], v[198:201], v[24:27]
	v_mfma_f32_16x16x32_bf16 v[8:11], v[172:175], v[206:209], v[8:11]
	v_mfma_f32_16x16x32_bf16 v[12:15], v[164:167], v[206:209], v[12:15]
	s_barrier
	s_add_i32 s16, s50, s18
	v_lshl_add_u64 v[144:145], v[232:233], 0, s[46:47]
	s_mov_b32 m0, s16
	s_nop 0
	global_load_lds_dwordx4 v[144:145], off
	v_lshl_add_u64 v[144:145], v[234:235], 0, s[46:47]
	s_add_i32 m0, s16, 0x2000
	s_nop 0
	global_load_lds_dwordx4 v[144:145], off
	s_waitcnt vmcnt(6)
	s_barrier
	v_mfma_f32_16x16x32_bf16 v[52:55], v[210:213], v[176:179], v[52:55]
	v_mfma_f32_16x16x32_bf16 v[48:51], v[218:221], v[176:179], v[48:51]
	v_mfma_f32_16x16x32_bf16 v[32:35], v[218:221], v[184:187], v[32:35]
	v_mfma_f32_16x16x32_bf16 v[36:39], v[210:213], v[184:187], v[36:39]
	v_mfma_f32_16x16x32_bf16 v[20:23], v[210:213], v[192:195], v[20:23]
	v_mfma_f32_16x16x32_bf16 v[16:19], v[218:221], v[192:195], v[16:19]
	v_mfma_f32_16x16x32_bf16 v[0:3], v[218:221], v[202:205], v[0:3]
	v_mfma_f32_16x16x32_bf16 v[4:7], v[210:213], v[202:205], v[4:7]
	v_mfma_f32_16x16x32_bf16 v[52:55], v[214:217], v[180:183], v[52:55]
	v_mfma_f32_16x16x32_bf16 v[48:51], v[222:225], v[180:183], v[48:51]
	v_mfma_f32_16x16x32_bf16 v[32:35], v[222:225], v[188:191], v[32:35]
	v_mfma_f32_16x16x32_bf16 v[36:39], v[214:217], v[188:191], v[36:39]
	v_mfma_f32_16x16x32_bf16 v[20:23], v[214:217], v[198:201], v[20:23]
	v_mfma_f32_16x16x32_bf16 v[16:19], v[222:225], v[198:201], v[16:19]
	v_mfma_f32_16x16x32_bf16 v[0:3], v[222:225], v[206:209], v[0:3]
	v_mfma_f32_16x16x32_bf16 v[4:7], v[214:217], v[206:209], v[4:7]
	s_add_u32 s14, s14, 0x100
	s_addc_u32 s15, s15, 0
	s_add_u32 s64, s64, 0x100
	s_addc_u32 s65, s65, 0
	s_cmp_ge_i32 s77, s25
	s_mov_b32 s16, s77
	s_barrier
	s_cbranch_scc0 .LBB0_744
	v_readlane_b32 s78, v240, 54
	v_readlane_b32 s79, v240, 55

; #define PG8_STAGE(bufoff, gbase, voff) do { _Pragma("unroll") for (int _i = 0; _i < 2; ++_i) \
;         __builtin_amdgcn_global_load_lds((const unsigned*)((const char*)(gbase) + (voff)[_i]), (LAS unsigned*)(lds + (bufoff) + ldsw + _i * 8192), 16, 0, 0); } while (0)
; #define PG8_LDA(dst, b, h) do { _Pragma("unroll") for (int m = 0; m < 4; ++m) _Pragma("unroll") for (int k = 0; k < 2; ++k) dst[m][k] = *(const LAS bf16x8*)(lds + PG8_SA(b, h) + aoff + m * 2048 + k * 1024); } while (0)
; #define PG8_LDB(dst, b, h) do { _Pragma("unroll") for (int n = 0; n < 2; ++n) _Pragma("unroll") for (int k = 0; k < 2; ++k) dst[n][k] = *(const LAS bf16x8*)(lds + PG8_SB(b, h) + boff + n * 2048 + k * 1024); } while (0)
; #define PG8_MMA(ai, bj, At, Bt) do { __builtin_amdgcn_s_setprio(1); _Pragma("unroll") for (int m = 0; m < 4; ++m) _Pragma("unroll") for (int n = 0; n < 2; ++n) _Pragma("unroll") for (int k = 0; k < 2; ++k) \
;         acc[ai][bj][m][n] = __builtin_amdgcn_mfma_f32_16x16x32_bf16(Bt[n][k], At[m][k], acc[ai][bj][m][n], 0, 0, 0); __builtin_amdgcn_s_setprio(0); } while (0)
; #define PG8_WAIT_L(n) asm volatile("s_waitcnt lgkmcnt(" #n ")" ::: "memory")
; #define PG8_BAR __builtin_amdgcn_s_barrier()
; #define PG8_SCHED __builtin_amdgcn_sched_barrier(0)
; template <class Epi>
; DEVI void gemm_phase(LAS unsigned char* lds, const bf16_t* gA, const bf16_t* gBt, const int lda, const int ldb, const int K, const StaticOrder S_, const Epi E) {
;     ...
;             PG8_LDB(B0, 0, 0); PG8_SCHED; PG8_LDA(At, 0, 0); PG8_STAGE(PG8_SA(1, 1), a1 + hstepA, voffA);
;             PG8_WAIT_L(8); PG8_BAR; PG8_WAIT_L(0); PG8_MMA(0, 0, At, B0); PG8_BAR; PG8_SCHED;
;             PG8_LDB(B1, 0, 1); PG8_STAGE(PG8_SB(0, 0), b2, voffB);
;             PG8_BAR; PG8_WAIT_L(0); PG8_MMA(0, 1, At, B1); PG8_BAR;
;             PG8_LDA(At, 0, 1); PG8_STAGE(PG8_SA(0, 0), a2, voffA);
;             PG8_BAR; PG8_WAIT_L(0); PG8_MMA(1, 0, At, B0); PG8_BAR; PG8_SCHED;
.LBB0_800:
	ds_read_b128 v[160:163], v153
	ds_read_b128 v[164:167], v153 offset:1024
	ds_read_b128 v[168:171], v153 offset:2048
	ds_read_b128 v[172:175], v153 offset:3072
	s_add_i32 s76, s16, 2
	s_add_u32 s40, s14, 0x80
	s_addc_u32 s17, s15, 0
	s_cmp_eq_u32 s26, s16
	s_cselect_b32 s16, s48, s40
	s_cselect_b32 s17, s49, s17
	s_cselect_b32 s41, s61, s65
	s_cselect_b32 s40, s60, s64
	v_lshl_add_u64 v[144:145], s[14:15], 0, v[138:139]
	s_add_i32 m0, s19, 0xc000
	ds_read_b128 v[176:179], v154
	ds_read_b128 v[180:183], v154 offset:1024
	ds_read_b128 v[184:187], v154 offset:2048
	ds_read_b128 v[188:191], v154 offset:3072
	ds_read_b128 v[192:195], v154 offset:4096
	ds_read_b128 v[198:201], v154 offset:5120
	ds_read_b128 v[202:205], v154 offset:6144
	ds_read_b128 v[206:209], v154 offset:7168
	global_load_lds_dwordx4 v[144:145], off
	v_lshl_add_u64 v[144:145], s[14:15], 0, v[140:141]
	s_add_i32 m0, s19, 0xe000
	s_nop 0
	global_load_lds_dwordx4 v[144:145], off
	s_waitcnt lgkmcnt(8)
	s_barrier
	s_waitcnt lgkmcnt(0)
	s_waitcnt lgkmcnt(0)
	v_mfma_f32_16x16x32_bf16 v[124:127], v[160:163], v[176:179], v[124:127]
	v_mfma_f32_16x16x32_bf16 v[120:123], v[168:171], v[176:179], v[120:123]
	v_mfma_f32_16x16x32_bf16 v[104:107], v[168:171], v[184:187], v[104:107]
	v_mfma_f32_16x16x32_bf16 v[108:111], v[160:163], v[184:187], v[108:111]
	v_mfma_f32_16x16x32_bf16 v[92:95], v[160:163], v[192:195], v[92:95]
	v_mfma_f32_16x16x32_bf16 v[88:91], v[168:171], v[192:195], v[88:91]
	v_mfma_f32_16x16x32_bf16 v[72:75], v[168:171], v[202:205], v[72:75]
	v_mfma_f32_16x16x32_bf16 v[76:79], v[160:163], v[202:205], v[76:79]
	v_mfma_f32_16x16x32_bf16 v[124:127], v[164:167], v[180:183], v[124:127]
	v_mfma_f32_16x16x32_bf16 v[120:123], v[172:175], v[180:183], v[120:123]
	v_mfma_f32_16x16x32_bf16 v[104:107], v[172:175], v[188:191], v[104:107]
	v_mfma_f32_16x16x32_bf16 v[108:111], v[164:167], v[188:191], v[108:111]
	v_mfma_f32_16x16x32_bf16 v[92:95], v[164:167], v[198:201], v[92:95]
	v_mfma_f32_16x16x32_bf16 v[88:91], v[172:175], v[198:201], v[88:91]
	v_mfma_f32_16x16x32_bf16 v[72:75], v[172:175], v[206:209], v[72:75]
	v_mfma_f32_16x16x32_bf16 v[76:79], v[164:167], v[206:209], v[76:79]
	s_barrier
	s_add_i32 s77, s31, s18
	v_lshl_add_u64 v[144:145], s[40:41], 0, v[130:131]
	s_mov_b32 m0, s77
	ds_read_b128 v[210:213], v155
	ds_read_b128 v[214:217], v155 offset:1024
	ds_read_b128 v[218:221], v155 offset:2048
	ds_read_b128 v[222:225], v155 offset:3072
	global_load_lds_dwordx4 v[144:145], off
	v_lshl_add_u64 v[226:227], s[40:41], 0, v[134:135]
	s_add_i32 m0, s77, 0x2000
	s_nop 0
	global_load_lds_dwordx4 v[226:227], off
	s_barrier
	s_waitcnt lgkmcnt(0)
	s_waitcnt lgkmcnt(0)
	v_mfma_f32_16x16x32_bf16 v[116:119], v[210:213], v[176:179], v[116:119]
	v_mfma_f32_16x16x32_bf16 v[112:115], v[218:221], v[176:179], v[112:115]
	v_mfma_f32_16x16x32_bf16 v[96:99], v[218:221], v[184:187], v[96:99]
	v_mfma_f32_16x16x32_bf16 v[100:103], v[210:213], v[184:187], v[100:103]
	v_mfma_f32_16x16x32_bf16 v[84:87], v[210:213], v[192:195], v[84:87]
	v_mfma_f32_16x16x32_bf16 v[80:83], v[218:221], v[192:195], v[80:83]
	v_mfma_f32_16x16x32_bf16 v[64:67], v[218:221], v[202:205], v[64:67]
	v_mfma_f32_16x16x32_bf16 v[68:71], v[210:213], v[202:205], v[68:71]
	v_mfma_f32_16x16x32_bf16 v[116:119], v[214:217], v[180:183], v[116:119]
	v_mfma_f32_16x16x32_bf16 v[112:115], v[222:225], v[180:183], v[112:115]
	v_mfma_f32_16x16x32_bf16 v[96:99], v[222:225], v[188:191], v[96:99]
	v_mfma_f32_16x16x32_bf16 v[100:103], v[214:217], v[188:191], v[100:103]
	v_mfma_f32_16x16x32_bf16 v[84:87], v[214:217], v[198:201], v[84:87]
	v_mfma_f32_16x16x32_bf16 v[80:83], v[222:225], v[198:201], v[80:83]
	v_mfma_f32_16x16x32_bf16 v[64:67], v[222:225], v[206:209], v[64:67]
	v_mfma_f32_16x16x32_bf16 v[68:71], v[214:217], v[206:209], v[68:71]
	s_mov_b32 m0, s19
	v_lshl_add_u64 v[228:229], s[16:17], 0, v[128:129]
	s_barrier
	ds_read_b128 v[176:179], v154 offset:16384
	ds_read_b128 v[180:183], v154 offset:17408
	ds_read_b128 v[184:187], v154 offset:18432
	ds_read_b128 v[188:191], v154 offset:19456
	ds_read_b128 v[192:195], v154 offset:20480
	ds_read_b128 v[198:201], v154 offset:21504
	ds_read_b128 v[202:205], v154 offset:22528
	ds_read_b128 v[206:209], v154 offset:23552
	global_load_lds_dwordx4 v[228:229], off
	v_lshl_add_u64 v[230:231], s[16:17], 0, v[132:133]
	s_mov_b32 m0, s20
	s_nop 0
	global_load_lds_dwordx4 v[230:231], off
	s_barrier
	s_waitcnt lgkmcnt(0)
	s_waitcnt lgkmcnt(0)
	v_mfma_f32_16x16x32_bf16 v[60:63], v[160:163], v[176:179], v[60:63]
	v_mfma_f32_16x16x32_bf16 v[56:59], v[168:171], v[176:179], v[56:59]
	v_mfma_f32_16x16x32_bf16 v[40:43], v[168:171], v[184:187], v[40:43]
	v_mfma_f32_16x16x32_bf16 v[44:47], v[160:163], v[184:187], v[44:47]
	v_mfma_f32_16x16x32_bf16 v[28:31], v[160:163], v[192:195], v[28:31]
	v_mfma_f32_16x16x32_bf16 v[24:27], v[168:171], v[192:195], v[24:27]
	v_mfma_f32_16x16x32_bf16 v[8:11], v[168:171], v[202:205], v[8:11]
	v_mfma_f32_16x16x32_bf16 v[12:15], v[160:163], v[202:205], v[12:15]
	v_mfma_f32_16x16x32_bf16 v[60:63], v[164:167], v[180:183], v[60:63]
	v_mfma_f32_16x16x32_bf16 v[56:59], v[172:175], v[180:183], v[56:59]
	v_mfma_f32_16x16x32_bf16 v[40:43], v[172:175], v[188:191], v[40:43]
	v_mfma_f32_16x16x32_bf16 v[44:47], v[164:167], v[188:191], v[44:47]
	v_mfma_f32_16x16x32_bf16 v[28:31], v[164:167], v[198:201], v[28:31]
	v_mfma_f32_16x16x32_bf16 v[24:27], v[172:175], v[198:201], v[24:27]
	v_mfma_f32_16x16x32_bf16 v[8:11], v[172:175], v[206:209], v[8:11]
	v_mfma_f32_16x16x32_bf16 v[12:15], v[164:167], v[206:209], v[12:15]
	s_barrier
; #define PG8_STAGE(bufoff, gbase, voff) do { _Pragma("unroll") for (int _i = 0; _i < 2; ++_i) \
;         __builtin_amdgcn_global_load_lds((const unsigned*)((const char*)(gbase) + (voff)[_i]), (LAS unsigned*)(lds + (bufoff) + ldsw + _i * 8192), 16, 0, 0); } while (0)
; #define PG8_LDA(dst, b, h) do { _Pragma("unroll") for (int m = 0; m < 4; ++m) _Pragma("unroll") for (int k = 0; k < 2; ++k) dst[m][k] = *(const LAS bf16x8*)(lds + PG8_SA(b, h) + aoff + m * 2048 + k * 1024); } while (0)
; #define PG8_LDB(dst, b, h) do { _Pragma("unroll") for (int n = 0; n < 2; ++n) _Pragma("unroll") for (int k = 0; k < 2; ++k) dst[n][k] = *(const LAS bf16x8*)(lds + PG8_SB(b, h) + boff + n * 2048 + k * 1024); } while (0)
; #define PG8_MMA(ai, bj, At, Bt) do { __builtin_amdgcn_s_setprio(1); _Pragma("unroll") for (int m = 0; m < 4; ++m) _Pragma("unroll") for (int n = 0; n < 2; ++n) _Pragma("unroll") for (int k = 0; k < 2; ++k) \
;         acc[ai][bj][m][n] = __builtin_amdgcn_mfma_f32_16x16x32_bf16(Bt[n][k], At[m][k], acc[ai][bj][m][n], 0, 0, 0); __builtin_amdgcn_s_setprio(0); } while (0)
; #define PG8_WAIT_V(n) asm volatile("s_waitcnt vmcnt(" #n ")" ::: "memory")
; #define PG8_WAIT_L(n) asm volatile("s_waitcnt lgkmcnt(" #n ")" ::: "memory")
; #define PG8_BAR __builtin_amdgcn_s_barrier()
; #define PG8_SCHED __builtin_amdgcn_sched_barrier(0)
; template <class Epi>
; DEVI void gemm_phase(LAS unsigned char* lds, const bf16_t* gA, const bf16_t* gBt, const int lda, const int ldb, const int K, const StaticOrder S_, const Epi E) {
;     ...
;             PG8_STAGE(PG8_SB(0, 1), b2 + hstepB, voffB);
;             PG8_WAIT_V(6); PG8_BAR; PG8_MMA(1, 1, At, B1); PG8_BAR;
;             PG8_LDB(B0, 1, 0); PG8_SCHED; PG8_LDA(At, 1, 0); PG8_STAGE(PG8_SA(0, 1), a2 + hstepA, voffA);
;             PG8_WAIT_L(8); PG8_BAR; PG8_WAIT_L(0); PG8_MMA(0, 0, At, B0); PG8_BAR; PG8_SCHED;
;             PG8_LDB(B1, 1, 1); PG8_STAGE(PG8_SB(1, 0), b3, voffB);
	s_add_u32 s40, s40, s2
	s_addc_u32 s41, s41, s3
	s_add_i32 s77, s34, s18
	v_lshl_add_u64 v[232:233], s[40:41], 0, v[130:131]
	s_mov_b32 m0, s77
	v_lshl_add_u64 v[234:235], s[40:41], 0, v[134:135]
	global_load_lds_dwordx4 v[232:233], off
	s_add_i32 m0, s77, 0x2000
	s_nop 0
	global_load_lds_dwordx4 v[234:235], off
	s_waitcnt vmcnt(6)
	s_barrier
	v_mfma_f32_16x16x32_bf16 v[52:55], v[210:213], v[176:179], v[52:55]
	v_mfma_f32_16x16x32_bf16 v[48:51], v[218:221], v[176:179], v[48:51]
	v_mfma_f32_16x16x32_bf16 v[32:35], v[218:221], v[184:187], v[32:35]
	v_mfma_f32_16x16x32_bf16 v[36:39], v[210:213], v[184:187], v[36:39]
	v_mfma_f32_16x16x32_bf16 v[20:23], v[210:213], v[192:195], v[20:23]
	v_mfma_f32_16x16x32_bf16 v[16:19], v[218:221], v[192:195], v[16:19]
	v_mfma_f32_16x16x32_bf16 v[0:3], v[218:221], v[202:205], v[0:3]
	v_mfma_f32_16x16x32_bf16 v[4:7], v[210:213], v[202:205], v[4:7]
	v_mfma_f32_16x16x32_bf16 v[52:55], v[214:217], v[180:183], v[52:55]
	v_mfma_f32_16x16x32_bf16 v[48:51], v[222:225], v[180:183], v[48:51]
	v_mfma_f32_16x16x32_bf16 v[32:35], v[222:225], v[188:191], v[32:35]
	v_mfma_f32_16x16x32_bf16 v[36:39], v[214:217], v[188:191], v[36:39]
	v_mfma_f32_16x16x32_bf16 v[20:23], v[214:217], v[198:201], v[20:23]
	v_mfma_f32_16x16x32_bf16 v[16:19], v[222:225], v[198:201], v[16:19]
	v_mfma_f32_16x16x32_bf16 v[0:3], v[222:225], v[206:209], v[0:3]
	v_mfma_f32_16x16x32_bf16 v[4:7], v[214:217], v[206:209], v[4:7]
	s_barrier
	ds_read_b128 v[160:163], v156
	ds_read_b128 v[164:167], v156 offset:1024
	ds_read_b128 v[168:171], v156 offset:2048
	ds_read_b128 v[172:175], v156 offset:3072
	s_add_u32 s16, s16, s0
	s_addc_u32 s17, s17, s1
	s_mov_b32 m0, s21
	v_lshl_add_u64 v[210:211], s[16:17], 0, v[128:129]
	ds_read_b128 v[176:179], v154 offset:32768
	ds_read_b128 v[180:183], v154 offset:33792
	ds_read_b128 v[184:187], v154 offset:34816
	ds_read_b128 v[188:191], v154 offset:35840
	ds_read_b128 v[192:195], v154 offset:36864
	ds_read_b128 v[198:201], v154 offset:37888
	ds_read_b128 v[202:205], v154 offset:38912
	ds_read_b128 v[206:209], v154 offset:39936
	global_load_lds_dwordx4 v[210:211], off
	v_lshl_add_u64 v[210:211], s[16:17], 0, v[132:133]
	s_mov_b32 m0, s22
	s_nop 0
	global_load_lds_dwordx4 v[210:211], off
	s_waitcnt lgkmcnt(8)
	s_barrier
	s_waitcnt lgkmcnt(0)
	s_waitcnt lgkmcnt(0)
	v_mfma_f32_16x16x32_bf16 v[124:127], v[160:163], v[176:179], v[124:127]
	v_mfma_f32_16x16x32_bf16 v[120:123], v[168:171], v[176:179], v[120:123]
	v_mfma_f32_16x16x32_bf16 v[104:107], v[168:171], v[184:187], v[104:107]
	v_mfma_f32_16x16x32_bf16 v[108:111], v[160:163], v[184:187], v[108:111]
	v_mfma_f32_16x16x32_bf16 v[92:95], v[160:163], v[192:195], v[92:95]
	v_mfma_f32_16x16x32_bf16 v[88:91], v[168:171], v[192:195], v[88:91]
	v_mfma_f32_16x16x32_bf16 v[72:75], v[168:171], v[202:205], v[72:75]
	v_mfma_f32_16x16x32_bf16 v[76:79], v[160:163], v[202:205], v[76:79]
	v_mfma_f32_16x16x32_bf16 v[124:127], v[164:167], v[180:183], v[124:127]
	v_mfma_f32_16x16x32_bf16 v[120:123], v[172:175], v[180:183], v[120:123]
	v_mfma_f32_16x16x32_bf16 v[104:107], v[172:175], v[188:191], v[104:107]
	v_mfma_f32_16x16x32_bf16 v[108:111], v[164:167], v[188:191], v[108:111]
	v_mfma_f32_16x16x32_bf16 v[92:95], v[164:167], v[198:201], v[92:95]
	v_mfma_f32_16x16x32_bf16 v[88:91], v[172:175], v[198:201], v[88:91]
	v_mfma_f32_16x16x32_bf16 v[72:75], v[172:175], v[206:209], v[72:75]
	v_mfma_f32_16x16x32_bf16 v[76:79], v[164:167], v[206:209], v[76:79]
	s_barrier
	s_add_i32 s16, s35, s18
	v_lshl_add_u64 v[144:145], v[144:145], 0, s[46:47]
	s_mov_b32 m0, s16
	ds_read_b128 v[210:213], v157
	ds_read_b128 v[214:217], v157 offset:1024
	ds_read_b128 v[218:221], v157 offset:2048
	ds_read_b128 v[222:225], v157 offset:3072
	global_load_lds_dwordx4 v[144:145], off
	v_lshl_add_u64 v[144:145], v[226:227], 0, s[46:47]
	s_add_i32 m0, s16, 0x2000
	s_nop 0
	global_load_lds_dwordx4 v[144:145], off
	s_barrier
; #define PG8_STAGE(bufoff, gbase, voff) do { _Pragma("unroll") for (int _i = 0; _i < 2; ++_i) \
;         __builtin_amdgcn_global_load_lds((const unsigned*)((const char*)(gbase) + (voff)[_i]), (LAS unsigned*)(lds + (bufoff) + ldsw + _i * 8192), 16, 0, 0); } while (0)
; #define PG8_LDA(dst, b, h) do { _Pragma("unroll") for (int m = 0; m < 4; ++m) _Pragma("unroll") for (int k = 0; k < 2; ++k) dst[m][k] = *(const LAS bf16x8*)(lds + PG8_SA(b, h) + aoff + m * 2048 + k * 1024); } while (0)
; #define PG8_MMA(ai, bj, At, Bt) do { __builtin_amdgcn_s_setprio(1); _Pragma("unroll") for (int m = 0; m < 4; ++m) _Pragma("unroll") for (int n = 0; n < 2; ++n) _Pragma("unroll") for (int k = 0; k < 2; ++k) \
;         acc[ai][bj][m][n] = __builtin_amdgcn_mfma_f32_16x16x32_bf16(Bt[n][k], At[m][k], acc[ai][bj][m][n], 0, 0, 0); __builtin_amdgcn_s_setprio(0); } while (0)
; #define PG8_WAIT_V(n) asm volatile("s_waitcnt vmcnt(" #n ")" ::: "memory")
; #define PG8_WAIT_L(n) asm volatile("s_waitcnt lgkmcnt(" #n ")" ::: "memory")
; #define PG8_BAR __builtin_amdgcn_s_barrier()
; #define PG8_SCHED __builtin_amdgcn_sched_barrier(0)
; template <class Epi>
; DEVI void gemm_phase(LAS unsigned char* lds, const bf16_t* gA, const bf16_t* gBt, const int lda, const int ldb, const int K, const StaticOrder S_, const Epi E) {
;     ...
;             PG8_BAR; PG8_WAIT_L(0); PG8_MMA(0, 1, At, B1); PG8_BAR;
;             PG8_LDA(At, 1, 1); PG8_STAGE(PG8_SA(1, 0), a3, voffA);
;             PG8_BAR; PG8_WAIT_L(0); PG8_MMA(1, 0, At, B0); PG8_BAR; PG8_SCHED;
;             PG8_STAGE(PG8_SB(1, 1), b3 + hstepB, voffB);
;             PG8_WAIT_V(6); PG8_BAR; PG8_MMA(1, 1, At, B1); PG8_BAR;
	s_waitcnt lgkmcnt(0)
	s_waitcnt lgkmcnt(0)
	v_mfma_f32_16x16x32_bf16 v[116:119], v[210:213], v[176:179], v[116:119]
	v_mfma_f32_16x16x32_bf16 v[112:115], v[218:221], v[176:179], v[112:115]
	v_mfma_f32_16x16x32_bf16 v[96:99], v[218:221], v[184:187], v[96:99]
	v_mfma_f32_16x16x32_bf16 v[100:103], v[210:213], v[184:187], v[100:103]
	v_mfma_f32_16x16x32_bf16 v[84:87], v[210:213], v[192:195], v[84:87]
	v_mfma_f32_16x16x32_bf16 v[80:83], v[218:221], v[192:195], v[80:83]
	v_mfma_f32_16x16x32_bf16 v[64:67], v[218:221], v[202:205], v[64:67]
	v_mfma_f32_16x16x32_bf16 v[68:71], v[210:213], v[202:205], v[68:71]
	v_mfma_f32_16x16x32_bf16 v[116:119], v[214:217], v[180:183], v[116:119]
	v_mfma_f32_16x16x32_bf16 v[112:115], v[222:225], v[180:183], v[112:115]
	v_mfma_f32_16x16x32_bf16 v[96:99], v[222:225], v[188:191], v[96:99]
	v_mfma_f32_16x16x32_bf16 v[100:103], v[214:217], v[188:191], v[100:103]
	v_mfma_f32_16x16x32_bf16 v[84:87], v[214:217], v[198:201], v[84:87]
	v_mfma_f32_16x16x32_bf16 v[80:83], v[222:225], v[198:201], v[80:83]
	v_mfma_f32_16x16x32_bf16 v[64:67], v[222:225], v[206:209], v[64:67]
	v_mfma_f32_16x16x32_bf16 v[68:71], v[214:217], v[206:209], v[68:71]
	s_mov_b32 m0, s23
	v_lshl_add_u64 v[144:145], v[228:229], 0, s[46:47]
	s_barrier
	ds_read_b128 v[176:179], v154 offset:49152
	ds_read_b128 v[180:183], v154 offset:50176
	ds_read_b128 v[184:187], v154 offset:51200
	ds_read_b128 v[188:191], v154 offset:52224
	ds_read_b128 v[192:195], v154 offset:53248
	ds_read_b128 v[198:201], v154 offset:54272
	ds_read_b128 v[202:205], v154 offset:55296
	ds_read_b128 v[206:209], v154 offset:56320
	global_load_lds_dwordx4 v[144:145], off
	v_lshl_add_u64 v[144:145], v[230:231], 0, s[46:47]
	s_mov_b32 m0, s24
	s_nop 0
	global_load_lds_dwordx4 v[144:145], off
	s_barrier
	s_waitcnt lgkmcnt(0)
	s_waitcnt lgkmcnt(0)
	v_mfma_f32_16x16x32_bf16 v[60:63], v[160:163], v[176:179], v[60:63]
	v_mfma_f32_16x16x32_bf16 v[56:59], v[168:171], v[176:179], v[56:59]
	v_mfma_f32_16x16x32_bf16 v[40:43], v[168:171], v[184:187], v[40:43]
	v_mfma_f32_16x16x32_bf16 v[44:47], v[160:163], v[184:187], v[44:47]
	v_mfma_f32_16x16x32_bf16 v[28:31], v[160:163], v[192:195], v[28:31]
	v_mfma_f32_16x16x32_bf16 v[24:27], v[168:171], v[192:195], v[24:27]
	v_mfma_f32_16x16x32_bf16 v[8:11], v[168:171], v[202:205], v[8:11]
	v_mfma_f32_16x16x32_bf16 v[12:15], v[160:163], v[202:205], v[12:15]
	v_mfma_f32_16x16x32_bf16 v[60:63], v[164:167], v[180:183], v[60:63]
	v_mfma_f32_16x16x32_bf16 v[56:59], v[172:175], v[180:183], v[56:59]
	v_mfma_f32_16x16x32_bf16 v[40:43], v[172:175], v[188:191], v[40:43]
	v_mfma_f32_16x16x32_bf16 v[44:47], v[164:167], v[188:191], v[44:47]
	v_mfma_f32_16x16x32_bf16 v[28:31], v[164:167], v[198:201], v[28:31]
	v_mfma_f32_16x16x32_bf16 v[24:27], v[172:175], v[198:201], v[24:27]
	v_mfma_f32_16x16x32_bf16 v[8:11], v[172:175], v[206:209], v[8:11]
	v_mfma_f32_16x16x32_bf16 v[12:15], v[164:167], v[206:209], v[12:15]
	s_barrier
	s_add_i32 s16, s50, s18
	v_lshl_add_u64 v[144:145], v[232:233], 0, s[46:47]
	s_mov_b32 m0, s16
	s_nop 0
	global_load_lds_dwordx4 v[144:145], off
	v_lshl_add_u64 v[144:145], v[234:235], 0, s[46:47]
	s_add_i32 m0, s16, 0x2000
	s_nop 0
	global_load_lds_dwordx4 v[144:145], off
	s_waitcnt vmcnt(6)
	s_barrier
	v_mfma_f32_16x16x32_bf16 v[52:55], v[210:213], v[176:179], v[52:55]
	v_mfma_f32_16x16x32_bf16 v[48:51], v[218:221], v[176:179], v[48:51]
	v_mfma_f32_16x16x32_bf16 v[32:35], v[218:221], v[184:187], v[32:35]
	v_mfma_f32_16x16x32_bf16 v[36:39], v[210:213], v[184:187], v[36:39]
	v_mfma_f32_16x16x32_bf16 v[20:23], v[210:213], v[192:195], v[20:23]
	v_mfma_f32_16x16x32_bf16 v[16:19], v[218:221], v[192:195], v[16:19]
	v_mfma_f32_16x16x32_bf16 v[0:3], v[218:221], v[202:205], v[0:3]
	v_mfma_f32_16x16x32_bf16 v[4:7], v[210:213], v[202:205], v[4:7]
	v_mfma_f32_16x16x32_bf16 v[52:55], v[214:217], v[180:183], v[52:55]
	v_mfma_f32_16x16x32_bf16 v[48:51], v[222:225], v[180:183], v[48:51]
	v_mfma_f32_16x16x32_bf16 v[32:35], v[222:225], v[188:191], v[32:35]
	v_mfma_f32_16x16x32_bf16 v[36:39], v[214:217], v[188:191], v[36:39]
	v_mfma_f32_16x16x32_bf16 v[20:23], v[214:217], v[198:201], v[20:23]
	v_mfma_f32_16x16x32_bf16 v[16:19], v[222:225], v[198:201], v[16:19]
	v_mfma_f32_16x16x32_bf16 v[0:3], v[222:225], v[206:209], v[0:3]
	v_mfma_f32_16x16x32_bf16 v[4:7], v[214:217], v[206:209], v[4:7]
	s_add_u32 s14, s14, 0x100
	s_addc_u32 s15, s15, 0
	s_add_u32 s64, s64, 0x100
	s_addc_u32 s65, s65, 0
	s_cmp_ge_i32 s76, s25
	s_mov_b32 s16, s76
	s_barrier
	s_cbranch_scc0 .LBB0_800

; #define PG8_STAGE(bufoff, gbase, voff) do { _Pragma("unroll") for (int _i = 0; _i < 2; ++_i) \
;         __builtin_amdgcn_global_load_lds((const unsigned*)((const char*)(gbase) + (voff)[_i]), (LAS unsigned*)(lds + (bufoff) + ldsw + _i * 8192), 16, 0, 0); } while (0)
; #define PG8_LDA(dst, b, h) do { _Pragma("unroll") for (int m = 0; m < 4; ++m) _Pragma("unroll") for (int k = 0; k < 2; ++k) dst[m][k] = *(const LAS bf16x8*)(lds + PG8_SA(b, h) + aoff + m * 2048 + k * 1024); } while (0)
; #define PG8_LDB(dst, b, h) do { _Pragma("unroll") for (int n = 0; n < 2; ++n) _Pragma("unroll") for (int k = 0; k < 2; ++k) dst[n][k] = *(const LAS bf16x8*)(lds + PG8_SB(b, h) + boff + n * 2048 + k * 1024); } while (0)
; #define PG8_MMA(ai, bj, At, Bt) do { __builtin_amdgcn_s_setprio(1); _Pragma("unroll") for (int m = 0; m < 4; ++m) _Pragma("unroll") for (int n = 0; n < 2; ++n) _Pragma("unroll") for (int k = 0; k < 2; ++k) \
;         acc[ai][bj][m][n] = __builtin_amdgcn_mfma_f32_16x16x32_bf16(Bt[n][k], At[m][k], acc[ai][bj][m][n], 0, 0, 0); __builtin_amdgcn_s_setprio(0); } while (0)
; #define PG8_WAIT_L(n) asm volatile("s_waitcnt lgkmcnt(" #n ")" ::: "memory")
; #define PG8_BAR __builtin_amdgcn_s_barrier()
; #define PG8_SCHED __builtin_amdgcn_sched_barrier(0)
; template <class Epi>
; DEVI void gemm_phase(LAS unsigned char* lds, const bf16_t* gA, const bf16_t* gBt, const int lda, const int ldb, const int K, const StaticOrder S_, const Epi E) {
;     ...
;             PG8_LDB(B0, 0, 0); PG8_SCHED; PG8_LDA(At, 0, 0); PG8_STAGE(PG8_SA(1, 1), a1 + hstepA, voffA);
;             PG8_WAIT_L(8); PG8_BAR; PG8_WAIT_L(0); PG8_MMA(0, 0, At, B0); PG8_BAR; PG8_SCHED;
;             PG8_LDB(B1, 0, 1); PG8_STAGE(PG8_SB(0, 0), b2, voffB);
;             PG8_BAR; PG8_WAIT_L(0); PG8_MMA(0, 1, At, B1); PG8_BAR;
;             PG8_LDA(At, 0, 1); PG8_STAGE(PG8_SA(0, 0), a2, voffA);
;             PG8_BAR; PG8_WAIT_L(0); PG8_MMA(1, 0, At, B0); PG8_BAR; PG8_SCHED;
.LBB0_1301:
	ds_read_b128 v[128:131], v201
	ds_read_b128 v[132:135], v201 offset:1024
	ds_read_b128 v[136:139], v201 offset:2048
	ds_read_b128 v[140:143], v201 offset:3072
	s_add_i32 s72, s16, 2
	s_add_u32 s40, s14, 0x80
	s_addc_u32 s17, s15, 0
	s_cmp_eq_u32 s19, s16
	s_cselect_b32 s16, s12, s40
	s_cselect_b32 s17, s13, s17
	s_cselect_b32 s41, s43, s71
	s_cselect_b32 s40, s42, s70
	v_lshl_add_u64 v[164:165], s[14:15], 0, v[174:175]
	s_add_i32 m0, s82, 0xc000
	ds_read_b128 v[144:147], v202
	ds_read_b128 v[148:151], v202 offset:1024
	ds_read_b128 v[152:155], v202 offset:2048
	ds_read_b128 v[156:159], v202 offset:3072
	ds_read_b128 v[160:163], v202 offset:4096
	ds_read_b128 v[180:183], v202 offset:5120
	ds_read_b128 v[184:187], v202 offset:6144
	ds_read_b128 v[188:191], v202 offset:7168
	global_load_lds_dwordx4 v[164:165], off
	v_lshl_add_u64 v[164:165], s[14:15], 0, v[176:177]
	s_add_i32 m0, s82, 0xe000
	s_nop 0
	global_load_lds_dwordx4 v[164:165], off
	s_waitcnt lgkmcnt(8)
	s_barrier
	s_waitcnt lgkmcnt(0)
	s_waitcnt lgkmcnt(0)
	v_mfma_f32_16x16x32_bf16 v[124:127], v[128:131], v[144:147], v[124:127]
	v_mfma_f32_16x16x32_bf16 v[120:123], v[136:139], v[144:147], v[120:123]
	v_mfma_f32_16x16x32_bf16 v[104:107], v[136:139], v[152:155], v[104:107]
	v_mfma_f32_16x16x32_bf16 v[108:111], v[128:131], v[152:155], v[108:111]
	v_mfma_f32_16x16x32_bf16 v[92:95], v[128:131], v[160:163], v[92:95]
	v_mfma_f32_16x16x32_bf16 v[88:91], v[136:139], v[160:163], v[88:91]
	v_mfma_f32_16x16x32_bf16 v[72:75], v[136:139], v[184:187], v[72:75]
	v_mfma_f32_16x16x32_bf16 v[76:79], v[128:131], v[184:187], v[76:79]
	v_mfma_f32_16x16x32_bf16 v[124:127], v[132:135], v[148:151], v[124:127]
	v_mfma_f32_16x16x32_bf16 v[120:123], v[140:143], v[148:151], v[120:123]
	v_mfma_f32_16x16x32_bf16 v[104:107], v[140:143], v[156:159], v[104:107]
	v_mfma_f32_16x16x32_bf16 v[108:111], v[132:135], v[156:159], v[108:111]
	v_mfma_f32_16x16x32_bf16 v[92:95], v[132:135], v[180:183], v[92:95]
	v_mfma_f32_16x16x32_bf16 v[88:91], v[140:143], v[180:183], v[88:91]
	v_mfma_f32_16x16x32_bf16 v[72:75], v[140:143], v[188:191], v[72:75]
	v_mfma_f32_16x16x32_bf16 v[76:79], v[132:135], v[188:191], v[76:79]
	s_barrier
	s_add_i32 s73, s29, s20
	v_lshl_add_u64 v[164:165], s[40:41], 0, v[168:169]
	s_mov_b32 m0, s73
	ds_read_b128 v[192:195], v203
	ds_read_b128 v[206:209], v203 offset:1024
	ds_read_b128 v[210:213], v203 offset:2048
	ds_read_b128 v[214:217], v203 offset:3072
	global_load_lds_dwordx4 v[164:165], off
	v_lshl_add_u64 v[218:219], s[40:41], 0, v[172:173]
	s_add_i32 m0, s73, 0x2000
	s_nop 0
	global_load_lds_dwordx4 v[218:219], off
	s_barrier
	s_waitcnt lgkmcnt(0)
	s_waitcnt lgkmcnt(0)
	v_mfma_f32_16x16x32_bf16 v[116:119], v[192:195], v[144:147], v[116:119]
	v_mfma_f32_16x16x32_bf16 v[112:115], v[210:213], v[144:147], v[112:115]
	v_mfma_f32_16x16x32_bf16 v[96:99], v[210:213], v[152:155], v[96:99]
	v_mfma_f32_16x16x32_bf16 v[100:103], v[192:195], v[152:155], v[100:103]
	v_mfma_f32_16x16x32_bf16 v[84:87], v[192:195], v[160:163], v[84:87]
	v_mfma_f32_16x16x32_bf16 v[80:83], v[210:213], v[160:163], v[80:83]
	v_mfma_f32_16x16x32_bf16 v[64:67], v[210:213], v[184:187], v[64:67]
	v_mfma_f32_16x16x32_bf16 v[68:71], v[192:195], v[184:187], v[68:71]
	v_mfma_f32_16x16x32_bf16 v[116:119], v[206:209], v[148:151], v[116:119]
	v_mfma_f32_16x16x32_bf16 v[112:115], v[214:217], v[148:151], v[112:115]
	v_mfma_f32_16x16x32_bf16 v[96:99], v[214:217], v[156:159], v[96:99]
	v_mfma_f32_16x16x32_bf16 v[100:103], v[206:209], v[156:159], v[100:103]
	v_mfma_f32_16x16x32_bf16 v[84:87], v[206:209], v[180:183], v[84:87]
	v_mfma_f32_16x16x32_bf16 v[80:83], v[214:217], v[180:183], v[80:83]
	v_mfma_f32_16x16x32_bf16 v[64:67], v[214:217], v[188:191], v[64:67]
	v_mfma_f32_16x16x32_bf16 v[68:71], v[206:209], v[188:191], v[68:71]
	s_mov_b32 m0, s82
	v_lshl_add_u64 v[220:221], s[16:17], 0, v[166:167]
	s_barrier
	ds_read_b128 v[144:147], v202 offset:16384
	ds_read_b128 v[148:151], v202 offset:17408
	ds_read_b128 v[152:155], v202 offset:18432
	ds_read_b128 v[156:159], v202 offset:19456
	ds_read_b128 v[160:163], v202 offset:20480
	ds_read_b128 v[180:183], v202 offset:21504
	ds_read_b128 v[184:187], v202 offset:22528
	ds_read_b128 v[188:191], v202 offset:23552
	global_load_lds_dwordx4 v[220:221], off
	v_lshl_add_u64 v[222:223], s[16:17], 0, v[170:171]
	s_mov_b32 m0, s22
	s_nop 0
	global_load_lds_dwordx4 v[222:223], off
	s_barrier
	s_waitcnt lgkmcnt(0)
	s_waitcnt lgkmcnt(0)
	v_mfma_f32_16x16x32_bf16 v[60:63], v[128:131], v[144:147], v[60:63]
	v_mfma_f32_16x16x32_bf16 v[56:59], v[136:139], v[144:147], v[56:59]
	v_mfma_f32_16x16x32_bf16 v[40:43], v[136:139], v[152:155], v[40:43]
	v_mfma_f32_16x16x32_bf16 v[44:47], v[128:131], v[152:155], v[44:47]
	v_mfma_f32_16x16x32_bf16 v[28:31], v[128:131], v[160:163], v[28:31]
	v_mfma_f32_16x16x32_bf16 v[24:27], v[136:139], v[160:163], v[24:27]
	v_mfma_f32_16x16x32_bf16 v[8:11], v[136:139], v[184:187], v[8:11]
	v_mfma_f32_16x16x32_bf16 v[12:15], v[128:131], v[184:187], v[12:15]
	v_mfma_f32_16x16x32_bf16 v[60:63], v[132:135], v[148:151], v[60:63]
	v_mfma_f32_16x16x32_bf16 v[56:59], v[140:143], v[148:151], v[56:59]
	v_mfma_f32_16x16x32_bf16 v[40:43], v[140:143], v[156:159], v[40:43]
	v_mfma_f32_16x16x32_bf16 v[44:47], v[132:135], v[156:159], v[44:47]
	v_mfma_f32_16x16x32_bf16 v[28:31], v[132:135], v[180:183], v[28:31]
	v_mfma_f32_16x16x32_bf16 v[24:27], v[140:143], v[180:183], v[24:27]
	v_mfma_f32_16x16x32_bf16 v[8:11], v[140:143], v[188:191], v[8:11]
	v_mfma_f32_16x16x32_bf16 v[12:15], v[132:135], v[188:191], v[12:15]
	s_barrier
; #define PG8_STAGE(bufoff, gbase, voff) do { _Pragma("unroll") for (int _i = 0; _i < 2; ++_i) \
;         __builtin_amdgcn_global_load_lds((const unsigned*)((const char*)(gbase) + (voff)[_i]), (LAS unsigned*)(lds + (bufoff) + ldsw + _i * 8192), 16, 0, 0); } while (0)
; #define PG8_LDA(dst, b, h) do { _Pragma("unroll") for (int m = 0; m < 4; ++m) _Pragma("unroll") for (int k = 0; k < 2; ++k) dst[m][k] = *(const LAS bf16x8*)(lds + PG8_SA(b, h) + aoff + m * 2048 + k * 1024); } while (0)
; #define PG8_LDB(dst, b, h) do { _Pragma("unroll") for (int n = 0; n < 2; ++n) _Pragma("unroll") for (int k = 0; k < 2; ++k) dst[n][k] = *(const LAS bf16x8*)(lds + PG8_SB(b, h) + boff + n * 2048 + k * 1024); } while (0)
; #define PG8_MMA(ai, bj, At, Bt) do { __builtin_amdgcn_s_setprio(1); _Pragma("unroll") for (int m = 0; m < 4; ++m) _Pragma("unroll") for (int n = 0; n < 2; ++n) _Pragma("unroll") for (int k = 0; k < 2; ++k) \
;         acc[ai][bj][m][n] = __builtin_amdgcn_mfma_f32_16x16x32_bf16(Bt[n][k], At[m][k], acc[ai][bj][m][n], 0, 0, 0); __builtin_amdgcn_s_setprio(0); } while (0)
; #define PG8_WAIT_V(n) asm volatile("s_waitcnt vmcnt(" #n ")" ::: "memory")
; #define PG8_WAIT_L(n) asm volatile("s_waitcnt lgkmcnt(" #n ")" ::: "memory")
; #define PG8_BAR __builtin_amdgcn_s_barrier()
; #define PG8_SCHED __builtin_amdgcn_sched_barrier(0)
; template <class Epi>
; DEVI void gemm_phase(LAS unsigned char* lds, const bf16_t* gA, const bf16_t* gBt, const int lda, const int ldb, const int K, const StaticOrder S_, const Epi E) {
;     ...
;             PG8_STAGE(PG8_SB(0, 1), b2 + hstepB, voffB);
;             PG8_WAIT_V(6); PG8_BAR; PG8_MMA(1, 1, At, B1); PG8_BAR;
;             PG8_LDB(B0, 1, 0); PG8_SCHED; PG8_LDA(At, 1, 0); PG8_STAGE(PG8_SA(0, 1), a2 + hstepA, voffA);
;             PG8_WAIT_L(8); PG8_BAR; PG8_WAIT_L(0); PG8_MMA(0, 0, At, B0); PG8_BAR; PG8_SCHED;
;             PG8_LDB(B1, 1, 1); PG8_STAGE(PG8_SB(1, 0), b3, voffB);
	s_add_u32 s40, s40, s2
	s_addc_u32 s41, s41, s3
	s_add_i32 s73, s50, s20
	v_lshl_add_u64 v[224:225], s[40:41], 0, v[168:169]
	s_mov_b32 m0, s73
	v_lshl_add_u64 v[226:227], s[40:41], 0, v[172:173]
	global_load_lds_dwordx4 v[224:225], off
	s_add_i32 m0, s73, 0x2000
	s_nop 0
	global_load_lds_dwordx4 v[226:227], off
	s_waitcnt vmcnt(6)
	s_barrier
	v_mfma_f32_16x16x32_bf16 v[52:55], v[192:195], v[144:147], v[52:55]
	v_mfma_f32_16x16x32_bf16 v[48:51], v[210:213], v[144:147], v[48:51]
	v_mfma_f32_16x16x32_bf16 v[32:35], v[210:213], v[152:155], v[32:35]
	v_mfma_f32_16x16x32_bf16 v[36:39], v[192:195], v[152:155], v[36:39]
	v_mfma_f32_16x16x32_bf16 v[20:23], v[192:195], v[160:163], v[20:23]
	v_mfma_f32_16x16x32_bf16 v[16:19], v[210:213], v[160:163], v[16:19]
	v_mfma_f32_16x16x32_bf16 v[0:3], v[210:213], v[184:187], v[0:3]
	v_mfma_f32_16x16x32_bf16 v[4:7], v[192:195], v[184:187], v[4:7]
	v_mfma_f32_16x16x32_bf16 v[52:55], v[206:209], v[148:151], v[52:55]
	v_mfma_f32_16x16x32_bf16 v[48:51], v[214:217], v[148:151], v[48:51]
	v_mfma_f32_16x16x32_bf16 v[32:35], v[214:217], v[156:159], v[32:35]
	v_mfma_f32_16x16x32_bf16 v[36:39], v[206:209], v[156:159], v[36:39]
	v_mfma_f32_16x16x32_bf16 v[20:23], v[206:209], v[180:183], v[20:23]
	v_mfma_f32_16x16x32_bf16 v[16:19], v[214:217], v[180:183], v[16:19]
	v_mfma_f32_16x16x32_bf16 v[0:3], v[214:217], v[188:191], v[0:3]
	v_mfma_f32_16x16x32_bf16 v[4:7], v[206:209], v[188:191], v[4:7]
	s_add_i32 s40, 0, 0x18000
	v_add_u32_e32 v140, s40, v199
	s_barrier
	ds_read_b128 v[128:131], v140
	ds_read_b128 v[132:135], v140 offset:1024
	ds_read_b128 v[136:139], v140 offset:2048
	ds_read_b128 v[140:143], v140 offset:3072
	s_add_u32 s16, s16, s0
	s_addc_u32 s17, s17, s1
	s_mov_b32 m0, s23
	v_lshl_add_u64 v[192:193], s[16:17], 0, v[166:167]
	ds_read_b128 v[144:147], v202 offset:32768
	ds_read_b128 v[148:151], v202 offset:33792
	ds_read_b128 v[152:155], v202 offset:34816
	ds_read_b128 v[156:159], v202 offset:35840
	ds_read_b128 v[160:163], v202 offset:36864
	ds_read_b128 v[180:183], v202 offset:37888
	ds_read_b128 v[184:187], v202 offset:38912
	ds_read_b128 v[188:191], v202 offset:39936
	global_load_lds_dwordx4 v[192:193], off
	v_lshl_add_u64 v[192:193], s[16:17], 0, v[170:171]
	s_mov_b32 m0, s24
	s_nop 0
	global_load_lds_dwordx4 v[192:193], off
	s_waitcnt lgkmcnt(8)
	s_barrier
	s_waitcnt lgkmcnt(0)
	s_waitcnt lgkmcnt(0)
	v_mfma_f32_16x16x32_bf16 v[124:127], v[128:131], v[144:147], v[124:127]
	v_mfma_f32_16x16x32_bf16 v[120:123], v[136:139], v[144:147], v[120:123]
	v_mfma_f32_16x16x32_bf16 v[104:107], v[136:139], v[152:155], v[104:107]
	v_mfma_f32_16x16x32_bf16 v[108:111], v[128:131], v[152:155], v[108:111]
	v_mfma_f32_16x16x32_bf16 v[92:95], v[128:131], v[160:163], v[92:95]
	v_mfma_f32_16x16x32_bf16 v[88:91], v[136:139], v[160:163], v[88:91]
	v_mfma_f32_16x16x32_bf16 v[72:75], v[136:139], v[184:187], v[72:75]
	v_mfma_f32_16x16x32_bf16 v[76:79], v[128:131], v[184:187], v[76:79]
	v_mfma_f32_16x16x32_bf16 v[124:127], v[132:135], v[148:151], v[124:127]
	v_mfma_f32_16x16x32_bf16 v[120:123], v[140:143], v[148:151], v[120:123]
	v_mfma_f32_16x16x32_bf16 v[104:107], v[140:143], v[156:159], v[104:107]
	v_mfma_f32_16x16x32_bf16 v[108:111], v[132:135], v[156:159], v[108:111]
	v_mfma_f32_16x16x32_bf16 v[92:95], v[132:135], v[180:183], v[92:95]
	v_mfma_f32_16x16x32_bf16 v[88:91], v[140:143], v[180:183], v[88:91]
	v_mfma_f32_16x16x32_bf16 v[72:75], v[140:143], v[188:191], v[72:75]
	v_mfma_f32_16x16x32_bf16 v[76:79], v[132:135], v[188:191], v[76:79]
	s_barrier
	s_add_i32 s16, 0, 0x1c000
	s_add_i32 s17, s40, s20
	v_add_u32_e32 v205, s16, v199
	v_lshl_add_u64 v[164:165], v[164:165], 0, s[8:9]
	s_mov_b32 m0, s17
	ds_read_b128 v[192:195], v205
	ds_read_b128 v[206:209], v205 offset:1024
	ds_read_b128 v[210:213], v205 offset:2048
	ds_read_b128 v[214:217], v205 offset:3072
	global_load_lds_dwordx4 v[164:165], off
	v_lshl_add_u64 v[164:165], v[218:219], 0, s[8:9]
	s_add_i32 m0, s17, 0x2000
	s_nop 0
	global_load_lds_dwordx4 v[164:165], off
	s_barrier
; #define PG8_STAGE(bufoff, gbase, voff) do { _Pragma("unroll") for (int _i = 0; _i < 2; ++_i) \
;         __builtin_amdgcn_global_load_lds((const unsigned*)((const char*)(gbase) + (voff)[_i]), (LAS unsigned*)(lds + (bufoff) + ldsw + _i * 8192), 16, 0, 0); } while (0)
; #define PG8_LDA(dst, b, h) do { _Pragma("unroll") for (int m = 0; m < 4; ++m) _Pragma("unroll") for (int k = 0; k < 2; ++k) dst[m][k] = *(const LAS bf16x8*)(lds + PG8_SA(b, h) + aoff + m * 2048 + k * 1024); } while (0)
; #define PG8_MMA(ai, bj, At, Bt) do { __builtin_amdgcn_s_setprio(1); _Pragma("unroll") for (int m = 0; m < 4; ++m) _Pragma("unroll") for (int n = 0; n < 2; ++n) _Pragma("unroll") for (int k = 0; k < 2; ++k) \
;         acc[ai][bj][m][n] = __builtin_amdgcn_mfma_f32_16x16x32_bf16(Bt[n][k], At[m][k], acc[ai][bj][m][n], 0, 0, 0); __builtin_amdgcn_s_setprio(0); } while (0)
; #define PG8_WAIT_V(n) asm volatile("s_waitcnt vmcnt(" #n ")" ::: "memory")
; #define PG8_WAIT_L(n) asm volatile("s_waitcnt lgkmcnt(" #n ")" ::: "memory")
; #define PG8_BAR __builtin_amdgcn_s_barrier()
; #define PG8_SCHED __builtin_amdgcn_sched_barrier(0)
; template <class Epi>
; DEVI void gemm_phase(LAS unsigned char* lds, const bf16_t* gA, const bf16_t* gBt, const int lda, const int ldb, const int K, const StaticOrder S_, const Epi E) {
;     ...
;             PG8_BAR; PG8_WAIT_L(0); PG8_MMA(0, 1, At, B1); PG8_BAR;
;             PG8_LDA(At, 1, 1); PG8_STAGE(PG8_SA(1, 0), a3, voffA);
;             PG8_BAR; PG8_WAIT_L(0); PG8_MMA(1, 0, At, B0); PG8_BAR; PG8_SCHED;
;             PG8_STAGE(PG8_SB(1, 1), b3 + hstepB, voffB);
;             PG8_WAIT_V(6); PG8_BAR; PG8_MMA(1, 1, At, B1); PG8_BAR;
	s_waitcnt lgkmcnt(0)
	s_waitcnt lgkmcnt(0)
	v_mfma_f32_16x16x32_bf16 v[116:119], v[192:195], v[144:147], v[116:119]
	v_mfma_f32_16x16x32_bf16 v[112:115], v[210:213], v[144:147], v[112:115]
	v_mfma_f32_16x16x32_bf16 v[96:99], v[210:213], v[152:155], v[96:99]
	v_mfma_f32_16x16x32_bf16 v[100:103], v[192:195], v[152:155], v[100:103]
	v_mfma_f32_16x16x32_bf16 v[84:87], v[192:195], v[160:163], v[84:87]
	v_mfma_f32_16x16x32_bf16 v[80:83], v[210:213], v[160:163], v[80:83]
	v_mfma_f32_16x16x32_bf16 v[64:67], v[210:213], v[184:187], v[64:67]
	v_mfma_f32_16x16x32_bf16 v[68:71], v[192:195], v[184:187], v[68:71]
	v_mfma_f32_16x16x32_bf16 v[116:119], v[206:209], v[148:151], v[116:119]
	v_mfma_f32_16x16x32_bf16 v[112:115], v[214:217], v[148:151], v[112:115]
	v_mfma_f32_16x16x32_bf16 v[96:99], v[214:217], v[156:159], v[96:99]
	v_mfma_f32_16x16x32_bf16 v[100:103], v[206:209], v[156:159], v[100:103]
	v_mfma_f32_16x16x32_bf16 v[84:87], v[206:209], v[180:183], v[84:87]
	v_mfma_f32_16x16x32_bf16 v[80:83], v[214:217], v[180:183], v[80:83]
	v_mfma_f32_16x16x32_bf16 v[64:67], v[214:217], v[188:191], v[64:67]
	v_mfma_f32_16x16x32_bf16 v[68:71], v[206:209], v[188:191], v[68:71]
	s_mov_b32 m0, s26
	v_lshl_add_u64 v[164:165], v[220:221], 0, s[8:9]
	s_barrier
	ds_read_b128 v[144:147], v202 offset:49152
	ds_read_b128 v[148:151], v202 offset:50176
	ds_read_b128 v[152:155], v202 offset:51200
	ds_read_b128 v[156:159], v202 offset:52224
	ds_read_b128 v[160:163], v202 offset:53248
	ds_read_b128 v[180:183], v202 offset:54272
	ds_read_b128 v[184:187], v202 offset:55296
	ds_read_b128 v[188:191], v202 offset:56320
	global_load_lds_dwordx4 v[164:165], off
	v_lshl_add_u64 v[164:165], v[222:223], 0, s[8:9]
	s_mov_b32 m0, s27
	s_nop 0
	global_load_lds_dwordx4 v[164:165], off
	s_barrier
	s_waitcnt lgkmcnt(0)
	s_waitcnt lgkmcnt(0)
	v_mfma_f32_16x16x32_bf16 v[60:63], v[128:131], v[144:147], v[60:63]
	v_mfma_f32_16x16x32_bf16 v[56:59], v[136:139], v[144:147], v[56:59]
	v_mfma_f32_16x16x32_bf16 v[40:43], v[136:139], v[152:155], v[40:43]
	v_mfma_f32_16x16x32_bf16 v[44:47], v[128:131], v[152:155], v[44:47]
	v_mfma_f32_16x16x32_bf16 v[28:31], v[128:131], v[160:163], v[28:31]
	v_mfma_f32_16x16x32_bf16 v[24:27], v[136:139], v[160:163], v[24:27]
	v_mfma_f32_16x16x32_bf16 v[8:11], v[136:139], v[184:187], v[8:11]
	v_mfma_f32_16x16x32_bf16 v[12:15], v[128:131], v[184:187], v[12:15]
	v_mfma_f32_16x16x32_bf16 v[60:63], v[132:135], v[148:151], v[60:63]
	v_mfma_f32_16x16x32_bf16 v[56:59], v[140:143], v[148:151], v[56:59]
	v_mfma_f32_16x16x32_bf16 v[40:43], v[140:143], v[156:159], v[40:43]
	v_mfma_f32_16x16x32_bf16 v[44:47], v[132:135], v[156:159], v[44:47]
	v_mfma_f32_16x16x32_bf16 v[28:31], v[132:135], v[180:183], v[28:31]
	v_mfma_f32_16x16x32_bf16 v[24:27], v[140:143], v[180:183], v[24:27]
	v_mfma_f32_16x16x32_bf16 v[8:11], v[140:143], v[188:191], v[8:11]
	v_mfma_f32_16x16x32_bf16 v[12:15], v[132:135], v[188:191], v[12:15]
	s_barrier
	s_add_i32 s16, s16, s20
	v_lshl_add_u64 v[128:129], v[224:225], 0, s[8:9]
	s_mov_b32 m0, s16
	s_nop 0
	global_load_lds_dwordx4 v[128:129], off
	v_lshl_add_u64 v[128:129], v[226:227], 0, s[8:9]
	s_add_i32 m0, s16, 0x2000
	s_nop 0
	global_load_lds_dwordx4 v[128:129], off
	s_waitcnt vmcnt(6)
	s_barrier
	v_mfma_f32_16x16x32_bf16 v[52:55], v[192:195], v[144:147], v[52:55]
	v_mfma_f32_16x16x32_bf16 v[48:51], v[210:213], v[144:147], v[48:51]
	v_mfma_f32_16x16x32_bf16 v[32:35], v[210:213], v[152:155], v[32:35]
	v_mfma_f32_16x16x32_bf16 v[36:39], v[192:195], v[152:155], v[36:39]
	v_mfma_f32_16x16x32_bf16 v[20:23], v[192:195], v[160:163], v[20:23]
	v_mfma_f32_16x16x32_bf16 v[16:19], v[210:213], v[160:163], v[16:19]
	v_mfma_f32_16x16x32_bf16 v[0:3], v[210:213], v[184:187], v[0:3]
	v_mfma_f32_16x16x32_bf16 v[4:7], v[192:195], v[184:187], v[4:7]
	v_mfma_f32_16x16x32_bf16 v[52:55], v[206:209], v[148:151], v[52:55]
	v_mfma_f32_16x16x32_bf16 v[48:51], v[214:217], v[148:151], v[48:51]
	v_mfma_f32_16x16x32_bf16 v[32:35], v[214:217], v[156:159], v[32:35]
	v_mfma_f32_16x16x32_bf16 v[36:39], v[206:209], v[156:159], v[36:39]
	v_mfma_f32_16x16x32_bf16 v[20:23], v[206:209], v[180:183], v[20:23]
	v_mfma_f32_16x16x32_bf16 v[16:19], v[214:217], v[180:183], v[16:19]
	v_mfma_f32_16x16x32_bf16 v[0:3], v[214:217], v[188:191], v[0:3]
	v_mfma_f32_16x16x32_bf16 v[4:7], v[206:209], v[188:191], v[4:7]
	s_add_u32 s14, s14, 0x100
	s_addc_u32 s15, s15, 0
	s_add_u32 s70, s70, 0x100
	s_addc_u32 s71, s71, 0
	s_cmp_ge_i32 s72, s25
	s_mov_b32 s16, s72
	s_barrier
	s_cbranch_scc0 .LBB0_1301

; #define PG8_STAGE(bufoff, gbase, voff) do { _Pragma("unroll") for (int _i = 0; _i < 2; ++_i) \
;         __builtin_amdgcn_global_load_lds((const unsigned*)((const char*)(gbase) + (voff)[_i]), (LAS unsigned*)(lds + (bufoff) + ldsw + _i * 8192), 16, 0, 0); } while (0)
; #define PG8_LDA(dst, b, h) do { _Pragma("unroll") for (int m = 0; m < 4; ++m) _Pragma("unroll") for (int k = 0; k < 2; ++k) dst[m][k] = *(const LAS bf16x8*)(lds + PG8_SA(b, h) + aoff + m * 2048 + k * 1024); } while (0)
; #define PG8_LDB(dst, b, h) do { _Pragma("unroll") for (int n = 0; n < 2; ++n) _Pragma("unroll") for (int k = 0; k < 2; ++k) dst[n][k] = *(const LAS bf16x8*)(lds + PG8_SB(b, h) + boff + n * 2048 + k * 1024); } while (0)
; #define PG8_MMA(ai, bj, At, Bt) do { __builtin_amdgcn_s_setprio(1); _Pragma("unroll") for (int m = 0; m < 4; ++m) _Pragma("unroll") for (int n = 0; n < 2; ++n) _Pragma("unroll") for (int k = 0; k < 2; ++k) \
;         acc[ai][bj][m][n] = __builtin_amdgcn_mfma_f32_16x16x32_bf16(Bt[n][k], At[m][k], acc[ai][bj][m][n], 0, 0, 0); __builtin_amdgcn_s_setprio(0); } while (0)
; #define PG8_WAIT_L(n) asm volatile("s_waitcnt lgkmcnt(" #n ")" ::: "memory")
; #define PG8_BAR __builtin_amdgcn_s_barrier()
; #define PG8_SCHED __builtin_amdgcn_sched_barrier(0)
; template <class Epi>
; DEVI void gemm_phase(LAS unsigned char* lds, const bf16_t* gA, const bf16_t* gBt, const int lda, const int ldb, const int K, const StaticOrder S_, const Epi E) {
;     ...
;             PG8_LDB(B0, 0, 0); PG8_SCHED; PG8_LDA(At, 0, 0); PG8_STAGE(PG8_SA(1, 1), a1 + hstepA, voffA);
;             PG8_WAIT_L(8); PG8_BAR; PG8_WAIT_L(0); PG8_MMA(0, 0, At, B0); PG8_BAR; PG8_SCHED;
;             PG8_LDB(B1, 0, 1); PG8_STAGE(PG8_SB(0, 0), b2, voffB);
;             PG8_BAR; PG8_WAIT_L(0); PG8_MMA(0, 1, At, B1); PG8_BAR;
;             PG8_LDA(At, 0, 1); PG8_STAGE(PG8_SA(0, 0), a2, voffA);
;             PG8_BAR; PG8_WAIT_L(0); PG8_MMA(1, 0, At, B0); PG8_BAR; PG8_SCHED;
.LBB0_1445:
	ds_read_b128 v[158:161], v151
	ds_read_b128 v[162:165], v151 offset:1024
	ds_read_b128 v[166:169], v151 offset:2048
	ds_read_b128 v[170:173], v151 offset:3072
	s_add_i32 s79, s16, 2
	s_add_u32 s70, s14, 0x80
	s_addc_u32 s17, s15, 0
	s_cmp_eq_u32 s26, s16
	s_cselect_b32 s16, s40, s70
	s_cselect_b32 s17, s41, s17
	s_cselect_b32 s71, s67, s78
	s_cselect_b32 s70, s66, s77
	v_lshl_add_u64 v[144:145], s[14:15], 0, v[138:139]
	s_add_i32 m0, s19, 0xc000
	ds_read_b128 v[174:177], v152
	ds_read_b128 v[178:181], v152 offset:1024
	ds_read_b128 v[182:185], v152 offset:2048
	ds_read_b128 v[186:189], v152 offset:3072
	ds_read_b128 v[190:193], v152 offset:4096
	ds_read_b128 v[198:201], v152 offset:5120
	ds_read_b128 v[202:205], v152 offset:6144
	ds_read_b128 v[206:209], v152 offset:7168
	global_load_lds_dwordx4 v[144:145], off
	v_lshl_add_u64 v[144:145], s[14:15], 0, v[140:141]
	s_add_i32 m0, s19, 0xe000
	s_nop 0
	global_load_lds_dwordx4 v[144:145], off
	s_waitcnt lgkmcnt(8)
	s_barrier
	s_waitcnt lgkmcnt(0)
	s_waitcnt lgkmcnt(0)
	v_mfma_f32_16x16x32_bf16 v[120:123], v[158:161], v[174:177], v[120:123]
	v_mfma_f32_16x16x32_bf16 v[116:119], v[166:169], v[174:177], v[116:119]
	v_mfma_f32_16x16x32_bf16 v[100:103], v[166:169], v[182:185], v[100:103]
	v_mfma_f32_16x16x32_bf16 v[108:111], v[158:161], v[182:185], v[108:111]
	v_mfma_f32_16x16x32_bf16 v[92:95], v[158:161], v[190:193], v[92:95]
	v_mfma_f32_16x16x32_bf16 v[84:87], v[166:169], v[190:193], v[84:87]
	v_mfma_f32_16x16x32_bf16 v[68:71], v[166:169], v[202:205], v[68:71]
	v_mfma_f32_16x16x32_bf16 v[76:79], v[158:161], v[202:205], v[76:79]
	v_mfma_f32_16x16x32_bf16 v[120:123], v[162:165], v[178:181], v[120:123]
	v_mfma_f32_16x16x32_bf16 v[116:119], v[170:173], v[178:181], v[116:119]
	v_mfma_f32_16x16x32_bf16 v[100:103], v[170:173], v[186:189], v[100:103]
	v_mfma_f32_16x16x32_bf16 v[108:111], v[162:165], v[186:189], v[108:111]
	v_mfma_f32_16x16x32_bf16 v[92:95], v[162:165], v[198:201], v[92:95]
	v_mfma_f32_16x16x32_bf16 v[84:87], v[170:173], v[198:201], v[84:87]
	v_mfma_f32_16x16x32_bf16 v[68:71], v[170:173], v[206:209], v[68:71]
	v_mfma_f32_16x16x32_bf16 v[76:79], v[162:165], v[206:209], v[76:79]
	s_barrier
	s_add_i32 s80, s34, s18
	v_lshl_add_u64 v[144:145], s[70:71], 0, v[130:131]
	s_mov_b32 m0, s80
	ds_read_b128 v[210:213], v153
	ds_read_b128 v[214:217], v153 offset:1024
	ds_read_b128 v[218:221], v153 offset:2048
	ds_read_b128 v[222:225], v153 offset:3072
	global_load_lds_dwordx4 v[144:145], off
	v_lshl_add_u64 v[194:195], s[70:71], 0, v[134:135]
	s_add_i32 m0, s80, 0x2000
	s_nop 0
	global_load_lds_dwordx4 v[194:195], off
	s_barrier
	s_waitcnt lgkmcnt(0)
	s_waitcnt lgkmcnt(0)
	v_mfma_f32_16x16x32_bf16 v[124:127], v[210:213], v[174:177], v[124:127]
	v_mfma_f32_16x16x32_bf16 v[112:115], v[218:221], v[174:177], v[112:115]
	v_mfma_f32_16x16x32_bf16 v[96:99], v[218:221], v[182:185], v[96:99]
	v_mfma_f32_16x16x32_bf16 v[104:107], v[210:213], v[182:185], v[104:107]
	v_mfma_f32_16x16x32_bf16 v[88:91], v[210:213], v[190:193], v[88:91]
	v_mfma_f32_16x16x32_bf16 v[80:83], v[218:221], v[190:193], v[80:83]
	v_mfma_f32_16x16x32_bf16 v[64:67], v[218:221], v[202:205], v[64:67]
	v_mfma_f32_16x16x32_bf16 v[72:75], v[210:213], v[202:205], v[72:75]
	v_mfma_f32_16x16x32_bf16 v[124:127], v[214:217], v[178:181], v[124:127]
	v_mfma_f32_16x16x32_bf16 v[112:115], v[222:225], v[178:181], v[112:115]
	v_mfma_f32_16x16x32_bf16 v[96:99], v[222:225], v[186:189], v[96:99]
	v_mfma_f32_16x16x32_bf16 v[104:107], v[214:217], v[186:189], v[104:107]
	v_mfma_f32_16x16x32_bf16 v[88:91], v[214:217], v[198:201], v[88:91]
	v_mfma_f32_16x16x32_bf16 v[80:83], v[222:225], v[198:201], v[80:83]
	v_mfma_f32_16x16x32_bf16 v[64:67], v[222:225], v[206:209], v[64:67]
	v_mfma_f32_16x16x32_bf16 v[72:75], v[214:217], v[206:209], v[72:75]
	s_mov_b32 m0, s19
	v_lshl_add_u64 v[226:227], s[16:17], 0, v[128:129]
	s_barrier
	ds_read_b128 v[174:177], v152 offset:16384
	ds_read_b128 v[178:181], v152 offset:17408
	ds_read_b128 v[182:185], v152 offset:18432
	ds_read_b128 v[186:189], v152 offset:19456
	ds_read_b128 v[190:193], v152 offset:20480
	ds_read_b128 v[198:201], v152 offset:21504
	ds_read_b128 v[202:205], v152 offset:22528
	ds_read_b128 v[206:209], v152 offset:23552
	global_load_lds_dwordx4 v[226:227], off
	v_lshl_add_u64 v[228:229], s[16:17], 0, v[132:133]
	s_mov_b32 m0, s20
	s_nop 0
	global_load_lds_dwordx4 v[228:229], off
	s_barrier
	s_waitcnt lgkmcnt(0)
	s_waitcnt lgkmcnt(0)
	v_mfma_f32_16x16x32_bf16 v[60:63], v[158:161], v[174:177], v[60:63]
	v_mfma_f32_16x16x32_bf16 v[56:59], v[166:169], v[174:177], v[56:59]
	v_mfma_f32_16x16x32_bf16 v[40:43], v[166:169], v[182:185], v[40:43]
	v_mfma_f32_16x16x32_bf16 v[44:47], v[158:161], v[182:185], v[44:47]
	v_mfma_f32_16x16x32_bf16 v[28:31], v[158:161], v[190:193], v[28:31]
	v_mfma_f32_16x16x32_bf16 v[24:27], v[166:169], v[190:193], v[24:27]
	v_mfma_f32_16x16x32_bf16 v[8:11], v[166:169], v[202:205], v[8:11]
	v_mfma_f32_16x16x32_bf16 v[12:15], v[158:161], v[202:205], v[12:15]
	v_mfma_f32_16x16x32_bf16 v[60:63], v[162:165], v[178:181], v[60:63]
	v_mfma_f32_16x16x32_bf16 v[56:59], v[170:173], v[178:181], v[56:59]
	v_mfma_f32_16x16x32_bf16 v[40:43], v[170:173], v[186:189], v[40:43]
	v_mfma_f32_16x16x32_bf16 v[44:47], v[162:165], v[186:189], v[44:47]
	v_mfma_f32_16x16x32_bf16 v[28:31], v[162:165], v[198:201], v[28:31]
	v_mfma_f32_16x16x32_bf16 v[24:27], v[170:173], v[198:201], v[24:27]
	v_mfma_f32_16x16x32_bf16 v[8:11], v[170:173], v[206:209], v[8:11]
	v_mfma_f32_16x16x32_bf16 v[12:15], v[162:165], v[206:209], v[12:15]
	s_barrier
; #define PG8_STAGE(bufoff, gbase, voff) do { _Pragma("unroll") for (int _i = 0; _i < 2; ++_i) \
;         __builtin_amdgcn_global_load_lds((const unsigned*)((const char*)(gbase) + (voff)[_i]), (LAS unsigned*)(lds + (bufoff) + ldsw + _i * 8192), 16, 0, 0); } while (0)
; #define PG8_LDA(dst, b, h) do { _Pragma("unroll") for (int m = 0; m < 4; ++m) _Pragma("unroll") for (int k = 0; k < 2; ++k) dst[m][k] = *(const LAS bf16x8*)(lds + PG8_SA(b, h) + aoff + m * 2048 + k * 1024); } while (0)
; #define PG8_LDB(dst, b, h) do { _Pragma("unroll") for (int n = 0; n < 2; ++n) _Pragma("unroll") for (int k = 0; k < 2; ++k) dst[n][k] = *(const LAS bf16x8*)(lds + PG8_SB(b, h) + boff + n * 2048 + k * 1024); } while (0)
; #define PG8_MMA(ai, bj, At, Bt) do { __builtin_amdgcn_s_setprio(1); _Pragma("unroll") for (int m = 0; m < 4; ++m) _Pragma("unroll") for (int n = 0; n < 2; ++n) _Pragma("unroll") for (int k = 0; k < 2; ++k) \
;         acc[ai][bj][m][n] = __builtin_amdgcn_mfma_f32_16x16x32_bf16(Bt[n][k], At[m][k], acc[ai][bj][m][n], 0, 0, 0); __builtin_amdgcn_s_setprio(0); } while (0)
; #define PG8_WAIT_V(n) asm volatile("s_waitcnt vmcnt(" #n ")" ::: "memory")
; #define PG8_WAIT_L(n) asm volatile("s_waitcnt lgkmcnt(" #n ")" ::: "memory")
; #define PG8_BAR __builtin_amdgcn_s_barrier()
; #define PG8_SCHED __builtin_amdgcn_sched_barrier(0)
; template <class Epi>
; DEVI void gemm_phase(LAS unsigned char* lds, const bf16_t* gA, const bf16_t* gBt, const int lda, const int ldb, const int K, const StaticOrder S_, const Epi E) {
;     ...
;             PG8_STAGE(PG8_SB(0, 1), b2 + hstepB, voffB);
;             PG8_WAIT_V(6); PG8_BAR; PG8_MMA(1, 1, At, B1); PG8_BAR;
;             PG8_LDB(B0, 1, 0); PG8_SCHED; PG8_LDA(At, 1, 0); PG8_STAGE(PG8_SA(0, 1), a2 + hstepA, voffA);
;             PG8_WAIT_L(8); PG8_BAR; PG8_WAIT_L(0); PG8_MMA(0, 0, At, B0); PG8_BAR; PG8_SCHED;
;             PG8_LDB(B1, 1, 1); PG8_STAGE(PG8_SB(1, 0), b3, voffB);
	s_add_u32 s70, s70, s2
	s_addc_u32 s71, s71, s3
	s_add_i32 s80, s35, s18
	v_lshl_add_u64 v[230:231], s[70:71], 0, v[130:131]
	s_mov_b32 m0, s80
	v_lshl_add_u64 v[232:233], s[70:71], 0, v[134:135]
	global_load_lds_dwordx4 v[230:231], off
	s_add_i32 m0, s80, 0x2000
	s_nop 0
	global_load_lds_dwordx4 v[232:233], off
	s_waitcnt vmcnt(6)
	s_barrier
	v_mfma_f32_16x16x32_bf16 v[52:55], v[210:213], v[174:177], v[52:55]
	v_mfma_f32_16x16x32_bf16 v[48:51], v[218:221], v[174:177], v[48:51]
	v_mfma_f32_16x16x32_bf16 v[32:35], v[218:221], v[182:185], v[32:35]
	v_mfma_f32_16x16x32_bf16 v[36:39], v[210:213], v[182:185], v[36:39]
	v_mfma_f32_16x16x32_bf16 v[20:23], v[210:213], v[190:193], v[20:23]
	v_mfma_f32_16x16x32_bf16 v[16:19], v[218:221], v[190:193], v[16:19]
	v_mfma_f32_16x16x32_bf16 v[0:3], v[218:221], v[202:205], v[0:3]
	v_mfma_f32_16x16x32_bf16 v[4:7], v[210:213], v[202:205], v[4:7]
	v_mfma_f32_16x16x32_bf16 v[52:55], v[214:217], v[178:181], v[52:55]
	v_mfma_f32_16x16x32_bf16 v[48:51], v[222:225], v[178:181], v[48:51]
	v_mfma_f32_16x16x32_bf16 v[32:35], v[222:225], v[186:189], v[32:35]
	v_mfma_f32_16x16x32_bf16 v[36:39], v[214:217], v[186:189], v[36:39]
	v_mfma_f32_16x16x32_bf16 v[20:23], v[214:217], v[198:201], v[20:23]
	v_mfma_f32_16x16x32_bf16 v[16:19], v[222:225], v[198:201], v[16:19]
	v_mfma_f32_16x16x32_bf16 v[0:3], v[222:225], v[206:209], v[0:3]
	v_mfma_f32_16x16x32_bf16 v[4:7], v[214:217], v[206:209], v[4:7]
	s_barrier
	ds_read_b128 v[158:161], v154
	ds_read_b128 v[162:165], v154 offset:1024
	ds_read_b128 v[166:169], v154 offset:2048
	ds_read_b128 v[170:173], v154 offset:3072
	s_add_u32 s16, s16, s0
	s_addc_u32 s17, s17, s1
	s_mov_b32 m0, s21
	v_lshl_add_u64 v[210:211], s[16:17], 0, v[128:129]
	ds_read_b128 v[174:177], v152 offset:32768
	ds_read_b128 v[178:181], v152 offset:33792
	ds_read_b128 v[182:185], v152 offset:34816
	ds_read_b128 v[186:189], v152 offset:35840
	ds_read_b128 v[190:193], v152 offset:36864
	ds_read_b128 v[198:201], v152 offset:37888
	ds_read_b128 v[202:205], v152 offset:38912
	ds_read_b128 v[206:209], v152 offset:39936
	global_load_lds_dwordx4 v[210:211], off
	v_lshl_add_u64 v[210:211], s[16:17], 0, v[132:133]
	s_mov_b32 m0, s22
	s_nop 0
	global_load_lds_dwordx4 v[210:211], off
	s_waitcnt lgkmcnt(8)
	s_barrier
	s_waitcnt lgkmcnt(0)
	s_waitcnt lgkmcnt(0)
	v_mfma_f32_16x16x32_bf16 v[120:123], v[158:161], v[174:177], v[120:123]
	v_mfma_f32_16x16x32_bf16 v[116:119], v[166:169], v[174:177], v[116:119]
	v_mfma_f32_16x16x32_bf16 v[100:103], v[166:169], v[182:185], v[100:103]
	v_mfma_f32_16x16x32_bf16 v[108:111], v[158:161], v[182:185], v[108:111]
	v_mfma_f32_16x16x32_bf16 v[92:95], v[158:161], v[190:193], v[92:95]
	v_mfma_f32_16x16x32_bf16 v[84:87], v[166:169], v[190:193], v[84:87]
	v_mfma_f32_16x16x32_bf16 v[68:71], v[166:169], v[202:205], v[68:71]
	v_mfma_f32_16x16x32_bf16 v[76:79], v[158:161], v[202:205], v[76:79]
	v_mfma_f32_16x16x32_bf16 v[120:123], v[162:165], v[178:181], v[120:123]
	v_mfma_f32_16x16x32_bf16 v[116:119], v[170:173], v[178:181], v[116:119]
	v_mfma_f32_16x16x32_bf16 v[100:103], v[170:173], v[186:189], v[100:103]
	v_mfma_f32_16x16x32_bf16 v[108:111], v[162:165], v[186:189], v[108:111]
	v_mfma_f32_16x16x32_bf16 v[92:95], v[162:165], v[198:201], v[92:95]
	v_mfma_f32_16x16x32_bf16 v[84:87], v[170:173], v[198:201], v[84:87]
	v_mfma_f32_16x16x32_bf16 v[68:71], v[170:173], v[206:209], v[68:71]
	v_mfma_f32_16x16x32_bf16 v[76:79], v[162:165], v[206:209], v[76:79]
	s_barrier
	s_add_i32 s16, s49, s18
	v_lshl_add_u64 v[144:145], v[144:145], 0, s[64:65]
	s_mov_b32 m0, s16
	ds_read_b128 v[210:213], v155
	ds_read_b128 v[214:217], v155 offset:1024
	ds_read_b128 v[218:221], v155 offset:2048
	ds_read_b128 v[222:225], v155 offset:3072
	global_load_lds_dwordx4 v[144:145], off
	v_lshl_add_u64 v[144:145], v[194:195], 0, s[64:65]
	s_add_i32 m0, s16, 0x2000
	s_nop 0
	global_load_lds_dwordx4 v[144:145], off
	s_barrier
; #define PG8_STAGE(bufoff, gbase, voff) do { _Pragma("unroll") for (int _i = 0; _i < 2; ++_i) \
;         __builtin_amdgcn_global_load_lds((const unsigned*)((const char*)(gbase) + (voff)[_i]), (LAS unsigned*)(lds + (bufoff) + ldsw + _i * 8192), 16, 0, 0); } while (0)
; #define PG8_LDA(dst, b, h) do { _Pragma("unroll") for (int m = 0; m < 4; ++m) _Pragma("unroll") for (int k = 0; k < 2; ++k) dst[m][k] = *(const LAS bf16x8*)(lds + PG8_SA(b, h) + aoff + m * 2048 + k * 1024); } while (0)
; #define PG8_MMA(ai, bj, At, Bt) do { __builtin_amdgcn_s_setprio(1); _Pragma("unroll") for (int m = 0; m < 4; ++m) _Pragma("unroll") for (int n = 0; n < 2; ++n) _Pragma("unroll") for (int k = 0; k < 2; ++k) \
;         acc[ai][bj][m][n] = __builtin_amdgcn_mfma_f32_16x16x32_bf16(Bt[n][k], At[m][k], acc[ai][bj][m][n], 0, 0, 0); __builtin_amdgcn_s_setprio(0); } while (0)
; #define PG8_WAIT_V(n) asm volatile("s_waitcnt vmcnt(" #n ")" ::: "memory")
; #define PG8_WAIT_L(n) asm volatile("s_waitcnt lgkmcnt(" #n ")" ::: "memory")
; #define PG8_BAR __builtin_amdgcn_s_barrier()
; #define PG8_SCHED __builtin_amdgcn_sched_barrier(0)
; template <class Epi>
; DEVI void gemm_phase(LAS unsigned char* lds, const bf16_t* gA, const bf16_t* gBt, const int lda, const int ldb, const int K, const StaticOrder S_, const Epi E) {
;     ...
;             PG8_BAR; PG8_WAIT_L(0); PG8_MMA(0, 1, At, B1); PG8_BAR;
;             PG8_LDA(At, 1, 1); PG8_STAGE(PG8_SA(1, 0), a3, voffA);
;             PG8_BAR; PG8_WAIT_L(0); PG8_MMA(1, 0, At, B0); PG8_BAR; PG8_SCHED;
;             PG8_STAGE(PG8_SB(1, 1), b3 + hstepB, voffB);
;             PG8_WAIT_V(6); PG8_BAR; PG8_MMA(1, 1, At, B1); PG8_BAR;
	s_waitcnt lgkmcnt(0)
	s_waitcnt lgkmcnt(0)
	v_mfma_f32_16x16x32_bf16 v[124:127], v[210:213], v[174:177], v[124:127]
	v_mfma_f32_16x16x32_bf16 v[112:115], v[218:221], v[174:177], v[112:115]
	v_mfma_f32_16x16x32_bf16 v[96:99], v[218:221], v[182:185], v[96:99]
	v_mfma_f32_16x16x32_bf16 v[104:107], v[210:213], v[182:185], v[104:107]
	v_mfma_f32_16x16x32_bf16 v[88:91], v[210:213], v[190:193], v[88:91]
	v_mfma_f32_16x16x32_bf16 v[80:83], v[218:221], v[190:193], v[80:83]
	v_mfma_f32_16x16x32_bf16 v[64:67], v[218:221], v[202:205], v[64:67]
	v_mfma_f32_16x16x32_bf16 v[72:75], v[210:213], v[202:205], v[72:75]
	v_mfma_f32_16x16x32_bf16 v[124:127], v[214:217], v[178:181], v[124:127]
	v_mfma_f32_16x16x32_bf16 v[112:115], v[222:225], v[178:181], v[112:115]
	v_mfma_f32_16x16x32_bf16 v[96:99], v[222:225], v[186:189], v[96:99]
	v_mfma_f32_16x16x32_bf16 v[104:107], v[214:217], v[186:189], v[104:107]
	v_mfma_f32_16x16x32_bf16 v[88:91], v[214:217], v[198:201], v[88:91]
	v_mfma_f32_16x16x32_bf16 v[80:83], v[222:225], v[198:201], v[80:83]
	v_mfma_f32_16x16x32_bf16 v[64:67], v[222:225], v[206:209], v[64:67]
	v_mfma_f32_16x16x32_bf16 v[72:75], v[214:217], v[206:209], v[72:75]
	s_mov_b32 m0, s23
	v_lshl_add_u64 v[144:145], v[226:227], 0, s[64:65]
	s_barrier
	ds_read_b128 v[174:177], v152 offset:49152
	ds_read_b128 v[178:181], v152 offset:50176
	ds_read_b128 v[182:185], v152 offset:51200
	ds_read_b128 v[186:189], v152 offset:52224
	ds_read_b128 v[190:193], v152 offset:53248
	ds_read_b128 v[198:201], v152 offset:54272
	ds_read_b128 v[202:205], v152 offset:55296
	ds_read_b128 v[206:209], v152 offset:56320
	global_load_lds_dwordx4 v[144:145], off
	v_lshl_add_u64 v[144:145], v[228:229], 0, s[64:65]
	s_mov_b32 m0, s24
	s_nop 0
	global_load_lds_dwordx4 v[144:145], off
	s_barrier
	s_waitcnt lgkmcnt(0)
	s_waitcnt lgkmcnt(0)
	v_mfma_f32_16x16x32_bf16 v[60:63], v[158:161], v[174:177], v[60:63]
	v_mfma_f32_16x16x32_bf16 v[56:59], v[166:169], v[174:177], v[56:59]
	v_mfma_f32_16x16x32_bf16 v[40:43], v[166:169], v[182:185], v[40:43]
	v_mfma_f32_16x16x32_bf16 v[44:47], v[158:161], v[182:185], v[44:47]
	v_mfma_f32_16x16x32_bf16 v[28:31], v[158:161], v[190:193], v[28:31]
	v_mfma_f32_16x16x32_bf16 v[24:27], v[166:169], v[190:193], v[24:27]
	v_mfma_f32_16x16x32_bf16 v[8:11], v[166:169], v[202:205], v[8:11]
	v_mfma_f32_16x16x32_bf16 v[12:15], v[158:161], v[202:205], v[12:15]
	v_mfma_f32_16x16x32_bf16 v[60:63], v[162:165], v[178:181], v[60:63]
	v_mfma_f32_16x16x32_bf16 v[56:59], v[170:173], v[178:181], v[56:59]
	v_mfma_f32_16x16x32_bf16 v[40:43], v[170:173], v[186:189], v[40:43]
	v_mfma_f32_16x16x32_bf16 v[44:47], v[162:165], v[186:189], v[44:47]
	v_mfma_f32_16x16x32_bf16 v[28:31], v[162:165], v[198:201], v[28:31]
	v_mfma_f32_16x16x32_bf16 v[24:27], v[170:173], v[198:201], v[24:27]
	v_mfma_f32_16x16x32_bf16 v[8:11], v[170:173], v[206:209], v[8:11]
	v_mfma_f32_16x16x32_bf16 v[12:15], v[162:165], v[206:209], v[12:15]
	s_barrier
	s_add_i32 s16, s31, s18
	v_lshl_add_u64 v[144:145], v[230:231], 0, s[64:65]
	s_mov_b32 m0, s16
	s_nop 0
	global_load_lds_dwordx4 v[144:145], off
	v_lshl_add_u64 v[144:145], v[232:233], 0, s[64:65]
	s_add_i32 m0, s16, 0x2000
	s_nop 0
	global_load_lds_dwordx4 v[144:145], off
	s_waitcnt vmcnt(6)
	s_barrier
	v_mfma_f32_16x16x32_bf16 v[52:55], v[210:213], v[174:177], v[52:55]
	v_mfma_f32_16x16x32_bf16 v[48:51], v[218:221], v[174:177], v[48:51]
	v_mfma_f32_16x16x32_bf16 v[32:35], v[218:221], v[182:185], v[32:35]
	v_mfma_f32_16x16x32_bf16 v[36:39], v[210:213], v[182:185], v[36:39]
	v_mfma_f32_16x16x32_bf16 v[20:23], v[210:213], v[190:193], v[20:23]
	v_mfma_f32_16x16x32_bf16 v[16:19], v[218:221], v[190:193], v[16:19]
	v_mfma_f32_16x16x32_bf16 v[0:3], v[218:221], v[202:205], v[0:3]
	v_mfma_f32_16x16x32_bf16 v[4:7], v[210:213], v[202:205], v[4:7]
	v_mfma_f32_16x16x32_bf16 v[52:55], v[214:217], v[178:181], v[52:55]
	v_mfma_f32_16x16x32_bf16 v[48:51], v[222:225], v[178:181], v[48:51]
	v_mfma_f32_16x16x32_bf16 v[32:35], v[222:225], v[186:189], v[32:35]
	v_mfma_f32_16x16x32_bf16 v[36:39], v[214:217], v[186:189], v[36:39]
	v_mfma_f32_16x16x32_bf16 v[20:23], v[214:217], v[198:201], v[20:23]
	v_mfma_f32_16x16x32_bf16 v[16:19], v[222:225], v[198:201], v[16:19]
	v_mfma_f32_16x16x32_bf16 v[0:3], v[222:225], v[206:209], v[0:3]
	v_mfma_f32_16x16x32_bf16 v[4:7], v[214:217], v[206:209], v[4:7]
	s_add_u32 s14, s14, 0x100
	s_addc_u32 s15, s15, 0
	s_add_u32 s77, s77, 0x100
	s_addc_u32 s78, s78, 0
	s_cmp_ge_i32 s79, s25
	s_mov_b32 s16, s79
	s_barrier
	s_cbranch_scc0 .LBB0_1445

; #define PG8_STAGE(bufoff, gbase, voff) do { _Pragma("unroll") for (int _i = 0; _i < 2; ++_i) \
;         __builtin_amdgcn_global_load_lds((const unsigned*)((const char*)(gbase) + (voff)[_i]), (LAS unsigned*)(lds + (bufoff) + ldsw + _i * 8192), 16, 0, 0); } while (0)
; #define PG8_LDA(dst, b, h) do { _Pragma("unroll") for (int m = 0; m < 4; ++m) _Pragma("unroll") for (int k = 0; k < 2; ++k) dst[m][k] = *(const LAS bf16x8*)(lds + PG8_SA(b, h) + aoff + m * 2048 + k * 1024); } while (0)
; #define PG8_LDB(dst, b, h) do { _Pragma("unroll") for (int n = 0; n < 2; ++n) _Pragma("unroll") for (int k = 0; k < 2; ++k) dst[n][k] = *(const LAS bf16x8*)(lds + PG8_SB(b, h) + boff + n * 2048 + k * 1024); } while (0)
; #define PG8_MMA(ai, bj, At, Bt) do { __builtin_amdgcn_s_setprio(1); _Pragma("unroll") for (int m = 0; m < 4; ++m) _Pragma("unroll") for (int n = 0; n < 2; ++n) _Pragma("unroll") for (int k = 0; k < 2; ++k) \
;         acc[ai][bj][m][n] = __builtin_amdgcn_mfma_f32_16x16x32_bf16(Bt[n][k], At[m][k], acc[ai][bj][m][n], 0, 0, 0); __builtin_amdgcn_s_setprio(0); } while (0)
; #define PG8_WAIT_L(n) asm volatile("s_waitcnt lgkmcnt(" #n ")" ::: "memory")
; #define PG8_BAR __builtin_amdgcn_s_barrier()
; #define PG8_SCHED __builtin_amdgcn_sched_barrier(0)
; template <class Epi>
; DEVI void gemm_phase(LAS unsigned char* lds, const bf16_t* gA, const bf16_t* gBt, const int lda, const int ldb, const int K, const StaticOrder S_, const Epi E) {
;     ...
;             PG8_LDB(B0, 0, 0); PG8_SCHED; PG8_LDA(At, 0, 0); PG8_STAGE(PG8_SA(1, 1), a1 + hstepA, voffA);
;             PG8_WAIT_L(8); PG8_BAR; PG8_WAIT_L(0); PG8_MMA(0, 0, At, B0); PG8_BAR; PG8_SCHED;
;             PG8_LDB(B1, 0, 1); PG8_STAGE(PG8_SB(0, 0), b2, voffB);
;             PG8_BAR; PG8_WAIT_L(0); PG8_MMA(0, 1, At, B1); PG8_BAR;
;             PG8_LDA(At, 0, 1); PG8_STAGE(PG8_SA(0, 0), a2, voffA);
;             PG8_BAR; PG8_WAIT_L(0); PG8_MMA(1, 0, At, B0); PG8_BAR; PG8_SCHED;
.LBB0_1574:
	ds_read_b128 v[128:131], v201
	ds_read_b128 v[132:135], v201 offset:1024
	ds_read_b128 v[136:139], v201 offset:2048
	ds_read_b128 v[140:143], v201 offset:3072
	s_add_i32 s75, s16, 2
	s_add_u32 s40, s14, 0x80
	s_addc_u32 s17, s15, 0
	s_cmp_eq_u32 s19, s16
	s_cselect_b32 s16, s12, s40
	s_cselect_b32 s17, s13, s17
	s_cselect_b32 s41, s43, s71
	s_cselect_b32 s40, s42, s70
	v_lshl_add_u64 v[164:165], s[14:15], 0, v[174:175]
	s_add_i32 m0, s74, 0xc000
	ds_read_b128 v[144:147], v202
	ds_read_b128 v[148:151], v202 offset:1024
	ds_read_b128 v[152:155], v202 offset:2048
	ds_read_b128 v[156:159], v202 offset:3072
	ds_read_b128 v[160:163], v202 offset:4096
	ds_read_b128 v[180:183], v202 offset:5120
	ds_read_b128 v[184:187], v202 offset:6144
	ds_read_b128 v[188:191], v202 offset:7168
	global_load_lds_dwordx4 v[164:165], off
	v_lshl_add_u64 v[164:165], s[14:15], 0, v[176:177]
	s_add_i32 m0, s74, 0xe000
	s_nop 0
	global_load_lds_dwordx4 v[164:165], off
	s_waitcnt lgkmcnt(8)
	s_barrier
	s_waitcnt lgkmcnt(0)
	s_waitcnt lgkmcnt(0)
	v_mfma_f32_16x16x32_bf16 v[124:127], v[128:131], v[144:147], v[124:127]
	v_mfma_f32_16x16x32_bf16 v[120:123], v[136:139], v[144:147], v[120:123]
	v_mfma_f32_16x16x32_bf16 v[104:107], v[136:139], v[152:155], v[104:107]
	v_mfma_f32_16x16x32_bf16 v[108:111], v[128:131], v[152:155], v[108:111]
	v_mfma_f32_16x16x32_bf16 v[92:95], v[128:131], v[160:163], v[92:95]
	v_mfma_f32_16x16x32_bf16 v[88:91], v[136:139], v[160:163], v[88:91]
	v_mfma_f32_16x16x32_bf16 v[72:75], v[136:139], v[184:187], v[72:75]
	v_mfma_f32_16x16x32_bf16 v[76:79], v[128:131], v[184:187], v[76:79]
	v_mfma_f32_16x16x32_bf16 v[124:127], v[132:135], v[148:151], v[124:127]
	v_mfma_f32_16x16x32_bf16 v[120:123], v[140:143], v[148:151], v[120:123]
	v_mfma_f32_16x16x32_bf16 v[104:107], v[140:143], v[156:159], v[104:107]
	v_mfma_f32_16x16x32_bf16 v[108:111], v[132:135], v[156:159], v[108:111]
	v_mfma_f32_16x16x32_bf16 v[92:95], v[132:135], v[180:183], v[92:95]
	v_mfma_f32_16x16x32_bf16 v[88:91], v[140:143], v[180:183], v[88:91]
	v_mfma_f32_16x16x32_bf16 v[72:75], v[140:143], v[188:191], v[72:75]
	v_mfma_f32_16x16x32_bf16 v[76:79], v[132:135], v[188:191], v[76:79]
	s_barrier
	s_add_i32 s76, s29, s20
	v_lshl_add_u64 v[164:165], s[40:41], 0, v[168:169]
	s_mov_b32 m0, s76
	ds_read_b128 v[192:195], v203
	ds_read_b128 v[206:209], v203 offset:1024
	ds_read_b128 v[210:213], v203 offset:2048
	ds_read_b128 v[214:217], v203 offset:3072
	global_load_lds_dwordx4 v[164:165], off
	v_lshl_add_u64 v[218:219], s[40:41], 0, v[172:173]
	s_add_i32 m0, s76, 0x2000
	s_nop 0
	global_load_lds_dwordx4 v[218:219], off
	s_barrier
	s_waitcnt lgkmcnt(0)
	s_waitcnt lgkmcnt(0)
	v_mfma_f32_16x16x32_bf16 v[116:119], v[192:195], v[144:147], v[116:119]
	v_mfma_f32_16x16x32_bf16 v[112:115], v[210:213], v[144:147], v[112:115]
	v_mfma_f32_16x16x32_bf16 v[96:99], v[210:213], v[152:155], v[96:99]
	v_mfma_f32_16x16x32_bf16 v[100:103], v[192:195], v[152:155], v[100:103]
	v_mfma_f32_16x16x32_bf16 v[84:87], v[192:195], v[160:163], v[84:87]
	v_mfma_f32_16x16x32_bf16 v[80:83], v[210:213], v[160:163], v[80:83]
	v_mfma_f32_16x16x32_bf16 v[64:67], v[210:213], v[184:187], v[64:67]
	v_mfma_f32_16x16x32_bf16 v[68:71], v[192:195], v[184:187], v[68:71]
	v_mfma_f32_16x16x32_bf16 v[116:119], v[206:209], v[148:151], v[116:119]
	v_mfma_f32_16x16x32_bf16 v[112:115], v[214:217], v[148:151], v[112:115]
	v_mfma_f32_16x16x32_bf16 v[96:99], v[214:217], v[156:159], v[96:99]
	v_mfma_f32_16x16x32_bf16 v[100:103], v[206:209], v[156:159], v[100:103]
	v_mfma_f32_16x16x32_bf16 v[84:87], v[206:209], v[180:183], v[84:87]
	v_mfma_f32_16x16x32_bf16 v[80:83], v[214:217], v[180:183], v[80:83]
	v_mfma_f32_16x16x32_bf16 v[64:67], v[214:217], v[188:191], v[64:67]
	v_mfma_f32_16x16x32_bf16 v[68:71], v[206:209], v[188:191], v[68:71]
	s_mov_b32 m0, s74
	v_lshl_add_u64 v[220:221], s[16:17], 0, v[166:167]
	s_barrier
	ds_read_b128 v[144:147], v202 offset:16384
	ds_read_b128 v[148:151], v202 offset:17408
	ds_read_b128 v[152:155], v202 offset:18432
	ds_read_b128 v[156:159], v202 offset:19456
	ds_read_b128 v[160:163], v202 offset:20480
	ds_read_b128 v[180:183], v202 offset:21504
	ds_read_b128 v[184:187], v202 offset:22528
	ds_read_b128 v[188:191], v202 offset:23552
	global_load_lds_dwordx4 v[220:221], off
	v_lshl_add_u64 v[222:223], s[16:17], 0, v[170:171]
	s_mov_b32 m0, s22
	s_nop 0
	global_load_lds_dwordx4 v[222:223], off
	s_barrier
	s_waitcnt lgkmcnt(0)
	s_waitcnt lgkmcnt(0)
	v_mfma_f32_16x16x32_bf16 v[60:63], v[128:131], v[144:147], v[60:63]
	v_mfma_f32_16x16x32_bf16 v[56:59], v[136:139], v[144:147], v[56:59]
	v_mfma_f32_16x16x32_bf16 v[40:43], v[136:139], v[152:155], v[40:43]
	v_mfma_f32_16x16x32_bf16 v[44:47], v[128:131], v[152:155], v[44:47]
	v_mfma_f32_16x16x32_bf16 v[28:31], v[128:131], v[160:163], v[28:31]
	v_mfma_f32_16x16x32_bf16 v[24:27], v[136:139], v[160:163], v[24:27]
	v_mfma_f32_16x16x32_bf16 v[8:11], v[136:139], v[184:187], v[8:11]
	v_mfma_f32_16x16x32_bf16 v[12:15], v[128:131], v[184:187], v[12:15]
	v_mfma_f32_16x16x32_bf16 v[60:63], v[132:135], v[148:151], v[60:63]
	v_mfma_f32_16x16x32_bf16 v[56:59], v[140:143], v[148:151], v[56:59]
	v_mfma_f32_16x16x32_bf16 v[40:43], v[140:143], v[156:159], v[40:43]
	v_mfma_f32_16x16x32_bf16 v[44:47], v[132:135], v[156:159], v[44:47]
	v_mfma_f32_16x16x32_bf16 v[28:31], v[132:135], v[180:183], v[28:31]
	v_mfma_f32_16x16x32_bf16 v[24:27], v[140:143], v[180:183], v[24:27]
	v_mfma_f32_16x16x32_bf16 v[8:11], v[140:143], v[188:191], v[8:11]
	v_mfma_f32_16x16x32_bf16 v[12:15], v[132:135], v[188:191], v[12:15]
	s_barrier
; #define PG8_STAGE(bufoff, gbase, voff) do { _Pragma("unroll") for (int _i = 0; _i < 2; ++_i) \
;         __builtin_amdgcn_global_load_lds((const unsigned*)((const char*)(gbase) + (voff)[_i]), (LAS unsigned*)(lds + (bufoff) + ldsw + _i * 8192), 16, 0, 0); } while (0)
; #define PG8_LDA(dst, b, h) do { _Pragma("unroll") for (int m = 0; m < 4; ++m) _Pragma("unroll") for (int k = 0; k < 2; ++k) dst[m][k] = *(const LAS bf16x8*)(lds + PG8_SA(b, h) + aoff + m * 2048 + k * 1024); } while (0)
; #define PG8_LDB(dst, b, h) do { _Pragma("unroll") for (int n = 0; n < 2; ++n) _Pragma("unroll") for (int k = 0; k < 2; ++k) dst[n][k] = *(const LAS bf16x8*)(lds + PG8_SB(b, h) + boff + n * 2048 + k * 1024); } while (0)
; #define PG8_MMA(ai, bj, At, Bt) do { __builtin_amdgcn_s_setprio(1); _Pragma("unroll") for (int m = 0; m < 4; ++m) _Pragma("unroll") for (int n = 0; n < 2; ++n) _Pragma("unroll") for (int k = 0; k < 2; ++k) \
;         acc[ai][bj][m][n] = __builtin_amdgcn_mfma_f32_16x16x32_bf16(Bt[n][k], At[m][k], acc[ai][bj][m][n], 0, 0, 0); __builtin_amdgcn_s_setprio(0); } while (0)
; #define PG8_WAIT_V(n) asm volatile("s_waitcnt vmcnt(" #n ")" ::: "memory")
; #define PG8_WAIT_L(n) asm volatile("s_waitcnt lgkmcnt(" #n ")" ::: "memory")
; #define PG8_BAR __builtin_amdgcn_s_barrier()
; #define PG8_SCHED __builtin_amdgcn_sched_barrier(0)
; template <class Epi>
; DEVI void gemm_phase(LAS unsigned char* lds, const bf16_t* gA, const bf16_t* gBt, const int lda, const int ldb, const int K, const StaticOrder S_, const Epi E) {
;     ...
;             PG8_STAGE(PG8_SB(0, 1), b2 + hstepB, voffB);
;             PG8_WAIT_V(6); PG8_BAR; PG8_MMA(1, 1, At, B1); PG8_BAR;
;             PG8_LDB(B0, 1, 0); PG8_SCHED; PG8_LDA(At, 1, 0); PG8_STAGE(PG8_SA(0, 1), a2 + hstepA, voffA);
;             PG8_WAIT_L(8); PG8_BAR; PG8_WAIT_L(0); PG8_MMA(0, 0, At, B0); PG8_BAR; PG8_SCHED;
;             PG8_LDB(B1, 1, 1); PG8_STAGE(PG8_SB(1, 0), b3, voffB);
	s_add_u32 s40, s40, s2
	s_addc_u32 s41, s41, s3
	s_add_i32 s76, s50, s20
	v_lshl_add_u64 v[224:225], s[40:41], 0, v[168:169]
	s_mov_b32 m0, s76
	v_lshl_add_u64 v[226:227], s[40:41], 0, v[172:173]
	global_load_lds_dwordx4 v[224:225], off
	s_add_i32 m0, s76, 0x2000
	s_nop 0
	global_load_lds_dwordx4 v[226:227], off
	s_waitcnt vmcnt(6)
	s_barrier
	v_mfma_f32_16x16x32_bf16 v[52:55], v[192:195], v[144:147], v[52:55]
	v_mfma_f32_16x16x32_bf16 v[48:51], v[210:213], v[144:147], v[48:51]
	v_mfma_f32_16x16x32_bf16 v[32:35], v[210:213], v[152:155], v[32:35]
	v_mfma_f32_16x16x32_bf16 v[36:39], v[192:195], v[152:155], v[36:39]
	v_mfma_f32_16x16x32_bf16 v[20:23], v[192:195], v[160:163], v[20:23]
	v_mfma_f32_16x16x32_bf16 v[16:19], v[210:213], v[160:163], v[16:19]
	v_mfma_f32_16x16x32_bf16 v[0:3], v[210:213], v[184:187], v[0:3]
	v_mfma_f32_16x16x32_bf16 v[4:7], v[192:195], v[184:187], v[4:7]
	v_mfma_f32_16x16x32_bf16 v[52:55], v[206:209], v[148:151], v[52:55]
	v_mfma_f32_16x16x32_bf16 v[48:51], v[214:217], v[148:151], v[48:51]
	v_mfma_f32_16x16x32_bf16 v[32:35], v[214:217], v[156:159], v[32:35]
	v_mfma_f32_16x16x32_bf16 v[36:39], v[206:209], v[156:159], v[36:39]
	v_mfma_f32_16x16x32_bf16 v[20:23], v[206:209], v[180:183], v[20:23]
	v_mfma_f32_16x16x32_bf16 v[16:19], v[214:217], v[180:183], v[16:19]
	v_mfma_f32_16x16x32_bf16 v[0:3], v[214:217], v[188:191], v[0:3]
	v_mfma_f32_16x16x32_bf16 v[4:7], v[206:209], v[188:191], v[4:7]
	s_add_i32 s40, 0, 0x18000
	v_add_u32_e32 v140, s40, v199
	s_barrier
	ds_read_b128 v[128:131], v140
	ds_read_b128 v[132:135], v140 offset:1024
	ds_read_b128 v[136:139], v140 offset:2048
	ds_read_b128 v[140:143], v140 offset:3072
	s_add_u32 s16, s16, s0
	s_addc_u32 s17, s17, s1
	s_mov_b32 m0, s23
	v_lshl_add_u64 v[192:193], s[16:17], 0, v[166:167]
	ds_read_b128 v[144:147], v202 offset:32768
	ds_read_b128 v[148:151], v202 offset:33792
	ds_read_b128 v[152:155], v202 offset:34816
	ds_read_b128 v[156:159], v202 offset:35840
	ds_read_b128 v[160:163], v202 offset:36864
	ds_read_b128 v[180:183], v202 offset:37888
	ds_read_b128 v[184:187], v202 offset:38912
	ds_read_b128 v[188:191], v202 offset:39936
	global_load_lds_dwordx4 v[192:193], off
	v_lshl_add_u64 v[192:193], s[16:17], 0, v[170:171]
	s_mov_b32 m0, s24
	s_nop 0
	global_load_lds_dwordx4 v[192:193], off
	s_waitcnt lgkmcnt(8)
	s_barrier
	s_waitcnt lgkmcnt(0)
	s_waitcnt lgkmcnt(0)
	v_mfma_f32_16x16x32_bf16 v[124:127], v[128:131], v[144:147], v[124:127]
	v_mfma_f32_16x16x32_bf16 v[120:123], v[136:139], v[144:147], v[120:123]
	v_mfma_f32_16x16x32_bf16 v[104:107], v[136:139], v[152:155], v[104:107]
	v_mfma_f32_16x16x32_bf16 v[108:111], v[128:131], v[152:155], v[108:111]
	v_mfma_f32_16x16x32_bf16 v[92:95], v[128:131], v[160:163], v[92:95]
	v_mfma_f32_16x16x32_bf16 v[88:91], v[136:139], v[160:163], v[88:91]
	v_mfma_f32_16x16x32_bf16 v[72:75], v[136:139], v[184:187], v[72:75]
	v_mfma_f32_16x16x32_bf16 v[76:79], v[128:131], v[184:187], v[76:79]
	v_mfma_f32_16x16x32_bf16 v[124:127], v[132:135], v[148:151], v[124:127]
	v_mfma_f32_16x16x32_bf16 v[120:123], v[140:143], v[148:151], v[120:123]
	v_mfma_f32_16x16x32_bf16 v[104:107], v[140:143], v[156:159], v[104:107]
	v_mfma_f32_16x16x32_bf16 v[108:111], v[132:135], v[156:159], v[108:111]
	v_mfma_f32_16x16x32_bf16 v[92:95], v[132:135], v[180:183], v[92:95]
	v_mfma_f32_16x16x32_bf16 v[88:91], v[140:143], v[180:183], v[88:91]
	v_mfma_f32_16x16x32_bf16 v[72:75], v[140:143], v[188:191], v[72:75]
	v_mfma_f32_16x16x32_bf16 v[76:79], v[132:135], v[188:191], v[76:79]
	s_barrier
	s_add_i32 s16, 0, 0x1c000
	s_add_i32 s17, s40, s20
	v_add_u32_e32 v205, s16, v199
	v_lshl_add_u64 v[164:165], v[164:165], 0, s[8:9]
	s_mov_b32 m0, s17
	ds_read_b128 v[192:195], v205
	ds_read_b128 v[206:209], v205 offset:1024
	ds_read_b128 v[210:213], v205 offset:2048
	ds_read_b128 v[214:217], v205 offset:3072
	global_load_lds_dwordx4 v[164:165], off
	v_lshl_add_u64 v[164:165], v[218:219], 0, s[8:9]
	s_add_i32 m0, s17, 0x2000
	s_nop 0
	global_load_lds_dwordx4 v[164:165], off
	s_barrier
; #define PG8_STAGE(bufoff, gbase, voff) do { _Pragma("unroll") for (int _i = 0; _i < 2; ++_i) \
;         __builtin_amdgcn_global_load_lds((const unsigned*)((const char*)(gbase) + (voff)[_i]), (LAS unsigned*)(lds + (bufoff) + ldsw + _i * 8192), 16, 0, 0); } while (0)
; #define PG8_LDA(dst, b, h) do { _Pragma("unroll") for (int m = 0; m < 4; ++m) _Pragma("unroll") for (int k = 0; k < 2; ++k) dst[m][k] = *(const LAS bf16x8*)(lds + PG8_SA(b, h) + aoff + m * 2048 + k * 1024); } while (0)
; #define PG8_MMA(ai, bj, At, Bt) do { __builtin_amdgcn_s_setprio(1); _Pragma("unroll") for (int m = 0; m < 4; ++m) _Pragma("unroll") for (int n = 0; n < 2; ++n) _Pragma("unroll") for (int k = 0; k < 2; ++k) \
;         acc[ai][bj][m][n] = __builtin_amdgcn_mfma_f32_16x16x32_bf16(Bt[n][k], At[m][k], acc[ai][bj][m][n], 0, 0, 0); __builtin_amdgcn_s_setprio(0); } while (0)
; #define PG8_WAIT_V(n) asm volatile("s_waitcnt vmcnt(" #n ")" ::: "memory")
; #define PG8_WAIT_L(n) asm volatile("s_waitcnt lgkmcnt(" #n ")" ::: "memory")
; #define PG8_BAR __builtin_amdgcn_s_barrier()
; #define PG8_SCHED __builtin_amdgcn_sched_barrier(0)
; template <class Epi>
; DEVI void gemm_phase(LAS unsigned char* lds, const bf16_t* gA, const bf16_t* gBt, const int lda, const int ldb, const int K, const StaticOrder S_, const Epi E) {
;     ...
;             PG8_BAR; PG8_WAIT_L(0); PG8_MMA(0, 1, At, B1); PG8_BAR;
;             PG8_LDA(At, 1, 1); PG8_STAGE(PG8_SA(1, 0), a3, voffA);
;             PG8_BAR; PG8_WAIT_L(0); PG8_MMA(1, 0, At, B0); PG8_BAR; PG8_SCHED;
;             PG8_STAGE(PG8_SB(1, 1), b3 + hstepB, voffB);
;             PG8_WAIT_V(6); PG8_BAR; PG8_MMA(1, 1, At, B1); PG8_BAR;
	s_waitcnt lgkmcnt(0)
	s_waitcnt lgkmcnt(0)
	v_mfma_f32_16x16x32_bf16 v[116:119], v[192:195], v[144:147], v[116:119]
	v_mfma_f32_16x16x32_bf16 v[112:115], v[210:213], v[144:147], v[112:115]
	v_mfma_f32_16x16x32_bf16 v[96:99], v[210:213], v[152:155], v[96:99]
	v_mfma_f32_16x16x32_bf16 v[100:103], v[192:195], v[152:155], v[100:103]
	v_mfma_f32_16x16x32_bf16 v[84:87], v[192:195], v[160:163], v[84:87]
	v_mfma_f32_16x16x32_bf16 v[80:83], v[210:213], v[160:163], v[80:83]
	v_mfma_f32_16x16x32_bf16 v[64:67], v[210:213], v[184:187], v[64:67]
	v_mfma_f32_16x16x32_bf16 v[68:71], v[192:195], v[184:187], v[68:71]
	v_mfma_f32_16x16x32_bf16 v[116:119], v[206:209], v[148:151], v[116:119]
	v_mfma_f32_16x16x32_bf16 v[112:115], v[214:217], v[148:151], v[112:115]
	v_mfma_f32_16x16x32_bf16 v[96:99], v[214:217], v[156:159], v[96:99]
	v_mfma_f32_16x16x32_bf16 v[100:103], v[206:209], v[156:159], v[100:103]
	v_mfma_f32_16x16x32_bf16 v[84:87], v[206:209], v[180:183], v[84:87]
	v_mfma_f32_16x16x32_bf16 v[80:83], v[214:217], v[180:183], v[80:83]
	v_mfma_f32_16x16x32_bf16 v[64:67], v[214:217], v[188:191], v[64:67]
	v_mfma_f32_16x16x32_bf16 v[68:71], v[206:209], v[188:191], v[68:71]
	s_mov_b32 m0, s26
	v_lshl_add_u64 v[164:165], v[220:221], 0, s[8:9]
	s_barrier
	ds_read_b128 v[144:147], v202 offset:49152
	ds_read_b128 v[148:151], v202 offset:50176
	ds_read_b128 v[152:155], v202 offset:51200
	ds_read_b128 v[156:159], v202 offset:52224
	ds_read_b128 v[160:163], v202 offset:53248
	ds_read_b128 v[180:183], v202 offset:54272
	ds_read_b128 v[184:187], v202 offset:55296
	ds_read_b128 v[188:191], v202 offset:56320
	global_load_lds_dwordx4 v[164:165], off
	v_lshl_add_u64 v[164:165], v[222:223], 0, s[8:9]
	s_mov_b32 m0, s27
	s_nop 0
	global_load_lds_dwordx4 v[164:165], off
	s_barrier
	s_waitcnt lgkmcnt(0)
	s_waitcnt lgkmcnt(0)
	v_mfma_f32_16x16x32_bf16 v[60:63], v[128:131], v[144:147], v[60:63]
	v_mfma_f32_16x16x32_bf16 v[56:59], v[136:139], v[144:147], v[56:59]
	v_mfma_f32_16x16x32_bf16 v[40:43], v[136:139], v[152:155], v[40:43]
	v_mfma_f32_16x16x32_bf16 v[44:47], v[128:131], v[152:155], v[44:47]
	v_mfma_f32_16x16x32_bf16 v[28:31], v[128:131], v[160:163], v[28:31]
	v_mfma_f32_16x16x32_bf16 v[24:27], v[136:139], v[160:163], v[24:27]
	v_mfma_f32_16x16x32_bf16 v[8:11], v[136:139], v[184:187], v[8:11]
	v_mfma_f32_16x16x32_bf16 v[12:15], v[128:131], v[184:187], v[12:15]
	v_mfma_f32_16x16x32_bf16 v[60:63], v[132:135], v[148:151], v[60:63]
	v_mfma_f32_16x16x32_bf16 v[56:59], v[140:143], v[148:151], v[56:59]
	v_mfma_f32_16x16x32_bf16 v[40:43], v[140:143], v[156:159], v[40:43]
	v_mfma_f32_16x16x32_bf16 v[44:47], v[132:135], v[156:159], v[44:47]
	v_mfma_f32_16x16x32_bf16 v[28:31], v[132:135], v[180:183], v[28:31]
	v_mfma_f32_16x16x32_bf16 v[24:27], v[140:143], v[180:183], v[24:27]
	v_mfma_f32_16x16x32_bf16 v[8:11], v[140:143], v[188:191], v[8:11]
	v_mfma_f32_16x16x32_bf16 v[12:15], v[132:135], v[188:191], v[12:15]
	s_barrier
	s_add_i32 s16, s16, s20
	v_lshl_add_u64 v[128:129], v[224:225], 0, s[8:9]
	s_mov_b32 m0, s16
	s_nop 0
	global_load_lds_dwordx4 v[128:129], off
	v_lshl_add_u64 v[128:129], v[226:227], 0, s[8:9]
	s_add_i32 m0, s16, 0x2000
	s_nop 0
	global_load_lds_dwordx4 v[128:129], off
	s_waitcnt vmcnt(6)
	s_barrier
	v_mfma_f32_16x16x32_bf16 v[52:55], v[192:195], v[144:147], v[52:55]
	v_mfma_f32_16x16x32_bf16 v[48:51], v[210:213], v[144:147], v[48:51]
	v_mfma_f32_16x16x32_bf16 v[32:35], v[210:213], v[152:155], v[32:35]
	v_mfma_f32_16x16x32_bf16 v[36:39], v[192:195], v[152:155], v[36:39]
	v_mfma_f32_16x16x32_bf16 v[20:23], v[192:195], v[160:163], v[20:23]
	v_mfma_f32_16x16x32_bf16 v[16:19], v[210:213], v[160:163], v[16:19]
	v_mfma_f32_16x16x32_bf16 v[0:3], v[210:213], v[184:187], v[0:3]
	v_mfma_f32_16x16x32_bf16 v[4:7], v[192:195], v[184:187], v[4:7]
	v_mfma_f32_16x16x32_bf16 v[52:55], v[206:209], v[148:151], v[52:55]
	v_mfma_f32_16x16x32_bf16 v[48:51], v[214:217], v[148:151], v[48:51]
	v_mfma_f32_16x16x32_bf16 v[32:35], v[214:217], v[156:159], v[32:35]
	v_mfma_f32_16x16x32_bf16 v[36:39], v[206:209], v[156:159], v[36:39]
	v_mfma_f32_16x16x32_bf16 v[20:23], v[206:209], v[180:183], v[20:23]
	v_mfma_f32_16x16x32_bf16 v[16:19], v[214:217], v[180:183], v[16:19]
	v_mfma_f32_16x16x32_bf16 v[0:3], v[214:217], v[188:191], v[0:3]
	v_mfma_f32_16x16x32_bf16 v[4:7], v[206:209], v[188:191], v[4:7]
	s_add_u32 s14, s14, 0x100
	s_addc_u32 s15, s15, 0
	s_add_u32 s70, s70, 0x100
	s_addc_u32 s71, s71, 0
	s_cmp_ge_i32 s75, s25
	s_mov_b32 s16, s75
	s_barrier
	s_cbranch_scc0 .LBB0_1574
	v_readlane_b32 s76, v238, 50
	v_readlane_b32 s77, v238, 51
	v_readlane_b32 s78, v238, 52
	v_readlane_b32 s79, v238, 53
	v_readlane_b32 s80, v238, 54
	v_readlane_b32 s81, v238, 55
	v_readlane_b32 s82, v238, 56
	v_readlane_b32 s83, v238, 57

; #define PG8_STAGE(bufoff, gbase, voff) do { _Pragma("unroll") for (int _i = 0; _i < 2; ++_i) \
;         __builtin_amdgcn_global_load_lds((const unsigned*)((const char*)(gbase) + (voff)[_i]), (LAS unsigned*)(lds + (bufoff) + ldsw + _i * 8192), 16, 0, 0); } while (0)
; #define PG8_LDA(dst, b, h) do { _Pragma("unroll") for (int m = 0; m < 4; ++m) _Pragma("unroll") for (int k = 0; k < 2; ++k) dst[m][k] = *(const LAS bf16x8*)(lds + PG8_SA(b, h) + aoff + m * 2048 + k * 1024); } while (0)
; #define PG8_LDB(dst, b, h) do { _Pragma("unroll") for (int n = 0; n < 2; ++n) _Pragma("unroll") for (int k = 0; k < 2; ++k) dst[n][k] = *(const LAS bf16x8*)(lds + PG8_SB(b, h) + boff + n * 2048 + k * 1024); } while (0)
; #define PG8_MMA(ai, bj, At, Bt) do { __builtin_amdgcn_s_setprio(1); _Pragma("unroll") for (int m = 0; m < 4; ++m) _Pragma("unroll") for (int n = 0; n < 2; ++n) _Pragma("unroll") for (int k = 0; k < 2; ++k) \
;         acc[ai][bj][m][n] = __builtin_amdgcn_mfma_f32_16x16x32_bf16(Bt[n][k], At[m][k], acc[ai][bj][m][n], 0, 0, 0); __builtin_amdgcn_s_setprio(0); } while (0)
; #define PG8_WAIT_L(n) asm volatile("s_waitcnt lgkmcnt(" #n ")" ::: "memory")
; #define PG8_BAR __builtin_amdgcn_s_barrier()
; #define PG8_SCHED __builtin_amdgcn_sched_barrier(0)
; template <class Epi>
; DEVI void gemm_phase(LAS unsigned char* lds, const bf16_t* gA, const bf16_t* gBt, const int lda, const int ldb, const int K, const StaticOrder S_, const Epi E) {
;     ...
;             PG8_LDB(B0, 0, 0); PG8_SCHED; PG8_LDA(At, 0, 0); PG8_STAGE(PG8_SA(1, 1), a1 + hstepA, voffA);
;             PG8_WAIT_L(8); PG8_BAR; PG8_WAIT_L(0); PG8_MMA(0, 0, At, B0); PG8_BAR; PG8_SCHED;
;             PG8_LDB(B1, 0, 1); PG8_STAGE(PG8_SB(0, 0), b2, voffB);
;             PG8_BAR; PG8_WAIT_L(0); PG8_MMA(0, 1, At, B1); PG8_BAR;
;             PG8_LDA(At, 0, 1); PG8_STAGE(PG8_SA(0, 0), a2, voffA);
;             PG8_BAR; PG8_WAIT_L(0); PG8_MMA(1, 0, At, B0); PG8_BAR; PG8_SCHED;
.LBB0_1848:
	ds_read_b128 v[128:131], v201
	ds_read_b128 v[132:135], v201 offset:1024
	ds_read_b128 v[136:139], v201 offset:2048
	ds_read_b128 v[140:143], v201 offset:3072
	s_add_i32 s64, s16, 2
	s_add_u32 s38, s14, 0x80
	s_addc_u32 s17, s15, 0
	s_cmp_eq_u32 s19, s16
	s_cselect_b32 s16, s12, s38
	s_cselect_b32 s17, s13, s17
	s_cselect_b32 s39, s41, s57
	s_cselect_b32 s38, s40, s56
	v_lshl_add_u64 v[164:165], s[14:15], 0, v[174:175]
	s_add_i32 m0, s61, 0xc000
	ds_read_b128 v[144:147], v202
	ds_read_b128 v[148:151], v202 offset:1024
	ds_read_b128 v[152:155], v202 offset:2048
	ds_read_b128 v[156:159], v202 offset:3072
	ds_read_b128 v[160:163], v202 offset:4096
	ds_read_b128 v[180:183], v202 offset:5120
	ds_read_b128 v[184:187], v202 offset:6144
	ds_read_b128 v[188:191], v202 offset:7168
	global_load_lds_dwordx4 v[164:165], off
	v_lshl_add_u64 v[164:165], s[14:15], 0, v[176:177]
	s_add_i32 m0, s61, 0xe000
	s_nop 0
	global_load_lds_dwordx4 v[164:165], off
	s_waitcnt lgkmcnt(8)
	s_barrier
	s_waitcnt lgkmcnt(0)
	s_waitcnt lgkmcnt(0)
	v_mfma_f32_16x16x32_bf16 v[124:127], v[128:131], v[144:147], v[124:127]
	v_mfma_f32_16x16x32_bf16 v[120:123], v[136:139], v[144:147], v[120:123]
	v_mfma_f32_16x16x32_bf16 v[104:107], v[136:139], v[152:155], v[104:107]
	v_mfma_f32_16x16x32_bf16 v[108:111], v[128:131], v[152:155], v[108:111]
	v_mfma_f32_16x16x32_bf16 v[92:95], v[128:131], v[160:163], v[92:95]
	v_mfma_f32_16x16x32_bf16 v[88:91], v[136:139], v[160:163], v[88:91]
	v_mfma_f32_16x16x32_bf16 v[72:75], v[136:139], v[184:187], v[72:75]
	v_mfma_f32_16x16x32_bf16 v[76:79], v[128:131], v[184:187], v[76:79]
	v_mfma_f32_16x16x32_bf16 v[124:127], v[132:135], v[148:151], v[124:127]
	v_mfma_f32_16x16x32_bf16 v[120:123], v[140:143], v[148:151], v[120:123]
	v_mfma_f32_16x16x32_bf16 v[104:107], v[140:143], v[156:159], v[104:107]
	v_mfma_f32_16x16x32_bf16 v[108:111], v[132:135], v[156:159], v[108:111]
	v_mfma_f32_16x16x32_bf16 v[92:95], v[132:135], v[180:183], v[92:95]
	v_mfma_f32_16x16x32_bf16 v[88:91], v[140:143], v[180:183], v[88:91]
	v_mfma_f32_16x16x32_bf16 v[72:75], v[140:143], v[188:191], v[72:75]
	v_mfma_f32_16x16x32_bf16 v[76:79], v[132:135], v[188:191], v[76:79]
	s_barrier
	s_add_i32 s65, s29, s20
	v_lshl_add_u64 v[164:165], s[38:39], 0, v[168:169]
	s_mov_b32 m0, s65
	ds_read_b128 v[192:195], v203
	ds_read_b128 v[206:209], v203 offset:1024
	ds_read_b128 v[210:213], v203 offset:2048
	ds_read_b128 v[214:217], v203 offset:3072
	global_load_lds_dwordx4 v[164:165], off
	v_lshl_add_u64 v[218:219], s[38:39], 0, v[172:173]
	s_add_i32 m0, s65, 0x2000
	s_nop 0
	global_load_lds_dwordx4 v[218:219], off
	s_barrier
	s_waitcnt lgkmcnt(0)
	s_waitcnt lgkmcnt(0)
	v_mfma_f32_16x16x32_bf16 v[116:119], v[192:195], v[144:147], v[116:119]
	v_mfma_f32_16x16x32_bf16 v[112:115], v[210:213], v[144:147], v[112:115]
	v_mfma_f32_16x16x32_bf16 v[96:99], v[210:213], v[152:155], v[96:99]
	v_mfma_f32_16x16x32_bf16 v[100:103], v[192:195], v[152:155], v[100:103]
	v_mfma_f32_16x16x32_bf16 v[84:87], v[192:195], v[160:163], v[84:87]
	v_mfma_f32_16x16x32_bf16 v[80:83], v[210:213], v[160:163], v[80:83]
	v_mfma_f32_16x16x32_bf16 v[64:67], v[210:213], v[184:187], v[64:67]
	v_mfma_f32_16x16x32_bf16 v[68:71], v[192:195], v[184:187], v[68:71]
	v_mfma_f32_16x16x32_bf16 v[116:119], v[206:209], v[148:151], v[116:119]
	v_mfma_f32_16x16x32_bf16 v[112:115], v[214:217], v[148:151], v[112:115]
	v_mfma_f32_16x16x32_bf16 v[96:99], v[214:217], v[156:159], v[96:99]
	v_mfma_f32_16x16x32_bf16 v[100:103], v[206:209], v[156:159], v[100:103]
	v_mfma_f32_16x16x32_bf16 v[84:87], v[206:209], v[180:183], v[84:87]
	v_mfma_f32_16x16x32_bf16 v[80:83], v[214:217], v[180:183], v[80:83]
	v_mfma_f32_16x16x32_bf16 v[64:67], v[214:217], v[188:191], v[64:67]
	v_mfma_f32_16x16x32_bf16 v[68:71], v[206:209], v[188:191], v[68:71]
	s_mov_b32 m0, s61
	v_lshl_add_u64 v[220:221], s[16:17], 0, v[166:167]
	s_barrier
	ds_read_b128 v[144:147], v202 offset:16384
	ds_read_b128 v[148:151], v202 offset:17408
	ds_read_b128 v[152:155], v202 offset:18432
	ds_read_b128 v[156:159], v202 offset:19456
	ds_read_b128 v[160:163], v202 offset:20480
	ds_read_b128 v[180:183], v202 offset:21504
	ds_read_b128 v[184:187], v202 offset:22528
	ds_read_b128 v[188:191], v202 offset:23552
	global_load_lds_dwordx4 v[220:221], off
	v_lshl_add_u64 v[222:223], s[16:17], 0, v[170:171]
	s_mov_b32 m0, s22
	s_nop 0
	global_load_lds_dwordx4 v[222:223], off
	s_barrier
	s_waitcnt lgkmcnt(0)
	s_waitcnt lgkmcnt(0)
	v_mfma_f32_16x16x32_bf16 v[60:63], v[128:131], v[144:147], v[60:63]
	v_mfma_f32_16x16x32_bf16 v[56:59], v[136:139], v[144:147], v[56:59]
	v_mfma_f32_16x16x32_bf16 v[40:43], v[136:139], v[152:155], v[40:43]
	v_mfma_f32_16x16x32_bf16 v[44:47], v[128:131], v[152:155], v[44:47]
	v_mfma_f32_16x16x32_bf16 v[28:31], v[128:131], v[160:163], v[28:31]
	v_mfma_f32_16x16x32_bf16 v[24:27], v[136:139], v[160:163], v[24:27]
	v_mfma_f32_16x16x32_bf16 v[8:11], v[136:139], v[184:187], v[8:11]
	v_mfma_f32_16x16x32_bf16 v[12:15], v[128:131], v[184:187], v[12:15]
	v_mfma_f32_16x16x32_bf16 v[60:63], v[132:135], v[148:151], v[60:63]
	v_mfma_f32_16x16x32_bf16 v[56:59], v[140:143], v[148:151], v[56:59]
	v_mfma_f32_16x16x32_bf16 v[40:43], v[140:143], v[156:159], v[40:43]
	v_mfma_f32_16x16x32_bf16 v[44:47], v[132:135], v[156:159], v[44:47]
	v_mfma_f32_16x16x32_bf16 v[28:31], v[132:135], v[180:183], v[28:31]
	v_mfma_f32_16x16x32_bf16 v[24:27], v[140:143], v[180:183], v[24:27]
	v_mfma_f32_16x16x32_bf16 v[8:11], v[140:143], v[188:191], v[8:11]
	v_mfma_f32_16x16x32_bf16 v[12:15], v[132:135], v[188:191], v[12:15]
	s_barrier
; #define PG8_STAGE(bufoff, gbase, voff) do { _Pragma("unroll") for (int _i = 0; _i < 2; ++_i) \
;         __builtin_amdgcn_global_load_lds((const unsigned*)((const char*)(gbase) + (voff)[_i]), (LAS unsigned*)(lds + (bufoff) + ldsw + _i * 8192), 16, 0, 0); } while (0)
; #define PG8_LDA(dst, b, h) do { _Pragma("unroll") for (int m = 0; m < 4; ++m) _Pragma("unroll") for (int k = 0; k < 2; ++k) dst[m][k] = *(const LAS bf16x8*)(lds + PG8_SA(b, h) + aoff + m * 2048 + k * 1024); } while (0)
; #define PG8_LDB(dst, b, h) do { _Pragma("unroll") for (int n = 0; n < 2; ++n) _Pragma("unroll") for (int k = 0; k < 2; ++k) dst[n][k] = *(const LAS bf16x8*)(lds + PG8_SB(b, h) + boff + n * 2048 + k * 1024); } while (0)
; #define PG8_MMA(ai, bj, At, Bt) do { __builtin_amdgcn_s_setprio(1); _Pragma("unroll") for (int m = 0; m < 4; ++m) _Pragma("unroll") for (int n = 0; n < 2; ++n) _Pragma("unroll") for (int k = 0; k < 2; ++k) \
;         acc[ai][bj][m][n] = __builtin_amdgcn_mfma_f32_16x16x32_bf16(Bt[n][k], At[m][k], acc[ai][bj][m][n], 0, 0, 0); __builtin_amdgcn_s_setprio(0); } while (0)
; #define PG8_WAIT_V(n) asm volatile("s_waitcnt vmcnt(" #n ")" ::: "memory")
; #define PG8_WAIT_L(n) asm volatile("s_waitcnt lgkmcnt(" #n ")" ::: "memory")
; #define PG8_BAR __builtin_amdgcn_s_barrier()
; #define PG8_SCHED __builtin_amdgcn_sched_barrier(0)
; template <class Epi>
; DEVI void gemm_phase(LAS unsigned char* lds, const bf16_t* gA, const bf16_t* gBt, const int lda, const int ldb, const int K, const StaticOrder S_, const Epi E) {
;     ...
;             PG8_STAGE(PG8_SB(0, 1), b2 + hstepB, voffB);
;             PG8_WAIT_V(6); PG8_BAR; PG8_MMA(1, 1, At, B1); PG8_BAR;
;             PG8_LDB(B0, 1, 0); PG8_SCHED; PG8_LDA(At, 1, 0); PG8_STAGE(PG8_SA(0, 1), a2 + hstepA, voffA);
;             PG8_WAIT_L(8); PG8_BAR; PG8_WAIT_L(0); PG8_MMA(0, 0, At, B0); PG8_BAR; PG8_SCHED;
;             PG8_LDB(B1, 1, 1); PG8_STAGE(PG8_SB(1, 0), b3, voffB);
	s_add_u32 s38, s38, s2
	s_addc_u32 s39, s39, s3
	s_add_i32 s65, s50, s20
	v_lshl_add_u64 v[224:225], s[38:39], 0, v[168:169]
	s_mov_b32 m0, s65
	v_lshl_add_u64 v[226:227], s[38:39], 0, v[172:173]
	global_load_lds_dwordx4 v[224:225], off
	s_add_i32 m0, s65, 0x2000
	s_nop 0
	global_load_lds_dwordx4 v[226:227], off
	s_waitcnt vmcnt(6)
	s_barrier
	v_mfma_f32_16x16x32_bf16 v[52:55], v[192:195], v[144:147], v[52:55]
	v_mfma_f32_16x16x32_bf16 v[48:51], v[210:213], v[144:147], v[48:51]
	v_mfma_f32_16x16x32_bf16 v[32:35], v[210:213], v[152:155], v[32:35]
	v_mfma_f32_16x16x32_bf16 v[36:39], v[192:195], v[152:155], v[36:39]
	v_mfma_f32_16x16x32_bf16 v[20:23], v[192:195], v[160:163], v[20:23]
	v_mfma_f32_16x16x32_bf16 v[16:19], v[210:213], v[160:163], v[16:19]
	v_mfma_f32_16x16x32_bf16 v[0:3], v[210:213], v[184:187], v[0:3]
	v_mfma_f32_16x16x32_bf16 v[4:7], v[192:195], v[184:187], v[4:7]
	v_mfma_f32_16x16x32_bf16 v[52:55], v[206:209], v[148:151], v[52:55]
	v_mfma_f32_16x16x32_bf16 v[48:51], v[214:217], v[148:151], v[48:51]
	v_mfma_f32_16x16x32_bf16 v[32:35], v[214:217], v[156:159], v[32:35]
	v_mfma_f32_16x16x32_bf16 v[36:39], v[206:209], v[156:159], v[36:39]
	v_mfma_f32_16x16x32_bf16 v[20:23], v[206:209], v[180:183], v[20:23]
	v_mfma_f32_16x16x32_bf16 v[16:19], v[214:217], v[180:183], v[16:19]
	v_mfma_f32_16x16x32_bf16 v[0:3], v[214:217], v[188:191], v[0:3]
	v_mfma_f32_16x16x32_bf16 v[4:7], v[206:209], v[188:191], v[4:7]
	s_add_i32 s38, 0, 0x18000
	v_add_u32_e32 v140, s38, v199
	s_barrier
	ds_read_b128 v[128:131], v140
	ds_read_b128 v[132:135], v140 offset:1024
	ds_read_b128 v[136:139], v140 offset:2048
	ds_read_b128 v[140:143], v140 offset:3072
	s_add_u32 s16, s16, s0
	s_addc_u32 s17, s17, s1
	s_mov_b32 m0, s23
	v_lshl_add_u64 v[192:193], s[16:17], 0, v[166:167]
	ds_read_b128 v[144:147], v202 offset:32768
	ds_read_b128 v[148:151], v202 offset:33792
	ds_read_b128 v[152:155], v202 offset:34816
	ds_read_b128 v[156:159], v202 offset:35840
	ds_read_b128 v[160:163], v202 offset:36864
	ds_read_b128 v[180:183], v202 offset:37888
	ds_read_b128 v[184:187], v202 offset:38912
	ds_read_b128 v[188:191], v202 offset:39936
	global_load_lds_dwordx4 v[192:193], off
	v_lshl_add_u64 v[192:193], s[16:17], 0, v[170:171]
	s_mov_b32 m0, s24
	s_nop 0
	global_load_lds_dwordx4 v[192:193], off
	s_waitcnt lgkmcnt(8)
	s_barrier
	s_waitcnt lgkmcnt(0)
	s_waitcnt lgkmcnt(0)
	v_mfma_f32_16x16x32_bf16 v[124:127], v[128:131], v[144:147], v[124:127]
	v_mfma_f32_16x16x32_bf16 v[120:123], v[136:139], v[144:147], v[120:123]
	v_mfma_f32_16x16x32_bf16 v[104:107], v[136:139], v[152:155], v[104:107]
	v_mfma_f32_16x16x32_bf16 v[108:111], v[128:131], v[152:155], v[108:111]
	v_mfma_f32_16x16x32_bf16 v[92:95], v[128:131], v[160:163], v[92:95]
	v_mfma_f32_16x16x32_bf16 v[88:91], v[136:139], v[160:163], v[88:91]
	v_mfma_f32_16x16x32_bf16 v[72:75], v[136:139], v[184:187], v[72:75]
	v_mfma_f32_16x16x32_bf16 v[76:79], v[128:131], v[184:187], v[76:79]
	v_mfma_f32_16x16x32_bf16 v[124:127], v[132:135], v[148:151], v[124:127]
	v_mfma_f32_16x16x32_bf16 v[120:123], v[140:143], v[148:151], v[120:123]
	v_mfma_f32_16x16x32_bf16 v[104:107], v[140:143], v[156:159], v[104:107]
	v_mfma_f32_16x16x32_bf16 v[108:111], v[132:135], v[156:159], v[108:111]
	v_mfma_f32_16x16x32_bf16 v[92:95], v[132:135], v[180:183], v[92:95]
	v_mfma_f32_16x16x32_bf16 v[88:91], v[140:143], v[180:183], v[88:91]
	v_mfma_f32_16x16x32_bf16 v[72:75], v[140:143], v[188:191], v[72:75]
	v_mfma_f32_16x16x32_bf16 v[76:79], v[132:135], v[188:191], v[76:79]
	s_barrier
	s_add_i32 s16, 0, 0x1c000
	s_add_i32 s17, s38, s20
	v_add_u32_e32 v205, s16, v199
	v_lshl_add_u64 v[164:165], v[164:165], 0, s[8:9]
	s_mov_b32 m0, s17
	ds_read_b128 v[192:195], v205
	ds_read_b128 v[206:209], v205 offset:1024
	ds_read_b128 v[210:213], v205 offset:2048
	ds_read_b128 v[214:217], v205 offset:3072
	global_load_lds_dwordx4 v[164:165], off
	v_lshl_add_u64 v[164:165], v[218:219], 0, s[8:9]
	s_add_i32 m0, s17, 0x2000
	s_nop 0
	global_load_lds_dwordx4 v[164:165], off
	s_barrier
; #define PG8_STAGE(bufoff, gbase, voff) do { _Pragma("unroll") for (int _i = 0; _i < 2; ++_i) \
;         __builtin_amdgcn_global_load_lds((const unsigned*)((const char*)(gbase) + (voff)[_i]), (LAS unsigned*)(lds + (bufoff) + ldsw + _i * 8192), 16, 0, 0); } while (0)
; #define PG8_LDA(dst, b, h) do { _Pragma("unroll") for (int m = 0; m < 4; ++m) _Pragma("unroll") for (int k = 0; k < 2; ++k) dst[m][k] = *(const LAS bf16x8*)(lds + PG8_SA(b, h) + aoff + m * 2048 + k * 1024); } while (0)
; #define PG8_MMA(ai, bj, At, Bt) do { __builtin_amdgcn_s_setprio(1); _Pragma("unroll") for (int m = 0; m < 4; ++m) _Pragma("unroll") for (int n = 0; n < 2; ++n) _Pragma("unroll") for (int k = 0; k < 2; ++k) \
;         acc[ai][bj][m][n] = __builtin_amdgcn_mfma_f32_16x16x32_bf16(Bt[n][k], At[m][k], acc[ai][bj][m][n], 0, 0, 0); __builtin_amdgcn_s_setprio(0); } while (0)
; #define PG8_WAIT_V(n) asm volatile("s_waitcnt vmcnt(" #n ")" ::: "memory")
; #define PG8_WAIT_L(n) asm volatile("s_waitcnt lgkmcnt(" #n ")" ::: "memory")
; #define PG8_BAR __builtin_amdgcn_s_barrier()
; #define PG8_SCHED __builtin_amdgcn_sched_barrier(0)
; template <class Epi>
; DEVI void gemm_phase(LAS unsigned char* lds, const bf16_t* gA, const bf16_t* gBt, const int lda, const int ldb, const int K, const StaticOrder S_, const Epi E) {
;     ...
;             PG8_BAR; PG8_WAIT_L(0); PG8_MMA(0, 1, At, B1); PG8_BAR;
;             PG8_LDA(At, 1, 1); PG8_STAGE(PG8_SA(1, 0), a3, voffA);
;             PG8_BAR; PG8_WAIT_L(0); PG8_MMA(1, 0, At, B0); PG8_BAR; PG8_SCHED;
;             PG8_STAGE(PG8_SB(1, 1), b3 + hstepB, voffB);
;             PG8_WAIT_V(6); PG8_BAR; PG8_MMA(1, 1, At, B1); PG8_BAR;
	s_waitcnt lgkmcnt(0)
	s_waitcnt lgkmcnt(0)
	v_mfma_f32_16x16x32_bf16 v[116:119], v[192:195], v[144:147], v[116:119]
	v_mfma_f32_16x16x32_bf16 v[112:115], v[210:213], v[144:147], v[112:115]
	v_mfma_f32_16x16x32_bf16 v[96:99], v[210:213], v[152:155], v[96:99]
	v_mfma_f32_16x16x32_bf16 v[100:103], v[192:195], v[152:155], v[100:103]
	v_mfma_f32_16x16x32_bf16 v[84:87], v[192:195], v[160:163], v[84:87]
	v_mfma_f32_16x16x32_bf16 v[80:83], v[210:213], v[160:163], v[80:83]
	v_mfma_f32_16x16x32_bf16 v[64:67], v[210:213], v[184:187], v[64:67]
	v_mfma_f32_16x16x32_bf16 v[68:71], v[192:195], v[184:187], v[68:71]
	v_mfma_f32_16x16x32_bf16 v[116:119], v[206:209], v[148:151], v[116:119]
	v_mfma_f32_16x16x32_bf16 v[112:115], v[214:217], v[148:151], v[112:115]
	v_mfma_f32_16x16x32_bf16 v[96:99], v[214:217], v[156:159], v[96:99]
	v_mfma_f32_16x16x32_bf16 v[100:103], v[206:209], v[156:159], v[100:103]
	v_mfma_f32_16x16x32_bf16 v[84:87], v[206:209], v[180:183], v[84:87]
	v_mfma_f32_16x16x32_bf16 v[80:83], v[214:217], v[180:183], v[80:83]
	v_mfma_f32_16x16x32_bf16 v[64:67], v[214:217], v[188:191], v[64:67]
	v_mfma_f32_16x16x32_bf16 v[68:71], v[206:209], v[188:191], v[68:71]
	s_mov_b32 m0, s26
	v_lshl_add_u64 v[164:165], v[220:221], 0, s[8:9]
	s_barrier
	ds_read_b128 v[144:147], v202 offset:49152
	ds_read_b128 v[148:151], v202 offset:50176
	ds_read_b128 v[152:155], v202 offset:51200
	ds_read_b128 v[156:159], v202 offset:52224
	ds_read_b128 v[160:163], v202 offset:53248
	ds_read_b128 v[180:183], v202 offset:54272
	ds_read_b128 v[184:187], v202 offset:55296
	ds_read_b128 v[188:191], v202 offset:56320
	global_load_lds_dwordx4 v[164:165], off
	v_lshl_add_u64 v[164:165], v[222:223], 0, s[8:9]
	s_mov_b32 m0, s27
	s_nop 0
	global_load_lds_dwordx4 v[164:165], off
	s_barrier
	s_waitcnt lgkmcnt(0)
	s_waitcnt lgkmcnt(0)
	v_mfma_f32_16x16x32_bf16 v[60:63], v[128:131], v[144:147], v[60:63]
	v_mfma_f32_16x16x32_bf16 v[56:59], v[136:139], v[144:147], v[56:59]
	v_mfma_f32_16x16x32_bf16 v[40:43], v[136:139], v[152:155], v[40:43]
	v_mfma_f32_16x16x32_bf16 v[44:47], v[128:131], v[152:155], v[44:47]
	v_mfma_f32_16x16x32_bf16 v[28:31], v[128:131], v[160:163], v[28:31]
	v_mfma_f32_16x16x32_bf16 v[24:27], v[136:139], v[160:163], v[24:27]
	v_mfma_f32_16x16x32_bf16 v[8:11], v[136:139], v[184:187], v[8:11]
	v_mfma_f32_16x16x32_bf16 v[12:15], v[128:131], v[184:187], v[12:15]
	v_mfma_f32_16x16x32_bf16 v[60:63], v[132:135], v[148:151], v[60:63]
	v_mfma_f32_16x16x32_bf16 v[56:59], v[140:143], v[148:151], v[56:59]
	v_mfma_f32_16x16x32_bf16 v[40:43], v[140:143], v[156:159], v[40:43]
	v_mfma_f32_16x16x32_bf16 v[44:47], v[132:135], v[156:159], v[44:47]
	v_mfma_f32_16x16x32_bf16 v[28:31], v[132:135], v[180:183], v[28:31]
	v_mfma_f32_16x16x32_bf16 v[24:27], v[140:143], v[180:183], v[24:27]
	v_mfma_f32_16x16x32_bf16 v[8:11], v[140:143], v[188:191], v[8:11]
	v_mfma_f32_16x16x32_bf16 v[12:15], v[132:135], v[188:191], v[12:15]
	s_barrier
	s_add_i32 s16, s16, s20
	v_lshl_add_u64 v[128:129], v[224:225], 0, s[8:9]
	s_mov_b32 m0, s16
	s_nop 0
	global_load_lds_dwordx4 v[128:129], off
	v_lshl_add_u64 v[128:129], v[226:227], 0, s[8:9]
	s_add_i32 m0, s16, 0x2000
	s_nop 0
	global_load_lds_dwordx4 v[128:129], off
	s_waitcnt vmcnt(6)
	s_barrier
	v_mfma_f32_16x16x32_bf16 v[52:55], v[192:195], v[144:147], v[52:55]
	v_mfma_f32_16x16x32_bf16 v[48:51], v[210:213], v[144:147], v[48:51]
	v_mfma_f32_16x16x32_bf16 v[32:35], v[210:213], v[152:155], v[32:35]
	v_mfma_f32_16x16x32_bf16 v[36:39], v[192:195], v[152:155], v[36:39]
	v_mfma_f32_16x16x32_bf16 v[20:23], v[192:195], v[160:163], v[20:23]
	v_mfma_f32_16x16x32_bf16 v[16:19], v[210:213], v[160:163], v[16:19]
	v_mfma_f32_16x16x32_bf16 v[0:3], v[210:213], v[184:187], v[0:3]
	v_mfma_f32_16x16x32_bf16 v[4:7], v[192:195], v[184:187], v[4:7]
	v_mfma_f32_16x16x32_bf16 v[52:55], v[206:209], v[148:151], v[52:55]
	v_mfma_f32_16x16x32_bf16 v[48:51], v[214:217], v[148:151], v[48:51]
	v_mfma_f32_16x16x32_bf16 v[32:35], v[214:217], v[156:159], v[32:35]
	v_mfma_f32_16x16x32_bf16 v[36:39], v[206:209], v[156:159], v[36:39]
	v_mfma_f32_16x16x32_bf16 v[20:23], v[206:209], v[180:183], v[20:23]
	v_mfma_f32_16x16x32_bf16 v[16:19], v[214:217], v[180:183], v[16:19]
	v_mfma_f32_16x16x32_bf16 v[0:3], v[214:217], v[188:191], v[0:3]
	v_mfma_f32_16x16x32_bf16 v[4:7], v[206:209], v[188:191], v[4:7]
	s_add_u32 s14, s14, 0x100
	s_addc_u32 s15, s15, 0
	s_add_u32 s56, s56, 0x100
	s_addc_u32 s57, s57, 0
	s_cmp_ge_i32 s64, s25
	s_mov_b32 s16, s64
	s_barrier
	s_cbranch_scc0 .LBB0_1848
	v_readlane_b32 s64, v241, 0
	v_readlane_b32 s66, v241, 2
	v_readlane_b32 s65, v241, 1
	v_readlane_b32 s67, v241, 3

; #define PG8_STAGE(bufoff, gbase, voff) do { _Pragma("unroll") for (int _i = 0; _i < 2; ++_i) \
;         __builtin_amdgcn_global_load_lds((const unsigned*)((const char*)(gbase) + (voff)[_i]), (LAS unsigned*)(lds + (bufoff) + ldsw + _i * 8192), 16, 0, 0); } while (0)
; #define PG8_LDA(dst, b, h) do { _Pragma("unroll") for (int m = 0; m < 4; ++m) _Pragma("unroll") for (int k = 0; k < 2; ++k) dst[m][k] = *(const LAS bf16x8*)(lds + PG8_SA(b, h) + aoff + m * 2048 + k * 1024); } while (0)
; #define PG8_LDB(dst, b, h) do { _Pragma("unroll") for (int n = 0; n < 2; ++n) _Pragma("unroll") for (int k = 0; k < 2; ++k) dst[n][k] = *(const LAS bf16x8*)(lds + PG8_SB(b, h) + boff + n * 2048 + k * 1024); } while (0)
; #define PG8_MMA(ai, bj, At, Bt) do { __builtin_amdgcn_s_setprio(1); _Pragma("unroll") for (int m = 0; m < 4; ++m) _Pragma("unroll") for (int n = 0; n < 2; ++n) _Pragma("unroll") for (int k = 0; k < 2; ++k) \
;         acc[ai][bj][m][n] = __builtin_amdgcn_mfma_f32_16x16x32_bf16(Bt[n][k], At[m][k], acc[ai][bj][m][n], 0, 0, 0); __builtin_amdgcn_s_setprio(0); } while (0)
; #define PG8_WAIT_L(n) asm volatile("s_waitcnt lgkmcnt(" #n ")" ::: "memory")
; #define PG8_BAR __builtin_amdgcn_s_barrier()
; #define PG8_SCHED __builtin_amdgcn_sched_barrier(0)
; template <class Epi>
; DEVI void gemm_phase(LAS unsigned char* lds, const bf16_t* gA, const bf16_t* gBt, const int lda, const int ldb, const int K, const StaticOrder S_, const Epi E) {
;     ...
;             PG8_LDB(B0, 0, 0); PG8_SCHED; PG8_LDA(At, 0, 0); PG8_STAGE(PG8_SA(1, 1), a1 + hstepA, voffA);
;             PG8_WAIT_L(8); PG8_BAR; PG8_WAIT_L(0); PG8_MMA(0, 0, At, B0); PG8_BAR; PG8_SCHED;
;             PG8_LDB(B1, 0, 1); PG8_STAGE(PG8_SB(0, 0), b2, voffB);
;             PG8_BAR; PG8_WAIT_L(0); PG8_MMA(0, 1, At, B1); PG8_BAR;
;             PG8_LDA(At, 0, 1); PG8_STAGE(PG8_SA(0, 0), a2, voffA);
;             PG8_BAR; PG8_WAIT_L(0); PG8_MMA(1, 0, At, B0); PG8_BAR; PG8_SCHED;
.LBB0_1980:
	ds_read_b128 v[160:163], v153
	ds_read_b128 v[164:167], v153 offset:1024
	ds_read_b128 v[168:171], v153 offset:2048
	ds_read_b128 v[172:175], v153 offset:3072
	s_add_i32 s70, s16, 2
	s_add_u32 s38, s14, 0x80
	s_addc_u32 s17, s15, 0
	s_cmp_eq_u32 s26, s16
	s_cselect_b32 s16, s54, s38
	s_cselect_b32 s17, s55, s17
	s_cselect_b32 s39, s57, s61
	s_cselect_b32 s38, s56, s60
	v_lshl_add_u64 v[144:145], s[14:15], 0, v[138:139]
	s_add_i32 m0, s19, 0xc000
	ds_read_b128 v[176:179], v154
	ds_read_b128 v[180:183], v154 offset:1024
	ds_read_b128 v[184:187], v154 offset:2048
	ds_read_b128 v[188:191], v154 offset:3072
	ds_read_b128 v[192:195], v154 offset:4096
	ds_read_b128 v[198:201], v154 offset:5120
	ds_read_b128 v[202:205], v154 offset:6144
	ds_read_b128 v[206:209], v154 offset:7168
	global_load_lds_dwordx4 v[144:145], off
	v_lshl_add_u64 v[144:145], s[14:15], 0, v[140:141]
	s_add_i32 m0, s19, 0xe000
	s_nop 0
	global_load_lds_dwordx4 v[144:145], off
	s_waitcnt lgkmcnt(8)
	s_barrier
	s_waitcnt lgkmcnt(0)
	s_waitcnt lgkmcnt(0)
	v_mfma_f32_16x16x32_bf16 v[124:127], v[160:163], v[176:179], v[124:127]
	v_mfma_f32_16x16x32_bf16 v[120:123], v[168:171], v[176:179], v[120:123]
	v_mfma_f32_16x16x32_bf16 v[104:107], v[168:171], v[184:187], v[104:107]
	v_mfma_f32_16x16x32_bf16 v[108:111], v[160:163], v[184:187], v[108:111]
	v_mfma_f32_16x16x32_bf16 v[92:95], v[160:163], v[192:195], v[92:95]
	v_mfma_f32_16x16x32_bf16 v[88:91], v[168:171], v[192:195], v[88:91]
	v_mfma_f32_16x16x32_bf16 v[72:75], v[168:171], v[202:205], v[72:75]
	v_mfma_f32_16x16x32_bf16 v[76:79], v[160:163], v[202:205], v[76:79]
	v_mfma_f32_16x16x32_bf16 v[124:127], v[164:167], v[180:183], v[124:127]
	v_mfma_f32_16x16x32_bf16 v[120:123], v[172:175], v[180:183], v[120:123]
	v_mfma_f32_16x16x32_bf16 v[104:107], v[172:175], v[188:191], v[104:107]
	v_mfma_f32_16x16x32_bf16 v[108:111], v[164:167], v[188:191], v[108:111]
	v_mfma_f32_16x16x32_bf16 v[92:95], v[164:167], v[198:201], v[92:95]
	v_mfma_f32_16x16x32_bf16 v[88:91], v[172:175], v[198:201], v[88:91]
	v_mfma_f32_16x16x32_bf16 v[72:75], v[172:175], v[206:209], v[72:75]
	v_mfma_f32_16x16x32_bf16 v[76:79], v[164:167], v[206:209], v[76:79]
	s_barrier
	s_add_i32 s71, s31, s18
	v_lshl_add_u64 v[144:145], s[38:39], 0, v[130:131]
	s_mov_b32 m0, s71
	ds_read_b128 v[210:213], v155
	ds_read_b128 v[214:217], v155 offset:1024
	ds_read_b128 v[218:221], v155 offset:2048
	ds_read_b128 v[222:225], v155 offset:3072
	global_load_lds_dwordx4 v[144:145], off
	v_lshl_add_u64 v[226:227], s[38:39], 0, v[134:135]
	s_add_i32 m0, s71, 0x2000
	s_nop 0
	global_load_lds_dwordx4 v[226:227], off
	s_barrier
	s_waitcnt lgkmcnt(0)
	s_waitcnt lgkmcnt(0)
	v_mfma_f32_16x16x32_bf16 v[116:119], v[210:213], v[176:179], v[116:119]
	v_mfma_f32_16x16x32_bf16 v[112:115], v[218:221], v[176:179], v[112:115]
	v_mfma_f32_16x16x32_bf16 v[96:99], v[218:221], v[184:187], v[96:99]
	v_mfma_f32_16x16x32_bf16 v[100:103], v[210:213], v[184:187], v[100:103]
	v_mfma_f32_16x16x32_bf16 v[84:87], v[210:213], v[192:195], v[84:87]
	v_mfma_f32_16x16x32_bf16 v[80:83], v[218:221], v[192:195], v[80:83]
	v_mfma_f32_16x16x32_bf16 v[64:67], v[218:221], v[202:205], v[64:67]
	v_mfma_f32_16x16x32_bf16 v[68:71], v[210:213], v[202:205], v[68:71]
	v_mfma_f32_16x16x32_bf16 v[116:119], v[214:217], v[180:183], v[116:119]
	v_mfma_f32_16x16x32_bf16 v[112:115], v[222:225], v[180:183], v[112:115]
	v_mfma_f32_16x16x32_bf16 v[96:99], v[222:225], v[188:191], v[96:99]
	v_mfma_f32_16x16x32_bf16 v[100:103], v[214:217], v[188:191], v[100:103]
	v_mfma_f32_16x16x32_bf16 v[84:87], v[214:217], v[198:201], v[84:87]
	v_mfma_f32_16x16x32_bf16 v[80:83], v[222:225], v[198:201], v[80:83]
	v_mfma_f32_16x16x32_bf16 v[64:67], v[222:225], v[206:209], v[64:67]
	v_mfma_f32_16x16x32_bf16 v[68:71], v[214:217], v[206:209], v[68:71]
	s_mov_b32 m0, s19
	v_lshl_add_u64 v[228:229], s[16:17], 0, v[128:129]
	s_barrier
	ds_read_b128 v[176:179], v154 offset:16384
	ds_read_b128 v[180:183], v154 offset:17408
	ds_read_b128 v[184:187], v154 offset:18432
	ds_read_b128 v[188:191], v154 offset:19456
	ds_read_b128 v[192:195], v154 offset:20480
	ds_read_b128 v[198:201], v154 offset:21504
	ds_read_b128 v[202:205], v154 offset:22528
	ds_read_b128 v[206:209], v154 offset:23552
	global_load_lds_dwordx4 v[228:229], off
	v_lshl_add_u64 v[230:231], s[16:17], 0, v[132:133]
	s_mov_b32 m0, s20
	s_nop 0
	global_load_lds_dwordx4 v[230:231], off
	s_barrier
	s_waitcnt lgkmcnt(0)
	s_waitcnt lgkmcnt(0)
	v_mfma_f32_16x16x32_bf16 v[60:63], v[160:163], v[176:179], v[60:63]
	v_mfma_f32_16x16x32_bf16 v[56:59], v[168:171], v[176:179], v[56:59]
	v_mfma_f32_16x16x32_bf16 v[40:43], v[168:171], v[184:187], v[40:43]
	v_mfma_f32_16x16x32_bf16 v[44:47], v[160:163], v[184:187], v[44:47]
	v_mfma_f32_16x16x32_bf16 v[28:31], v[160:163], v[192:195], v[28:31]
	v_mfma_f32_16x16x32_bf16 v[24:27], v[168:171], v[192:195], v[24:27]
	v_mfma_f32_16x16x32_bf16 v[8:11], v[168:171], v[202:205], v[8:11]
	v_mfma_f32_16x16x32_bf16 v[12:15], v[160:163], v[202:205], v[12:15]
	v_mfma_f32_16x16x32_bf16 v[60:63], v[164:167], v[180:183], v[60:63]
	v_mfma_f32_16x16x32_bf16 v[56:59], v[172:175], v[180:183], v[56:59]
	v_mfma_f32_16x16x32_bf16 v[40:43], v[172:175], v[188:191], v[40:43]
	v_mfma_f32_16x16x32_bf16 v[44:47], v[164:167], v[188:191], v[44:47]
	v_mfma_f32_16x16x32_bf16 v[28:31], v[164:167], v[198:201], v[28:31]
	v_mfma_f32_16x16x32_bf16 v[24:27], v[172:175], v[198:201], v[24:27]
	v_mfma_f32_16x16x32_bf16 v[8:11], v[172:175], v[206:209], v[8:11]
	v_mfma_f32_16x16x32_bf16 v[12:15], v[164:167], v[206:209], v[12:15]
	s_barrier
; #define PG8_STAGE(bufoff, gbase, voff) do { _Pragma("unroll") for (int _i = 0; _i < 2; ++_i) \
;         __builtin_amdgcn_global_load_lds((const unsigned*)((const char*)(gbase) + (voff)[_i]), (LAS unsigned*)(lds + (bufoff) + ldsw + _i * 8192), 16, 0, 0); } while (0)
; #define PG8_LDA(dst, b, h) do { _Pragma("unroll") for (int m = 0; m < 4; ++m) _Pragma("unroll") for (int k = 0; k < 2; ++k) dst[m][k] = *(const LAS bf16x8*)(lds + PG8_SA(b, h) + aoff + m * 2048 + k * 1024); } while (0)
; #define PG8_LDB(dst, b, h) do { _Pragma("unroll") for (int n = 0; n < 2; ++n) _Pragma("unroll") for (int k = 0; k < 2; ++k) dst[n][k] = *(const LAS bf16x8*)(lds + PG8_SB(b, h) + boff + n * 2048 + k * 1024); } while (0)
; #define PG8_MMA(ai, bj, At, Bt) do { __builtin_amdgcn_s_setprio(1); _Pragma("unroll") for (int m = 0; m < 4; ++m) _Pragma("unroll") for (int n = 0; n < 2; ++n) _Pragma("unroll") for (int k = 0; k < 2; ++k) \
;         acc[ai][bj][m][n] = __builtin_amdgcn_mfma_f32_16x16x32_bf16(Bt[n][k], At[m][k], acc[ai][bj][m][n], 0, 0, 0); __builtin_amdgcn_s_setprio(0); } while (0)
; #define PG8_WAIT_V(n) asm volatile("s_waitcnt vmcnt(" #n ")" ::: "memory")
; #define PG8_WAIT_L(n) asm volatile("s_waitcnt lgkmcnt(" #n ")" ::: "memory")
; #define PG8_BAR __builtin_amdgcn_s_barrier()
; #define PG8_SCHED __builtin_amdgcn_sched_barrier(0)
; template <class Epi>
; DEVI void gemm_phase(LAS unsigned char* lds, const bf16_t* gA, const bf16_t* gBt, const int lda, const int ldb, const int K, const StaticOrder S_, const Epi E) {
;     ...
;             PG8_STAGE(PG8_SB(0, 1), b2 + hstepB, voffB);
;             PG8_WAIT_V(6); PG8_BAR; PG8_MMA(1, 1, At, B1); PG8_BAR;
;             PG8_LDB(B0, 1, 0); PG8_SCHED; PG8_LDA(At, 1, 0); PG8_STAGE(PG8_SA(0, 1), a2 + hstepA, voffA);
;             PG8_WAIT_L(8); PG8_BAR; PG8_WAIT_L(0); PG8_MMA(0, 0, At, B0); PG8_BAR; PG8_SCHED;
;             PG8_LDB(B1, 1, 1); PG8_STAGE(PG8_SB(1, 0), b3, voffB);
	s_add_u32 s38, s38, s2
	s_addc_u32 s39, s39, s3
	s_add_i32 s71, s48, s18
	v_lshl_add_u64 v[232:233], s[38:39], 0, v[130:131]
	s_mov_b32 m0, s71
	v_lshl_add_u64 v[234:235], s[38:39], 0, v[134:135]
	global_load_lds_dwordx4 v[232:233], off
	s_add_i32 m0, s71, 0x2000
	s_nop 0
	global_load_lds_dwordx4 v[234:235], off
	s_waitcnt vmcnt(6)
	s_barrier
	v_mfma_f32_16x16x32_bf16 v[52:55], v[210:213], v[176:179], v[52:55]
	v_mfma_f32_16x16x32_bf16 v[48:51], v[218:221], v[176:179], v[48:51]
	v_mfma_f32_16x16x32_bf16 v[32:35], v[218:221], v[184:187], v[32:35]
	v_mfma_f32_16x16x32_bf16 v[36:39], v[210:213], v[184:187], v[36:39]
	v_mfma_f32_16x16x32_bf16 v[20:23], v[210:213], v[192:195], v[20:23]
	v_mfma_f32_16x16x32_bf16 v[16:19], v[218:221], v[192:195], v[16:19]
	v_mfma_f32_16x16x32_bf16 v[0:3], v[218:221], v[202:205], v[0:3]
	v_mfma_f32_16x16x32_bf16 v[4:7], v[210:213], v[202:205], v[4:7]
	v_mfma_f32_16x16x32_bf16 v[52:55], v[214:217], v[180:183], v[52:55]
	v_mfma_f32_16x16x32_bf16 v[48:51], v[222:225], v[180:183], v[48:51]
	v_mfma_f32_16x16x32_bf16 v[32:35], v[222:225], v[188:191], v[32:35]
	v_mfma_f32_16x16x32_bf16 v[36:39], v[214:217], v[188:191], v[36:39]
	v_mfma_f32_16x16x32_bf16 v[20:23], v[214:217], v[198:201], v[20:23]
	v_mfma_f32_16x16x32_bf16 v[16:19], v[222:225], v[198:201], v[16:19]
	v_mfma_f32_16x16x32_bf16 v[0:3], v[222:225], v[206:209], v[0:3]
	v_mfma_f32_16x16x32_bf16 v[4:7], v[214:217], v[206:209], v[4:7]
	s_barrier
	ds_read_b128 v[160:163], v156
	ds_read_b128 v[164:167], v156 offset:1024
	ds_read_b128 v[168:171], v156 offset:2048
	ds_read_b128 v[172:175], v156 offset:3072
	s_add_u32 s16, s16, s0
	s_addc_u32 s17, s17, s1
	s_mov_b32 m0, s21
	v_lshl_add_u64 v[210:211], s[16:17], 0, v[128:129]
	ds_read_b128 v[176:179], v154 offset:32768
	ds_read_b128 v[180:183], v154 offset:33792
	ds_read_b128 v[184:187], v154 offset:34816
	ds_read_b128 v[188:191], v154 offset:35840
	ds_read_b128 v[192:195], v154 offset:36864
	ds_read_b128 v[198:201], v154 offset:37888
	ds_read_b128 v[202:205], v154 offset:38912
	ds_read_b128 v[206:209], v154 offset:39936
	global_load_lds_dwordx4 v[210:211], off
	v_lshl_add_u64 v[210:211], s[16:17], 0, v[132:133]
	s_mov_b32 m0, s22
	s_nop 0
	global_load_lds_dwordx4 v[210:211], off
	s_waitcnt lgkmcnt(8)
	s_barrier
	s_waitcnt lgkmcnt(0)
	s_waitcnt lgkmcnt(0)
	v_mfma_f32_16x16x32_bf16 v[124:127], v[160:163], v[176:179], v[124:127]
	v_mfma_f32_16x16x32_bf16 v[120:123], v[168:171], v[176:179], v[120:123]
	v_mfma_f32_16x16x32_bf16 v[104:107], v[168:171], v[184:187], v[104:107]
	v_mfma_f32_16x16x32_bf16 v[108:111], v[160:163], v[184:187], v[108:111]
	v_mfma_f32_16x16x32_bf16 v[92:95], v[160:163], v[192:195], v[92:95]
	v_mfma_f32_16x16x32_bf16 v[88:91], v[168:171], v[192:195], v[88:91]
	v_mfma_f32_16x16x32_bf16 v[72:75], v[168:171], v[202:205], v[72:75]
	v_mfma_f32_16x16x32_bf16 v[76:79], v[160:163], v[202:205], v[76:79]
	v_mfma_f32_16x16x32_bf16 v[124:127], v[164:167], v[180:183], v[124:127]
	v_mfma_f32_16x16x32_bf16 v[120:123], v[172:175], v[180:183], v[120:123]
	v_mfma_f32_16x16x32_bf16 v[104:107], v[172:175], v[188:191], v[104:107]
	v_mfma_f32_16x16x32_bf16 v[108:111], v[164:167], v[188:191], v[108:111]
	v_mfma_f32_16x16x32_bf16 v[92:95], v[164:167], v[198:201], v[92:95]
	v_mfma_f32_16x16x32_bf16 v[88:91], v[172:175], v[198:201], v[88:91]
	v_mfma_f32_16x16x32_bf16 v[72:75], v[172:175], v[206:209], v[72:75]
	v_mfma_f32_16x16x32_bf16 v[76:79], v[164:167], v[206:209], v[76:79]
	s_barrier
	s_add_i32 s16, s49, s18
	v_lshl_add_u64 v[144:145], v[144:145], 0, s[52:53]
	s_mov_b32 m0, s16
	ds_read_b128 v[210:213], v157
	ds_read_b128 v[214:217], v157 offset:1024
	ds_read_b128 v[218:221], v157 offset:2048
	ds_read_b128 v[222:225], v157 offset:3072
	global_load_lds_dwordx4 v[144:145], off
	v_lshl_add_u64 v[144:145], v[226:227], 0, s[52:53]
	s_add_i32 m0, s16, 0x2000
	s_nop 0
	global_load_lds_dwordx4 v[144:145], off
	s_barrier
; #define PG8_STAGE(bufoff, gbase, voff) do { _Pragma("unroll") for (int _i = 0; _i < 2; ++_i) \
;         __builtin_amdgcn_global_load_lds((const unsigned*)((const char*)(gbase) + (voff)[_i]), (LAS unsigned*)(lds + (bufoff) + ldsw + _i * 8192), 16, 0, 0); } while (0)
; #define PG8_LDA(dst, b, h) do { _Pragma("unroll") for (int m = 0; m < 4; ++m) _Pragma("unroll") for (int k = 0; k < 2; ++k) dst[m][k] = *(const LAS bf16x8*)(lds + PG8_SA(b, h) + aoff + m * 2048 + k * 1024); } while (0)
; #define PG8_MMA(ai, bj, At, Bt) do { __builtin_amdgcn_s_setprio(1); _Pragma("unroll") for (int m = 0; m < 4; ++m) _Pragma("unroll") for (int n = 0; n < 2; ++n) _Pragma("unroll") for (int k = 0; k < 2; ++k) \
;         acc[ai][bj][m][n] = __builtin_amdgcn_mfma_f32_16x16x32_bf16(Bt[n][k], At[m][k], acc[ai][bj][m][n], 0, 0, 0); __builtin_amdgcn_s_setprio(0); } while (0)
; #define PG8_WAIT_V(n) asm volatile("s_waitcnt vmcnt(" #n ")" ::: "memory")
; #define PG8_WAIT_L(n) asm volatile("s_waitcnt lgkmcnt(" #n ")" ::: "memory")
; #define PG8_BAR __builtin_amdgcn_s_barrier()
; #define PG8_SCHED __builtin_amdgcn_sched_barrier(0)
; template <class Epi>
; DEVI void gemm_phase(LAS unsigned char* lds, const bf16_t* gA, const bf16_t* gBt, const int lda, const int ldb, const int K, const StaticOrder S_, const Epi E) {
;     ...
;             PG8_BAR; PG8_WAIT_L(0); PG8_MMA(0, 1, At, B1); PG8_BAR;
;             PG8_LDA(At, 1, 1); PG8_STAGE(PG8_SA(1, 0), a3, voffA);
;             PG8_BAR; PG8_WAIT_L(0); PG8_MMA(1, 0, At, B0); PG8_BAR; PG8_SCHED;
;             PG8_STAGE(PG8_SB(1, 1), b3 + hstepB, voffB);
;             PG8_WAIT_V(6); PG8_BAR; PG8_MMA(1, 1, At, B1); PG8_BAR;
	s_waitcnt lgkmcnt(0)
	s_waitcnt lgkmcnt(0)
	v_mfma_f32_16x16x32_bf16 v[116:119], v[210:213], v[176:179], v[116:119]
	v_mfma_f32_16x16x32_bf16 v[112:115], v[218:221], v[176:179], v[112:115]
	v_mfma_f32_16x16x32_bf16 v[96:99], v[218:221], v[184:187], v[96:99]
	v_mfma_f32_16x16x32_bf16 v[100:103], v[210:213], v[184:187], v[100:103]
	v_mfma_f32_16x16x32_bf16 v[84:87], v[210:213], v[192:195], v[84:87]
	v_mfma_f32_16x16x32_bf16 v[80:83], v[218:221], v[192:195], v[80:83]
	v_mfma_f32_16x16x32_bf16 v[64:67], v[218:221], v[202:205], v[64:67]
	v_mfma_f32_16x16x32_bf16 v[68:71], v[210:213], v[202:205], v[68:71]
	v_mfma_f32_16x16x32_bf16 v[116:119], v[214:217], v[180:183], v[116:119]
	v_mfma_f32_16x16x32_bf16 v[112:115], v[222:225], v[180:183], v[112:115]
	v_mfma_f32_16x16x32_bf16 v[96:99], v[222:225], v[188:191], v[96:99]
	v_mfma_f32_16x16x32_bf16 v[100:103], v[214:217], v[188:191], v[100:103]
	v_mfma_f32_16x16x32_bf16 v[84:87], v[214:217], v[198:201], v[84:87]
	v_mfma_f32_16x16x32_bf16 v[80:83], v[222:225], v[198:201], v[80:83]
	v_mfma_f32_16x16x32_bf16 v[64:67], v[222:225], v[206:209], v[64:67]
	v_mfma_f32_16x16x32_bf16 v[68:71], v[214:217], v[206:209], v[68:71]
	s_mov_b32 m0, s23
	v_lshl_add_u64 v[144:145], v[228:229], 0, s[52:53]
	s_barrier
	ds_read_b128 v[176:179], v154 offset:49152
	ds_read_b128 v[180:183], v154 offset:50176
	ds_read_b128 v[184:187], v154 offset:51200
	ds_read_b128 v[188:191], v154 offset:52224
	ds_read_b128 v[192:195], v154 offset:53248
	ds_read_b128 v[198:201], v154 offset:54272
	ds_read_b128 v[202:205], v154 offset:55296
	ds_read_b128 v[206:209], v154 offset:56320
	global_load_lds_dwordx4 v[144:145], off
	v_lshl_add_u64 v[144:145], v[230:231], 0, s[52:53]
	s_mov_b32 m0, s24
	s_nop 0
	global_load_lds_dwordx4 v[144:145], off
	s_barrier
	s_waitcnt lgkmcnt(0)
	s_waitcnt lgkmcnt(0)
	v_mfma_f32_16x16x32_bf16 v[60:63], v[160:163], v[176:179], v[60:63]
	v_mfma_f32_16x16x32_bf16 v[56:59], v[168:171], v[176:179], v[56:59]
	v_mfma_f32_16x16x32_bf16 v[40:43], v[168:171], v[184:187], v[40:43]
	v_mfma_f32_16x16x32_bf16 v[44:47], v[160:163], v[184:187], v[44:47]
	v_mfma_f32_16x16x32_bf16 v[28:31], v[160:163], v[192:195], v[28:31]
	v_mfma_f32_16x16x32_bf16 v[24:27], v[168:171], v[192:195], v[24:27]
	v_mfma_f32_16x16x32_bf16 v[8:11], v[168:171], v[202:205], v[8:11]
	v_mfma_f32_16x16x32_bf16 v[12:15], v[160:163], v[202:205], v[12:15]
	v_mfma_f32_16x16x32_bf16 v[60:63], v[164:167], v[180:183], v[60:63]
	v_mfma_f32_16x16x32_bf16 v[56:59], v[172:175], v[180:183], v[56:59]
	v_mfma_f32_16x16x32_bf16 v[40:43], v[172:175], v[188:191], v[40:43]
	v_mfma_f32_16x16x32_bf16 v[44:47], v[164:167], v[188:191], v[44:47]
	v_mfma_f32_16x16x32_bf16 v[28:31], v[164:167], v[198:201], v[28:31]
	v_mfma_f32_16x16x32_bf16 v[24:27], v[172:175], v[198:201], v[24:27]
	v_mfma_f32_16x16x32_bf16 v[8:11], v[172:175], v[206:209], v[8:11]
	v_mfma_f32_16x16x32_bf16 v[12:15], v[164:167], v[206:209], v[12:15]
	s_barrier
	s_add_i32 s16, s50, s18
	v_lshl_add_u64 v[144:145], v[232:233], 0, s[52:53]
	s_mov_b32 m0, s16
	s_nop 0
	global_load_lds_dwordx4 v[144:145], off
	v_lshl_add_u64 v[144:145], v[234:235], 0, s[52:53]
	s_add_i32 m0, s16, 0x2000
	s_nop 0
	global_load_lds_dwordx4 v[144:145], off
	s_waitcnt vmcnt(6)
	s_barrier
	v_mfma_f32_16x16x32_bf16 v[52:55], v[210:213], v[176:179], v[52:55]
	v_mfma_f32_16x16x32_bf16 v[48:51], v[218:221], v[176:179], v[48:51]
	v_mfma_f32_16x16x32_bf16 v[32:35], v[218:221], v[184:187], v[32:35]
	v_mfma_f32_16x16x32_bf16 v[36:39], v[210:213], v[184:187], v[36:39]
	v_mfma_f32_16x16x32_bf16 v[20:23], v[210:213], v[192:195], v[20:23]
	v_mfma_f32_16x16x32_bf16 v[16:19], v[218:221], v[192:195], v[16:19]
	v_mfma_f32_16x16x32_bf16 v[0:3], v[218:221], v[202:205], v[0:3]
	v_mfma_f32_16x16x32_bf16 v[4:7], v[210:213], v[202:205], v[4:7]
	v_mfma_f32_16x16x32_bf16 v[52:55], v[214:217], v[180:183], v[52:55]
	v_mfma_f32_16x16x32_bf16 v[48:51], v[222:225], v[180:183], v[48:51]
	v_mfma_f32_16x16x32_bf16 v[32:35], v[222:225], v[188:191], v[32:35]
	v_mfma_f32_16x16x32_bf16 v[36:39], v[214:217], v[188:191], v[36:39]
	v_mfma_f32_16x16x32_bf16 v[20:23], v[214:217], v[198:201], v[20:23]
	v_mfma_f32_16x16x32_bf16 v[16:19], v[222:225], v[198:201], v[16:19]
	v_mfma_f32_16x16x32_bf16 v[0:3], v[222:225], v[206:209], v[0:3]
	v_mfma_f32_16x16x32_bf16 v[4:7], v[214:217], v[206:209], v[4:7]
	s_add_u32 s14, s14, 0x100
	s_addc_u32 s15, s15, 0
	s_add_u32 s60, s60, 0x100
	s_addc_u32 s61, s61, 0
	s_cmp_ge_i32 s70, s25
	s_mov_b32 s16, s70
	s_barrier
	s_cbranch_scc0 .LBB0_1980

; #define PG8_STAGE(bufoff, gbase, voff) do { _Pragma("unroll") for (int _i = 0; _i < 2; ++_i) \
;         __builtin_amdgcn_global_load_lds((const unsigned*)((const char*)(gbase) + (voff)[_i]), (LAS unsigned*)(lds + (bufoff) + ldsw + _i * 8192), 16, 0, 0); } while (0)
; #define PG8_LDA(dst, b, h) do { _Pragma("unroll") for (int m = 0; m < 4; ++m) _Pragma("unroll") for (int k = 0; k < 2; ++k) dst[m][k] = *(const LAS bf16x8*)(lds + PG8_SA(b, h) + aoff + m * 2048 + k * 1024); } while (0)
; #define PG8_LDB(dst, b, h) do { _Pragma("unroll") for (int n = 0; n < 2; ++n) _Pragma("unroll") for (int k = 0; k < 2; ++k) dst[n][k] = *(const LAS bf16x8*)(lds + PG8_SB(b, h) + boff + n * 2048 + k * 1024); } while (0)
; #define PG8_MMA(ai, bj, At, Bt) do { __builtin_amdgcn_s_setprio(1); _Pragma("unroll") for (int m = 0; m < 4; ++m) _Pragma("unroll") for (int n = 0; n < 2; ++n) _Pragma("unroll") for (int k = 0; k < 2; ++k) \
;         acc[ai][bj][m][n] = __builtin_amdgcn_mfma_f32_16x16x32_bf16(Bt[n][k], At[m][k], acc[ai][bj][m][n], 0, 0, 0); __builtin_amdgcn_s_setprio(0); } while (0)
; #define PG8_WAIT_L(n) asm volatile("s_waitcnt lgkmcnt(" #n ")" ::: "memory")
; #define PG8_BAR __builtin_amdgcn_s_barrier()
; #define PG8_SCHED __builtin_amdgcn_sched_barrier(0)
; template <class Epi>
; DEVI void gemm_phase(LAS unsigned char* lds, const bf16_t* gA, const bf16_t* gBt, const int lda, const int ldb, const int K, const StaticOrder S_, const Epi E) {
;     ...
;             const bool last = (t == nt - 2);
;             const char* a1 = cA + (size_t)(t + 1) * kstep;
;             const char* a2 = last ? nA : cA + (size_t)(t + 2) * kstep; const char* b2 = last ? nB : cB + (size_t)(t + 2) * kstep;
;             const char* a3 = a2 + kstep; const char* b3 = b2 + kstep;
;             PG8_LDB(B0, 0, 0); PG8_SCHED; PG8_LDA(At, 0, 0); PG8_STAGE(PG8_SA(1, 1), a1 + hstepA, voffA);
;             PG8_WAIT_L(8); PG8_BAR; PG8_WAIT_L(0); PG8_MMA(0, 0, At, B0); PG8_BAR; PG8_SCHED;
;             PG8_LDB(B1, 0, 1); PG8_STAGE(PG8_SB(0, 0), b2, voffB);
;             PG8_BAR; PG8_WAIT_L(0); PG8_MMA(0, 1, At, B1); PG8_BAR;
;             PG8_LDA(At, 0, 1); PG8_STAGE(PG8_SA(0, 0), a2, voffA);
;             PG8_BAR; PG8_WAIT_L(0); PG8_MMA(1, 0, At, B0); PG8_BAR; PG8_SCHED;
.LBB0_2366:
	ds_read_b128 v[128:131], v201
	ds_read_b128 v[132:135], v201 offset:1024
	ds_read_b128 v[136:139], v201 offset:2048
	ds_read_b128 v[140:143], v201 offset:3072
	s_add_i32 s60, s16, 2
	s_add_u32 s38, s14, 0x80
	s_addc_u32 s17, s15, 0
	s_cmp_eq_u32 s19, s16
	s_cselect_b32 s16, s12, s38
	s_cselect_b32 s17, s13, s17
	s_cselect_b32 s39, s41, s49
	s_cselect_b32 s38, s40, s48
	v_lshl_add_u64 v[164:165], s[14:15], 0, v[174:175]
	s_add_i32 m0, s55, 0xc000
	ds_read_b128 v[144:147], v202
	ds_read_b128 v[148:151], v202 offset:1024
	ds_read_b128 v[152:155], v202 offset:2048
	ds_read_b128 v[156:159], v202 offset:3072
	ds_read_b128 v[160:163], v202 offset:4096
	ds_read_b128 v[180:183], v202 offset:5120
	ds_read_b128 v[184:187], v202 offset:6144
	ds_read_b128 v[188:191], v202 offset:7168
	global_load_lds_dwordx4 v[164:165], off
	v_lshl_add_u64 v[164:165], s[14:15], 0, v[176:177]
	s_add_i32 m0, s55, 0xe000
	s_nop 0
	global_load_lds_dwordx4 v[164:165], off
	s_waitcnt lgkmcnt(8)
	s_barrier
	s_waitcnt lgkmcnt(0)
	s_waitcnt lgkmcnt(0)
	v_mfma_f32_16x16x32_bf16 v[124:127], v[128:131], v[144:147], v[124:127]
	v_mfma_f32_16x16x32_bf16 v[120:123], v[136:139], v[144:147], v[120:123]
	v_mfma_f32_16x16x32_bf16 v[104:107], v[136:139], v[152:155], v[104:107]
	v_mfma_f32_16x16x32_bf16 v[108:111], v[128:131], v[152:155], v[108:111]
	v_mfma_f32_16x16x32_bf16 v[92:95], v[128:131], v[160:163], v[92:95]
	v_mfma_f32_16x16x32_bf16 v[88:91], v[136:139], v[160:163], v[88:91]
	v_mfma_f32_16x16x32_bf16 v[72:75], v[136:139], v[184:187], v[72:75]
	v_mfma_f32_16x16x32_bf16 v[76:79], v[128:131], v[184:187], v[76:79]
	v_mfma_f32_16x16x32_bf16 v[124:127], v[132:135], v[148:151], v[124:127]
	v_mfma_f32_16x16x32_bf16 v[120:123], v[140:143], v[148:151], v[120:123]
	v_mfma_f32_16x16x32_bf16 v[104:107], v[140:143], v[156:159], v[104:107]
	v_mfma_f32_16x16x32_bf16 v[108:111], v[132:135], v[156:159], v[108:111]
	v_mfma_f32_16x16x32_bf16 v[92:95], v[132:135], v[180:183], v[92:95]
	v_mfma_f32_16x16x32_bf16 v[88:91], v[140:143], v[180:183], v[88:91]
	v_mfma_f32_16x16x32_bf16 v[72:75], v[140:143], v[188:191], v[72:75]
	v_mfma_f32_16x16x32_bf16 v[76:79], v[132:135], v[188:191], v[76:79]
	s_barrier
	s_add_i32 s61, s29, s20
	v_lshl_add_u64 v[164:165], s[38:39], 0, v[168:169]
	s_mov_b32 m0, s61
	ds_read_b128 v[192:195], v203
	ds_read_b128 v[206:209], v203 offset:1024
	ds_read_b128 v[210:213], v203 offset:2048
	ds_read_b128 v[214:217], v203 offset:3072
	global_load_lds_dwordx4 v[164:165], off
	v_lshl_add_u64 v[218:219], s[38:39], 0, v[172:173]
	s_add_i32 m0, s61, 0x2000
	s_nop 0
	global_load_lds_dwordx4 v[218:219], off
	s_barrier
	s_waitcnt lgkmcnt(0)
	s_waitcnt lgkmcnt(0)
	v_mfma_f32_16x16x32_bf16 v[116:119], v[192:195], v[144:147], v[116:119]
	v_mfma_f32_16x16x32_bf16 v[112:115], v[210:213], v[144:147], v[112:115]
	v_mfma_f32_16x16x32_bf16 v[96:99], v[210:213], v[152:155], v[96:99]
	v_mfma_f32_16x16x32_bf16 v[100:103], v[192:195], v[152:155], v[100:103]
	v_mfma_f32_16x16x32_bf16 v[84:87], v[192:195], v[160:163], v[84:87]
	v_mfma_f32_16x16x32_bf16 v[80:83], v[210:213], v[160:163], v[80:83]
	v_mfma_f32_16x16x32_bf16 v[64:67], v[210:213], v[184:187], v[64:67]
	v_mfma_f32_16x16x32_bf16 v[68:71], v[192:195], v[184:187], v[68:71]
	v_mfma_f32_16x16x32_bf16 v[116:119], v[206:209], v[148:151], v[116:119]
	v_mfma_f32_16x16x32_bf16 v[112:115], v[214:217], v[148:151], v[112:115]
	v_mfma_f32_16x16x32_bf16 v[96:99], v[214:217], v[156:159], v[96:99]
	v_mfma_f32_16x16x32_bf16 v[100:103], v[206:209], v[156:159], v[100:103]
	v_mfma_f32_16x16x32_bf16 v[84:87], v[206:209], v[180:183], v[84:87]
	v_mfma_f32_16x16x32_bf16 v[80:83], v[214:217], v[180:183], v[80:83]
	v_mfma_f32_16x16x32_bf16 v[64:67], v[214:217], v[188:191], v[64:67]
	v_mfma_f32_16x16x32_bf16 v[68:71], v[206:209], v[188:191], v[68:71]
	s_mov_b32 m0, s55
	v_lshl_add_u64 v[220:221], s[16:17], 0, v[166:167]
	s_barrier
	ds_read_b128 v[144:147], v202 offset:16384
	ds_read_b128 v[148:151], v202 offset:17408
	ds_read_b128 v[152:155], v202 offset:18432
	ds_read_b128 v[156:159], v202 offset:19456
	ds_read_b128 v[160:163], v202 offset:20480
	ds_read_b128 v[180:183], v202 offset:21504
	ds_read_b128 v[184:187], v202 offset:22528
	ds_read_b128 v[188:191], v202 offset:23552
	global_load_lds_dwordx4 v[220:221], off
	v_lshl_add_u64 v[222:223], s[16:17], 0, v[170:171]
	s_mov_b32 m0, s22
	s_nop 0
	global_load_lds_dwordx4 v[222:223], off
	s_barrier
	s_waitcnt lgkmcnt(0)
	s_waitcnt lgkmcnt(0)
	v_mfma_f32_16x16x32_bf16 v[60:63], v[128:131], v[144:147], v[60:63]
	v_mfma_f32_16x16x32_bf16 v[56:59], v[136:139], v[144:147], v[56:59]
	v_mfma_f32_16x16x32_bf16 v[40:43], v[136:139], v[152:155], v[40:43]
	v_mfma_f32_16x16x32_bf16 v[44:47], v[128:131], v[152:155], v[44:47]
	v_mfma_f32_16x16x32_bf16 v[28:31], v[128:131], v[160:163], v[28:31]
	v_mfma_f32_16x16x32_bf16 v[24:27], v[136:139], v[160:163], v[24:27]
	v_mfma_f32_16x16x32_bf16 v[8:11], v[136:139], v[184:187], v[8:11]
	v_mfma_f32_16x16x32_bf16 v[12:15], v[128:131], v[184:187], v[12:15]
	v_mfma_f32_16x16x32_bf16 v[60:63], v[132:135], v[148:151], v[60:63]
	v_mfma_f32_16x16x32_bf16 v[56:59], v[140:143], v[148:151], v[56:59]
	v_mfma_f32_16x16x32_bf16 v[40:43], v[140:143], v[156:159], v[40:43]
	v_mfma_f32_16x16x32_bf16 v[44:47], v[132:135], v[156:159], v[44:47]
	v_mfma_f32_16x16x32_bf16 v[28:31], v[132:135], v[180:183], v[28:31]
	v_mfma_f32_16x16x32_bf16 v[24:27], v[140:143], v[180:183], v[24:27]
	v_mfma_f32_16x16x32_bf16 v[8:11], v[140:143], v[188:191], v[8:11]
	v_mfma_f32_16x16x32_bf16 v[12:15], v[132:135], v[188:191], v[12:15]
	s_barrier
; #define PG8_STAGE(bufoff, gbase, voff) do { _Pragma("unroll") for (int _i = 0; _i < 2; ++_i) \
;         __builtin_amdgcn_global_load_lds((const unsigned*)((const char*)(gbase) + (voff)[_i]), (LAS unsigned*)(lds + (bufoff) + ldsw + _i * 8192), 16, 0, 0); } while (0)
; #define PG8_LDA(dst, b, h) do { _Pragma("unroll") for (int m = 0; m < 4; ++m) _Pragma("unroll") for (int k = 0; k < 2; ++k) dst[m][k] = *(const LAS bf16x8*)(lds + PG8_SA(b, h) + aoff + m * 2048 + k * 1024); } while (0)
; #define PG8_LDB(dst, b, h) do { _Pragma("unroll") for (int n = 0; n < 2; ++n) _Pragma("unroll") for (int k = 0; k < 2; ++k) dst[n][k] = *(const LAS bf16x8*)(lds + PG8_SB(b, h) + boff + n * 2048 + k * 1024); } while (0)
; #define PG8_MMA(ai, bj, At, Bt) do { __builtin_amdgcn_s_setprio(1); _Pragma("unroll") for (int m = 0; m < 4; ++m) _Pragma("unroll") for (int n = 0; n < 2; ++n) _Pragma("unroll") for (int k = 0; k < 2; ++k) \
;         acc[ai][bj][m][n] = __builtin_amdgcn_mfma_f32_16x16x32_bf16(Bt[n][k], At[m][k], acc[ai][bj][m][n], 0, 0, 0); __builtin_amdgcn_s_setprio(0); } while (0)
; #define PG8_WAIT_V(n) asm volatile("s_waitcnt vmcnt(" #n ")" ::: "memory")
; #define PG8_WAIT_L(n) asm volatile("s_waitcnt lgkmcnt(" #n ")" ::: "memory")
; #define PG8_BAR __builtin_amdgcn_s_barrier()
; #define PG8_SCHED __builtin_amdgcn_sched_barrier(0)
; template <class Epi>
; DEVI void gemm_phase(LAS unsigned char* lds, const bf16_t* gA, const bf16_t* gBt, const int lda, const int ldb, const int K, const StaticOrder S_, const Epi E) {
;     ...
;             PG8_STAGE(PG8_SB(0, 1), b2 + hstepB, voffB);
;             PG8_WAIT_V(6); PG8_BAR; PG8_MMA(1, 1, At, B1); PG8_BAR;
;             PG8_LDB(B0, 1, 0); PG8_SCHED; PG8_LDA(At, 1, 0); PG8_STAGE(PG8_SA(0, 1), a2 + hstepA, voffA);
;             PG8_WAIT_L(8); PG8_BAR; PG8_WAIT_L(0); PG8_MMA(0, 0, At, B0); PG8_BAR; PG8_SCHED;
;             PG8_LDB(B1, 1, 1); PG8_STAGE(PG8_SB(1, 0), b3, voffB);
;             PG8_BAR; PG8_WAIT_L(0); PG8_MMA(0, 1, At, B1); PG8_BAR;
	s_add_u32 s38, s38, s2
	s_addc_u32 s39, s39, s3
	s_add_i32 s61, s50, s20
	v_lshl_add_u64 v[224:225], s[38:39], 0, v[168:169]
	s_mov_b32 m0, s61
	v_lshl_add_u64 v[226:227], s[38:39], 0, v[172:173]
	global_load_lds_dwordx4 v[224:225], off
	s_add_i32 m0, s61, 0x2000
	s_nop 0
	global_load_lds_dwordx4 v[226:227], off
	s_waitcnt vmcnt(6)
	s_barrier
	v_mfma_f32_16x16x32_bf16 v[52:55], v[192:195], v[144:147], v[52:55]
	v_mfma_f32_16x16x32_bf16 v[48:51], v[210:213], v[144:147], v[48:51]
	v_mfma_f32_16x16x32_bf16 v[32:35], v[210:213], v[152:155], v[32:35]
	v_mfma_f32_16x16x32_bf16 v[36:39], v[192:195], v[152:155], v[36:39]
	v_mfma_f32_16x16x32_bf16 v[20:23], v[192:195], v[160:163], v[20:23]
	v_mfma_f32_16x16x32_bf16 v[16:19], v[210:213], v[160:163], v[16:19]
	v_mfma_f32_16x16x32_bf16 v[0:3], v[210:213], v[184:187], v[0:3]
	v_mfma_f32_16x16x32_bf16 v[4:7], v[192:195], v[184:187], v[4:7]
	v_mfma_f32_16x16x32_bf16 v[52:55], v[206:209], v[148:151], v[52:55]
	v_mfma_f32_16x16x32_bf16 v[48:51], v[214:217], v[148:151], v[48:51]
	v_mfma_f32_16x16x32_bf16 v[32:35], v[214:217], v[156:159], v[32:35]
	v_mfma_f32_16x16x32_bf16 v[36:39], v[206:209], v[156:159], v[36:39]
	v_mfma_f32_16x16x32_bf16 v[20:23], v[206:209], v[180:183], v[20:23]
	v_mfma_f32_16x16x32_bf16 v[16:19], v[214:217], v[180:183], v[16:19]
	v_mfma_f32_16x16x32_bf16 v[0:3], v[214:217], v[188:191], v[0:3]
	v_mfma_f32_16x16x32_bf16 v[4:7], v[206:209], v[188:191], v[4:7]
	s_add_i32 s38, 0, 0x18000
	v_add_u32_e32 v140, s38, v199
	s_barrier
	ds_read_b128 v[128:131], v140
	ds_read_b128 v[132:135], v140 offset:1024
	ds_read_b128 v[136:139], v140 offset:2048
	ds_read_b128 v[140:143], v140 offset:3072
	s_add_u32 s16, s16, s0
	s_addc_u32 s17, s17, s1
	s_mov_b32 m0, s23
	v_lshl_add_u64 v[192:193], s[16:17], 0, v[166:167]
	ds_read_b128 v[144:147], v202 offset:32768
	ds_read_b128 v[148:151], v202 offset:33792
	ds_read_b128 v[152:155], v202 offset:34816
	ds_read_b128 v[156:159], v202 offset:35840
	ds_read_b128 v[160:163], v202 offset:36864
	ds_read_b128 v[180:183], v202 offset:37888
	ds_read_b128 v[184:187], v202 offset:38912
	ds_read_b128 v[188:191], v202 offset:39936
	global_load_lds_dwordx4 v[192:193], off
	v_lshl_add_u64 v[192:193], s[16:17], 0, v[170:171]
	s_mov_b32 m0, s24
	s_nop 0
	global_load_lds_dwordx4 v[192:193], off
	s_waitcnt lgkmcnt(8)
	s_barrier
	s_waitcnt lgkmcnt(0)
	s_waitcnt lgkmcnt(0)
	v_mfma_f32_16x16x32_bf16 v[124:127], v[128:131], v[144:147], v[124:127]
	v_mfma_f32_16x16x32_bf16 v[120:123], v[136:139], v[144:147], v[120:123]
	v_mfma_f32_16x16x32_bf16 v[104:107], v[136:139], v[152:155], v[104:107]
	v_mfma_f32_16x16x32_bf16 v[108:111], v[128:131], v[152:155], v[108:111]
	v_mfma_f32_16x16x32_bf16 v[92:95], v[128:131], v[160:163], v[92:95]
	v_mfma_f32_16x16x32_bf16 v[88:91], v[136:139], v[160:163], v[88:91]
	v_mfma_f32_16x16x32_bf16 v[72:75], v[136:139], v[184:187], v[72:75]
	v_mfma_f32_16x16x32_bf16 v[76:79], v[128:131], v[184:187], v[76:79]
	v_mfma_f32_16x16x32_bf16 v[124:127], v[132:135], v[148:151], v[124:127]
	v_mfma_f32_16x16x32_bf16 v[120:123], v[140:143], v[148:151], v[120:123]
	v_mfma_f32_16x16x32_bf16 v[104:107], v[140:143], v[156:159], v[104:107]
	v_mfma_f32_16x16x32_bf16 v[108:111], v[132:135], v[156:159], v[108:111]
	v_mfma_f32_16x16x32_bf16 v[92:95], v[132:135], v[180:183], v[92:95]
	v_mfma_f32_16x16x32_bf16 v[88:91], v[140:143], v[180:183], v[88:91]
	v_mfma_f32_16x16x32_bf16 v[72:75], v[140:143], v[188:191], v[72:75]
	v_mfma_f32_16x16x32_bf16 v[76:79], v[132:135], v[188:191], v[76:79]
	s_barrier
	s_add_i32 s16, 0, 0x1c000
	s_add_i32 s17, s38, s20
	v_add_u32_e32 v205, s16, v199
	v_lshl_add_u64 v[164:165], v[164:165], 0, s[8:9]
	s_mov_b32 m0, s17
	ds_read_b128 v[192:195], v205
	ds_read_b128 v[206:209], v205 offset:1024
	ds_read_b128 v[210:213], v205 offset:2048
	ds_read_b128 v[214:217], v205 offset:3072
	global_load_lds_dwordx4 v[164:165], off
	v_lshl_add_u64 v[164:165], v[218:219], 0, s[8:9]
	s_add_i32 m0, s17, 0x2000
	s_nop 0
	global_load_lds_dwordx4 v[164:165], off
	s_barrier
; #define PG8_STAGE(bufoff, gbase, voff) do { _Pragma("unroll") for (int _i = 0; _i < 2; ++_i) \
;         __builtin_amdgcn_global_load_lds((const unsigned*)((const char*)(gbase) + (voff)[_i]), (LAS unsigned*)(lds + (bufoff) + ldsw + _i * 8192), 16, 0, 0); } while (0)
; #define PG8_LDA(dst, b, h) do { _Pragma("unroll") for (int m = 0; m < 4; ++m) _Pragma("unroll") for (int k = 0; k < 2; ++k) dst[m][k] = *(const LAS bf16x8*)(lds + PG8_SA(b, h) + aoff + m * 2048 + k * 1024); } while (0)
; #define PG8_MMA(ai, bj, At, Bt) do { __builtin_amdgcn_s_setprio(1); _Pragma("unroll") for (int m = 0; m < 4; ++m) _Pragma("unroll") for (int n = 0; n < 2; ++n) _Pragma("unroll") for (int k = 0; k < 2; ++k) \
;         acc[ai][bj][m][n] = __builtin_amdgcn_mfma_f32_16x16x32_bf16(Bt[n][k], At[m][k], acc[ai][bj][m][n], 0, 0, 0); __builtin_amdgcn_s_setprio(0); } while (0)
; #define PG8_WAIT_V(n) asm volatile("s_waitcnt vmcnt(" #n ")" ::: "memory")
; #define PG8_WAIT_L(n) asm volatile("s_waitcnt lgkmcnt(" #n ")" ::: "memory")
; #define PG8_BAR __builtin_amdgcn_s_barrier()
; #define PG8_SCHED __builtin_amdgcn_sched_barrier(0)
; template <class Epi>
; DEVI void gemm_phase(LAS unsigned char* lds, const bf16_t* gA, const bf16_t* gBt, const int lda, const int ldb, const int K, const StaticOrder S_, const Epi E) {
;     ...
;             PG8_BAR; PG8_WAIT_L(0); PG8_MMA(0, 1, At, B1); PG8_BAR;
;             PG8_LDA(At, 1, 1); PG8_STAGE(PG8_SA(1, 0), a3, voffA);
;             PG8_BAR; PG8_WAIT_L(0); PG8_MMA(1, 0, At, B0); PG8_BAR; PG8_SCHED;
;             PG8_STAGE(PG8_SB(1, 1), b3 + hstepB, voffB);
;             PG8_WAIT_V(6); PG8_BAR; PG8_MMA(1, 1, At, B1); PG8_BAR;
	s_waitcnt lgkmcnt(0)
	s_waitcnt lgkmcnt(0)
	v_mfma_f32_16x16x32_bf16 v[116:119], v[192:195], v[144:147], v[116:119]
	v_mfma_f32_16x16x32_bf16 v[112:115], v[210:213], v[144:147], v[112:115]
	v_mfma_f32_16x16x32_bf16 v[96:99], v[210:213], v[152:155], v[96:99]
	v_mfma_f32_16x16x32_bf16 v[100:103], v[192:195], v[152:155], v[100:103]
	v_mfma_f32_16x16x32_bf16 v[84:87], v[192:195], v[160:163], v[84:87]
	v_mfma_f32_16x16x32_bf16 v[80:83], v[210:213], v[160:163], v[80:83]
	v_mfma_f32_16x16x32_bf16 v[64:67], v[210:213], v[184:187], v[64:67]
	v_mfma_f32_16x16x32_bf16 v[68:71], v[192:195], v[184:187], v[68:71]
	v_mfma_f32_16x16x32_bf16 v[116:119], v[206:209], v[148:151], v[116:119]
	v_mfma_f32_16x16x32_bf16 v[112:115], v[214:217], v[148:151], v[112:115]
	v_mfma_f32_16x16x32_bf16 v[96:99], v[214:217], v[156:159], v[96:99]
	v_mfma_f32_16x16x32_bf16 v[100:103], v[206:209], v[156:159], v[100:103]
	v_mfma_f32_16x16x32_bf16 v[84:87], v[206:209], v[180:183], v[84:87]
	v_mfma_f32_16x16x32_bf16 v[80:83], v[214:217], v[180:183], v[80:83]
	v_mfma_f32_16x16x32_bf16 v[64:67], v[214:217], v[188:191], v[64:67]
	v_mfma_f32_16x16x32_bf16 v[68:71], v[206:209], v[188:191], v[68:71]
	s_mov_b32 m0, s26
	v_lshl_add_u64 v[164:165], v[220:221], 0, s[8:9]
	s_barrier
	ds_read_b128 v[144:147], v202 offset:49152
	ds_read_b128 v[148:151], v202 offset:50176
	ds_read_b128 v[152:155], v202 offset:51200
	ds_read_b128 v[156:159], v202 offset:52224
	ds_read_b128 v[160:163], v202 offset:53248
	ds_read_b128 v[180:183], v202 offset:54272
	ds_read_b128 v[184:187], v202 offset:55296
	ds_read_b128 v[188:191], v202 offset:56320
	global_load_lds_dwordx4 v[164:165], off
	v_lshl_add_u64 v[164:165], v[222:223], 0, s[8:9]
	s_mov_b32 m0, s27
	s_nop 0
	global_load_lds_dwordx4 v[164:165], off
	s_barrier
	s_waitcnt lgkmcnt(0)
	s_waitcnt lgkmcnt(0)
	v_mfma_f32_16x16x32_bf16 v[60:63], v[128:131], v[144:147], v[60:63]
	v_mfma_f32_16x16x32_bf16 v[56:59], v[136:139], v[144:147], v[56:59]
	v_mfma_f32_16x16x32_bf16 v[40:43], v[136:139], v[152:155], v[40:43]
	v_mfma_f32_16x16x32_bf16 v[44:47], v[128:131], v[152:155], v[44:47]
	v_mfma_f32_16x16x32_bf16 v[28:31], v[128:131], v[160:163], v[28:31]
	v_mfma_f32_16x16x32_bf16 v[24:27], v[136:139], v[160:163], v[24:27]
	v_mfma_f32_16x16x32_bf16 v[8:11], v[136:139], v[184:187], v[8:11]
	v_mfma_f32_16x16x32_bf16 v[12:15], v[128:131], v[184:187], v[12:15]
	v_mfma_f32_16x16x32_bf16 v[60:63], v[132:135], v[148:151], v[60:63]
	v_mfma_f32_16x16x32_bf16 v[56:59], v[140:143], v[148:151], v[56:59]
	v_mfma_f32_16x16x32_bf16 v[40:43], v[140:143], v[156:159], v[40:43]
	v_mfma_f32_16x16x32_bf16 v[44:47], v[132:135], v[156:159], v[44:47]
	v_mfma_f32_16x16x32_bf16 v[28:31], v[132:135], v[180:183], v[28:31]
	v_mfma_f32_16x16x32_bf16 v[24:27], v[140:143], v[180:183], v[24:27]
	v_mfma_f32_16x16x32_bf16 v[8:11], v[140:143], v[188:191], v[8:11]
	v_mfma_f32_16x16x32_bf16 v[12:15], v[132:135], v[188:191], v[12:15]
	s_barrier
	s_add_i32 s16, s16, s20
	v_lshl_add_u64 v[128:129], v[224:225], 0, s[8:9]
	s_mov_b32 m0, s16
	s_nop 0
	global_load_lds_dwordx4 v[128:129], off
	v_lshl_add_u64 v[128:129], v[226:227], 0, s[8:9]
	s_add_i32 m0, s16, 0x2000
	s_nop 0
	global_load_lds_dwordx4 v[128:129], off
	s_waitcnt vmcnt(6)
	s_barrier
	v_mfma_f32_16x16x32_bf16 v[52:55], v[192:195], v[144:147], v[52:55]
	v_mfma_f32_16x16x32_bf16 v[48:51], v[210:213], v[144:147], v[48:51]
	v_mfma_f32_16x16x32_bf16 v[32:35], v[210:213], v[152:155], v[32:35]
	v_mfma_f32_16x16x32_bf16 v[36:39], v[192:195], v[152:155], v[36:39]
	v_mfma_f32_16x16x32_bf16 v[20:23], v[192:195], v[160:163], v[20:23]
	v_mfma_f32_16x16x32_bf16 v[16:19], v[210:213], v[160:163], v[16:19]
	v_mfma_f32_16x16x32_bf16 v[0:3], v[210:213], v[184:187], v[0:3]
	v_mfma_f32_16x16x32_bf16 v[4:7], v[192:195], v[184:187], v[4:7]
	v_mfma_f32_16x16x32_bf16 v[52:55], v[206:209], v[148:151], v[52:55]
	v_mfma_f32_16x16x32_bf16 v[48:51], v[214:217], v[148:151], v[48:51]
	v_mfma_f32_16x16x32_bf16 v[32:35], v[214:217], v[156:159], v[32:35]
	v_mfma_f32_16x16x32_bf16 v[36:39], v[206:209], v[156:159], v[36:39]
	v_mfma_f32_16x16x32_bf16 v[20:23], v[206:209], v[180:183], v[20:23]
	v_mfma_f32_16x16x32_bf16 v[16:19], v[214:217], v[180:183], v[16:19]
	v_mfma_f32_16x16x32_bf16 v[0:3], v[214:217], v[188:191], v[0:3]
	v_mfma_f32_16x16x32_bf16 v[4:7], v[206:209], v[188:191], v[4:7]
	s_add_u32 s14, s14, 0x100
	s_addc_u32 s15, s15, 0
	s_add_u32 s48, s48, 0x100
	s_addc_u32 s49, s49, 0
	s_cmp_ge_i32 s60, s25
	s_mov_b32 s16, s60
	s_barrier
	s_cbranch_scc0 .LBB0_2366

; #define PG8_STAGE(bufoff, gbase, voff) do { _Pragma("unroll") for (int _i = 0; _i < 2; ++_i) \
;         __builtin_amdgcn_global_load_lds((const unsigned*)((const char*)(gbase) + (voff)[_i]), (LAS unsigned*)(lds + (bufoff) + ldsw + _i * 8192), 16, 0, 0); } while (0)
; #define PG8_LDA(dst, b, h) do { _Pragma("unroll") for (int m = 0; m < 4; ++m) _Pragma("unroll") for (int k = 0; k < 2; ++k) dst[m][k] = *(const LAS bf16x8*)(lds + PG8_SA(b, h) + aoff + m * 2048 + k * 1024); } while (0)
; #define PG8_LDB(dst, b, h) do { _Pragma("unroll") for (int n = 0; n < 2; ++n) _Pragma("unroll") for (int k = 0; k < 2; ++k) dst[n][k] = *(const LAS bf16x8*)(lds + PG8_SB(b, h) + boff + n * 2048 + k * 1024); } while (0)
; #define PG8_MMA(ai, bj, At, Bt) do { __builtin_amdgcn_s_setprio(1); _Pragma("unroll") for (int m = 0; m < 4; ++m) _Pragma("unroll") for (int n = 0; n < 2; ++n) _Pragma("unroll") for (int k = 0; k < 2; ++k) \
;         acc[ai][bj][m][n] = __builtin_amdgcn_mfma_f32_16x16x32_bf16(Bt[n][k], At[m][k], acc[ai][bj][m][n], 0, 0, 0); __builtin_amdgcn_s_setprio(0); } while (0)
; #define PG8_WAIT_L(n) asm volatile("s_waitcnt lgkmcnt(" #n ")" ::: "memory")
; #define PG8_BAR __builtin_amdgcn_s_barrier()
; #define PG8_SCHED __builtin_amdgcn_sched_barrier(0)
; template <class Epi>
; DEVI void gemm_phase(LAS unsigned char* lds, const bf16_t* gA, const bf16_t* gBt, const int lda, const int ldb, const int K, const StaticOrder S_, const Epi E) {
;     ...
;             const bool last = (t == nt - 2);
;             const char* a1 = cA + (size_t)(t + 1) * kstep;
;             const char* a2 = last ? nA : cA + (size_t)(t + 2) * kstep; const char* b2 = last ? nB : cB + (size_t)(t + 2) * kstep;
;             const char* a3 = a2 + kstep; const char* b3 = b2 + kstep;
;             PG8_LDB(B0, 0, 0); PG8_SCHED; PG8_LDA(At, 0, 0); PG8_STAGE(PG8_SA(1, 1), a1 + hstepA, voffA);
;             PG8_WAIT_L(8); PG8_BAR; PG8_WAIT_L(0); PG8_MMA(0, 0, At, B0); PG8_BAR; PG8_SCHED;
;             PG8_LDB(B1, 0, 1); PG8_STAGE(PG8_SB(0, 0), b2, voffB);
;             PG8_BAR; PG8_WAIT_L(0); PG8_MMA(0, 1, At, B1); PG8_BAR;
;             PG8_LDA(At, 0, 1); PG8_STAGE(PG8_SA(0, 0), a2, voffA);
;             PG8_BAR; PG8_WAIT_L(0); PG8_MMA(1, 0, At, B0); PG8_BAR; PG8_SCHED;
.LBB0_2510:
	ds_read_b128 v[158:161], v151
	ds_read_b128 v[162:165], v151 offset:1024
	ds_read_b128 v[166:169], v151 offset:2048
	ds_read_b128 v[170:173], v151 offset:3072
	s_add_i32 s61, s16, 2
	s_add_u32 s48, s14, 0x80
	s_addc_u32 s17, s15, 0
	s_cmp_eq_u32 s26, s16
	s_cselect_b32 s16, s38, s48
	s_cselect_b32 s17, s39, s17
	s_cselect_b32 s49, s47, s60
	s_cselect_b32 s48, s46, s59
	v_lshl_add_u64 v[144:145], s[14:15], 0, v[138:139]
	s_add_i32 m0, s19, 0xc000
	ds_read_b128 v[174:177], v152
	ds_read_b128 v[178:181], v152 offset:1024
	ds_read_b128 v[182:185], v152 offset:2048
	ds_read_b128 v[186:189], v152 offset:3072
	ds_read_b128 v[190:193], v152 offset:4096
	ds_read_b128 v[198:201], v152 offset:5120
	ds_read_b128 v[202:205], v152 offset:6144
	ds_read_b128 v[206:209], v152 offset:7168
	global_load_lds_dwordx4 v[144:145], off
	v_lshl_add_u64 v[144:145], s[14:15], 0, v[140:141]
	s_add_i32 m0, s19, 0xe000
	s_nop 0
	global_load_lds_dwordx4 v[144:145], off
	s_waitcnt lgkmcnt(8)
	s_barrier
	s_waitcnt lgkmcnt(0)
	s_waitcnt lgkmcnt(0)
	v_mfma_f32_16x16x32_bf16 v[120:123], v[158:161], v[174:177], v[120:123]
	v_mfma_f32_16x16x32_bf16 v[116:119], v[166:169], v[174:177], v[116:119]
	v_mfma_f32_16x16x32_bf16 v[100:103], v[166:169], v[182:185], v[100:103]
	v_mfma_f32_16x16x32_bf16 v[108:111], v[158:161], v[182:185], v[108:111]
	v_mfma_f32_16x16x32_bf16 v[92:95], v[158:161], v[190:193], v[92:95]
	v_mfma_f32_16x16x32_bf16 v[84:87], v[166:169], v[190:193], v[84:87]
	v_mfma_f32_16x16x32_bf16 v[68:71], v[166:169], v[202:205], v[68:71]
	v_mfma_f32_16x16x32_bf16 v[76:79], v[158:161], v[202:205], v[76:79]
	v_mfma_f32_16x16x32_bf16 v[120:123], v[162:165], v[178:181], v[120:123]
	v_mfma_f32_16x16x32_bf16 v[116:119], v[170:173], v[178:181], v[116:119]
	v_mfma_f32_16x16x32_bf16 v[100:103], v[170:173], v[186:189], v[100:103]
	v_mfma_f32_16x16x32_bf16 v[108:111], v[162:165], v[186:189], v[108:111]
	v_mfma_f32_16x16x32_bf16 v[92:95], v[162:165], v[198:201], v[92:95]
	v_mfma_f32_16x16x32_bf16 v[84:87], v[170:173], v[198:201], v[84:87]
	v_mfma_f32_16x16x32_bf16 v[68:71], v[170:173], v[206:209], v[68:71]
	v_mfma_f32_16x16x32_bf16 v[76:79], v[162:165], v[206:209], v[76:79]
	s_barrier
	s_add_i32 s62, s30, s18
	v_lshl_add_u64 v[144:145], s[48:49], 0, v[130:131]
	s_mov_b32 m0, s62
	ds_read_b128 v[210:213], v153
	ds_read_b128 v[214:217], v153 offset:1024
	ds_read_b128 v[218:221], v153 offset:2048
	ds_read_b128 v[222:225], v153 offset:3072
	global_load_lds_dwordx4 v[144:145], off
	v_lshl_add_u64 v[194:195], s[48:49], 0, v[134:135]
	s_add_i32 m0, s62, 0x2000
	s_nop 0
	global_load_lds_dwordx4 v[194:195], off
	s_barrier
	s_waitcnt lgkmcnt(0)
	s_waitcnt lgkmcnt(0)
	v_mfma_f32_16x16x32_bf16 v[124:127], v[210:213], v[174:177], v[124:127]
	v_mfma_f32_16x16x32_bf16 v[112:115], v[218:221], v[174:177], v[112:115]
	v_mfma_f32_16x16x32_bf16 v[96:99], v[218:221], v[182:185], v[96:99]
	v_mfma_f32_16x16x32_bf16 v[104:107], v[210:213], v[182:185], v[104:107]
	v_mfma_f32_16x16x32_bf16 v[88:91], v[210:213], v[190:193], v[88:91]
	v_mfma_f32_16x16x32_bf16 v[80:83], v[218:221], v[190:193], v[80:83]
	v_mfma_f32_16x16x32_bf16 v[64:67], v[218:221], v[202:205], v[64:67]
	v_mfma_f32_16x16x32_bf16 v[72:75], v[210:213], v[202:205], v[72:75]
	v_mfma_f32_16x16x32_bf16 v[124:127], v[214:217], v[178:181], v[124:127]
	v_mfma_f32_16x16x32_bf16 v[112:115], v[222:225], v[178:181], v[112:115]
	v_mfma_f32_16x16x32_bf16 v[96:99], v[222:225], v[186:189], v[96:99]
	v_mfma_f32_16x16x32_bf16 v[104:107], v[214:217], v[186:189], v[104:107]
	v_mfma_f32_16x16x32_bf16 v[88:91], v[214:217], v[198:201], v[88:91]
	v_mfma_f32_16x16x32_bf16 v[80:83], v[222:225], v[198:201], v[80:83]
	v_mfma_f32_16x16x32_bf16 v[64:67], v[222:225], v[206:209], v[64:67]
	v_mfma_f32_16x16x32_bf16 v[72:75], v[214:217], v[206:209], v[72:75]
	s_mov_b32 m0, s19
	v_lshl_add_u64 v[226:227], s[16:17], 0, v[128:129]
	s_barrier
	ds_read_b128 v[174:177], v152 offset:16384
	ds_read_b128 v[178:181], v152 offset:17408
	ds_read_b128 v[182:185], v152 offset:18432
	ds_read_b128 v[186:189], v152 offset:19456
	ds_read_b128 v[190:193], v152 offset:20480
	ds_read_b128 v[198:201], v152 offset:21504
	ds_read_b128 v[202:205], v152 offset:22528
	ds_read_b128 v[206:209], v152 offset:23552
	global_load_lds_dwordx4 v[226:227], off
	v_lshl_add_u64 v[228:229], s[16:17], 0, v[132:133]
	s_mov_b32 m0, s20
	s_nop 0
	global_load_lds_dwordx4 v[228:229], off
	s_barrier
	s_waitcnt lgkmcnt(0)
	s_waitcnt lgkmcnt(0)
	v_mfma_f32_16x16x32_bf16 v[60:63], v[158:161], v[174:177], v[60:63]
	v_mfma_f32_16x16x32_bf16 v[56:59], v[166:169], v[174:177], v[56:59]
	v_mfma_f32_16x16x32_bf16 v[40:43], v[166:169], v[182:185], v[40:43]
	v_mfma_f32_16x16x32_bf16 v[44:47], v[158:161], v[182:185], v[44:47]
	v_mfma_f32_16x16x32_bf16 v[28:31], v[158:161], v[190:193], v[28:31]
	v_mfma_f32_16x16x32_bf16 v[24:27], v[166:169], v[190:193], v[24:27]
	v_mfma_f32_16x16x32_bf16 v[8:11], v[166:169], v[202:205], v[8:11]
	v_mfma_f32_16x16x32_bf16 v[12:15], v[158:161], v[202:205], v[12:15]
	v_mfma_f32_16x16x32_bf16 v[60:63], v[162:165], v[178:181], v[60:63]
	v_mfma_f32_16x16x32_bf16 v[56:59], v[170:173], v[178:181], v[56:59]
	v_mfma_f32_16x16x32_bf16 v[40:43], v[170:173], v[186:189], v[40:43]
	v_mfma_f32_16x16x32_bf16 v[44:47], v[162:165], v[186:189], v[44:47]
	v_mfma_f32_16x16x32_bf16 v[28:31], v[162:165], v[198:201], v[28:31]
	v_mfma_f32_16x16x32_bf16 v[24:27], v[170:173], v[198:201], v[24:27]
	v_mfma_f32_16x16x32_bf16 v[8:11], v[170:173], v[206:209], v[8:11]
	v_mfma_f32_16x16x32_bf16 v[12:15], v[162:165], v[206:209], v[12:15]
	s_barrier
; #define PG8_STAGE(bufoff, gbase, voff) do { _Pragma("unroll") for (int _i = 0; _i < 2; ++_i) \
;         __builtin_amdgcn_global_load_lds((const unsigned*)((const char*)(gbase) + (voff)[_i]), (LAS unsigned*)(lds + (bufoff) + ldsw + _i * 8192), 16, 0, 0); } while (0)
; #define PG8_LDA(dst, b, h) do { _Pragma("unroll") for (int m = 0; m < 4; ++m) _Pragma("unroll") for (int k = 0; k < 2; ++k) dst[m][k] = *(const LAS bf16x8*)(lds + PG8_SA(b, h) + aoff + m * 2048 + k * 1024); } while (0)
; #define PG8_LDB(dst, b, h) do { _Pragma("unroll") for (int n = 0; n < 2; ++n) _Pragma("unroll") for (int k = 0; k < 2; ++k) dst[n][k] = *(const LAS bf16x8*)(lds + PG8_SB(b, h) + boff + n * 2048 + k * 1024); } while (0)
; #define PG8_MMA(ai, bj, At, Bt) do { __builtin_amdgcn_s_setprio(1); _Pragma("unroll") for (int m = 0; m < 4; ++m) _Pragma("unroll") for (int n = 0; n < 2; ++n) _Pragma("unroll") for (int k = 0; k < 2; ++k) \
;         acc[ai][bj][m][n] = __builtin_amdgcn_mfma_f32_16x16x32_bf16(Bt[n][k], At[m][k], acc[ai][bj][m][n], 0, 0, 0); __builtin_amdgcn_s_setprio(0); } while (0)
; #define PG8_WAIT_V(n) asm volatile("s_waitcnt vmcnt(" #n ")" ::: "memory")
; #define PG8_WAIT_L(n) asm volatile("s_waitcnt lgkmcnt(" #n ")" ::: "memory")
; #define PG8_BAR __builtin_amdgcn_s_barrier()
; #define PG8_SCHED __builtin_amdgcn_sched_barrier(0)
; template <class Epi>
; DEVI void gemm_phase(LAS unsigned char* lds, const bf16_t* gA, const bf16_t* gBt, const int lda, const int ldb, const int K, const StaticOrder S_, const Epi E) {
;     ...
;             PG8_STAGE(PG8_SB(0, 1), b2 + hstepB, voffB);
;             PG8_WAIT_V(6); PG8_BAR; PG8_MMA(1, 1, At, B1); PG8_BAR;
;             PG8_LDB(B0, 1, 0); PG8_SCHED; PG8_LDA(At, 1, 0); PG8_STAGE(PG8_SA(0, 1), a2 + hstepA, voffA);
;             PG8_WAIT_L(8); PG8_BAR; PG8_WAIT_L(0); PG8_MMA(0, 0, At, B0); PG8_BAR; PG8_SCHED;
;             PG8_LDB(B1, 1, 1); PG8_STAGE(PG8_SB(1, 0), b3, voffB);
	s_add_u32 s48, s48, s2
	s_addc_u32 s49, s49, s3
	s_add_i32 s62, s50, s18
	v_lshl_add_u64 v[230:231], s[48:49], 0, v[130:131]
	s_mov_b32 m0, s62
	v_lshl_add_u64 v[232:233], s[48:49], 0, v[134:135]
	global_load_lds_dwordx4 v[230:231], off
	s_add_i32 m0, s62, 0x2000
	s_nop 0
	global_load_lds_dwordx4 v[232:233], off
	s_waitcnt vmcnt(6)
	s_barrier
	v_mfma_f32_16x16x32_bf16 v[52:55], v[210:213], v[174:177], v[52:55]
	v_mfma_f32_16x16x32_bf16 v[48:51], v[218:221], v[174:177], v[48:51]
	v_mfma_f32_16x16x32_bf16 v[32:35], v[218:221], v[182:185], v[32:35]
	v_mfma_f32_16x16x32_bf16 v[36:39], v[210:213], v[182:185], v[36:39]
	v_mfma_f32_16x16x32_bf16 v[20:23], v[210:213], v[190:193], v[20:23]
	v_mfma_f32_16x16x32_bf16 v[16:19], v[218:221], v[190:193], v[16:19]
	v_mfma_f32_16x16x32_bf16 v[0:3], v[218:221], v[202:205], v[0:3]
	v_mfma_f32_16x16x32_bf16 v[4:7], v[210:213], v[202:205], v[4:7]
	v_mfma_f32_16x16x32_bf16 v[52:55], v[214:217], v[178:181], v[52:55]
	v_mfma_f32_16x16x32_bf16 v[48:51], v[222:225], v[178:181], v[48:51]
	v_mfma_f32_16x16x32_bf16 v[32:35], v[222:225], v[186:189], v[32:35]
	v_mfma_f32_16x16x32_bf16 v[36:39], v[214:217], v[186:189], v[36:39]
	v_mfma_f32_16x16x32_bf16 v[20:23], v[214:217], v[198:201], v[20:23]
	v_mfma_f32_16x16x32_bf16 v[16:19], v[222:225], v[198:201], v[16:19]
	v_mfma_f32_16x16x32_bf16 v[0:3], v[222:225], v[206:209], v[0:3]
	v_mfma_f32_16x16x32_bf16 v[4:7], v[214:217], v[206:209], v[4:7]
	s_barrier
	ds_read_b128 v[158:161], v154
	ds_read_b128 v[162:165], v154 offset:1024
	ds_read_b128 v[166:169], v154 offset:2048
	ds_read_b128 v[170:173], v154 offset:3072
	s_add_u32 s16, s16, s0
	s_addc_u32 s17, s17, s1
	s_mov_b32 m0, s21
	v_lshl_add_u64 v[210:211], s[16:17], 0, v[128:129]
	ds_read_b128 v[174:177], v152 offset:32768
	ds_read_b128 v[178:181], v152 offset:33792
	ds_read_b128 v[182:185], v152 offset:34816
	ds_read_b128 v[186:189], v152 offset:35840
	ds_read_b128 v[190:193], v152 offset:36864
	ds_read_b128 v[198:201], v152 offset:37888
	ds_read_b128 v[202:205], v152 offset:38912
	ds_read_b128 v[206:209], v152 offset:39936
	global_load_lds_dwordx4 v[210:211], off
	v_lshl_add_u64 v[210:211], s[16:17], 0, v[132:133]
	s_mov_b32 m0, s22
	s_nop 0
	global_load_lds_dwordx4 v[210:211], off
	s_waitcnt lgkmcnt(8)
	s_barrier
	s_waitcnt lgkmcnt(0)
	s_waitcnt lgkmcnt(0)
	v_mfma_f32_16x16x32_bf16 v[120:123], v[158:161], v[174:177], v[120:123]
	v_mfma_f32_16x16x32_bf16 v[116:119], v[166:169], v[174:177], v[116:119]
	v_mfma_f32_16x16x32_bf16 v[100:103], v[166:169], v[182:185], v[100:103]
	v_mfma_f32_16x16x32_bf16 v[108:111], v[158:161], v[182:185], v[108:111]
	v_mfma_f32_16x16x32_bf16 v[92:95], v[158:161], v[190:193], v[92:95]
	v_mfma_f32_16x16x32_bf16 v[84:87], v[166:169], v[190:193], v[84:87]
	v_mfma_f32_16x16x32_bf16 v[68:71], v[166:169], v[202:205], v[68:71]
	v_mfma_f32_16x16x32_bf16 v[76:79], v[158:161], v[202:205], v[76:79]
	v_mfma_f32_16x16x32_bf16 v[120:123], v[162:165], v[178:181], v[120:123]
	v_mfma_f32_16x16x32_bf16 v[116:119], v[170:173], v[178:181], v[116:119]
	v_mfma_f32_16x16x32_bf16 v[100:103], v[170:173], v[186:189], v[100:103]
	v_mfma_f32_16x16x32_bf16 v[108:111], v[162:165], v[186:189], v[108:111]
	v_mfma_f32_16x16x32_bf16 v[92:95], v[162:165], v[198:201], v[92:95]
	v_mfma_f32_16x16x32_bf16 v[84:87], v[170:173], v[198:201], v[84:87]
	v_mfma_f32_16x16x32_bf16 v[68:71], v[170:173], v[206:209], v[68:71]
	v_mfma_f32_16x16x32_bf16 v[76:79], v[162:165], v[206:209], v[76:79]
	s_barrier
	s_add_i32 s16, s51, s18
	v_lshl_add_u64 v[144:145], v[144:145], 0, s[44:45]
	s_mov_b32 m0, s16
	ds_read_b128 v[210:213], v155
	ds_read_b128 v[214:217], v155 offset:1024
	ds_read_b128 v[218:221], v155 offset:2048
	ds_read_b128 v[222:225], v155 offset:3072
	global_load_lds_dwordx4 v[144:145], off
	v_lshl_add_u64 v[144:145], v[194:195], 0, s[44:45]
	s_add_i32 m0, s16, 0x2000
	s_nop 0
	global_load_lds_dwordx4 v[144:145], off
	s_barrier
; #define PG8_STAGE(bufoff, gbase, voff) do { _Pragma("unroll") for (int _i = 0; _i < 2; ++_i) \
;         __builtin_amdgcn_global_load_lds((const unsigned*)((const char*)(gbase) + (voff)[_i]), (LAS unsigned*)(lds + (bufoff) + ldsw + _i * 8192), 16, 0, 0); } while (0)
; #define PG8_LDA(dst, b, h) do { _Pragma("unroll") for (int m = 0; m < 4; ++m) _Pragma("unroll") for (int k = 0; k < 2; ++k) dst[m][k] = *(const LAS bf16x8*)(lds + PG8_SA(b, h) + aoff + m * 2048 + k * 1024); } while (0)
; #define PG8_MMA(ai, bj, At, Bt) do { __builtin_amdgcn_s_setprio(1); _Pragma("unroll") for (int m = 0; m < 4; ++m) _Pragma("unroll") for (int n = 0; n < 2; ++n) _Pragma("unroll") for (int k = 0; k < 2; ++k) \
;         acc[ai][bj][m][n] = __builtin_amdgcn_mfma_f32_16x16x32_bf16(Bt[n][k], At[m][k], acc[ai][bj][m][n], 0, 0, 0); __builtin_amdgcn_s_setprio(0); } while (0)
; #define PG8_WAIT_V(n) asm volatile("s_waitcnt vmcnt(" #n ")" ::: "memory")
; #define PG8_WAIT_L(n) asm volatile("s_waitcnt lgkmcnt(" #n ")" ::: "memory")
; #define PG8_BAR __builtin_amdgcn_s_barrier()
; #define PG8_SCHED __builtin_amdgcn_sched_barrier(0)
; template <class Epi>
; DEVI void gemm_phase(LAS unsigned char* lds, const bf16_t* gA, const bf16_t* gBt, const int lda, const int ldb, const int K, const StaticOrder S_, const Epi E) {
;     ...
;             PG8_BAR; PG8_WAIT_L(0); PG8_MMA(0, 1, At, B1); PG8_BAR;
;             PG8_LDA(At, 1, 1); PG8_STAGE(PG8_SA(1, 0), a3, voffA);
;             PG8_BAR; PG8_WAIT_L(0); PG8_MMA(1, 0, At, B0); PG8_BAR; PG8_SCHED;
;             PG8_STAGE(PG8_SB(1, 1), b3 + hstepB, voffB);
;             PG8_WAIT_V(6); PG8_BAR; PG8_MMA(1, 1, At, B1); PG8_BAR;
	s_waitcnt lgkmcnt(0)
	s_waitcnt lgkmcnt(0)
	v_mfma_f32_16x16x32_bf16 v[124:127], v[210:213], v[174:177], v[124:127]
	v_mfma_f32_16x16x32_bf16 v[112:115], v[218:221], v[174:177], v[112:115]
	v_mfma_f32_16x16x32_bf16 v[96:99], v[218:221], v[182:185], v[96:99]
	v_mfma_f32_16x16x32_bf16 v[104:107], v[210:213], v[182:185], v[104:107]
	v_mfma_f32_16x16x32_bf16 v[88:91], v[210:213], v[190:193], v[88:91]
	v_mfma_f32_16x16x32_bf16 v[80:83], v[218:221], v[190:193], v[80:83]
	v_mfma_f32_16x16x32_bf16 v[64:67], v[218:221], v[202:205], v[64:67]
	v_mfma_f32_16x16x32_bf16 v[72:75], v[210:213], v[202:205], v[72:75]
	v_mfma_f32_16x16x32_bf16 v[124:127], v[214:217], v[178:181], v[124:127]
	v_mfma_f32_16x16x32_bf16 v[112:115], v[222:225], v[178:181], v[112:115]
	v_mfma_f32_16x16x32_bf16 v[96:99], v[222:225], v[186:189], v[96:99]
	v_mfma_f32_16x16x32_bf16 v[104:107], v[214:217], v[186:189], v[104:107]
	v_mfma_f32_16x16x32_bf16 v[88:91], v[214:217], v[198:201], v[88:91]
	v_mfma_f32_16x16x32_bf16 v[80:83], v[222:225], v[198:201], v[80:83]
	v_mfma_f32_16x16x32_bf16 v[64:67], v[222:225], v[206:209], v[64:67]
	v_mfma_f32_16x16x32_bf16 v[72:75], v[214:217], v[206:209], v[72:75]
	s_mov_b32 m0, s23
	v_lshl_add_u64 v[144:145], v[226:227], 0, s[44:45]
	s_barrier
	ds_read_b128 v[174:177], v152 offset:49152
	ds_read_b128 v[178:181], v152 offset:50176
	ds_read_b128 v[182:185], v152 offset:51200
	ds_read_b128 v[186:189], v152 offset:52224
	ds_read_b128 v[190:193], v152 offset:53248
	ds_read_b128 v[198:201], v152 offset:54272
	ds_read_b128 v[202:205], v152 offset:55296
	ds_read_b128 v[206:209], v152 offset:56320
	global_load_lds_dwordx4 v[144:145], off
	v_lshl_add_u64 v[144:145], v[228:229], 0, s[44:45]
	s_mov_b32 m0, s24
	s_nop 0
	global_load_lds_dwordx4 v[144:145], off
	s_barrier
	s_waitcnt lgkmcnt(0)
	s_waitcnt lgkmcnt(0)
	v_mfma_f32_16x16x32_bf16 v[60:63], v[158:161], v[174:177], v[60:63]
	v_mfma_f32_16x16x32_bf16 v[56:59], v[166:169], v[174:177], v[56:59]
	v_mfma_f32_16x16x32_bf16 v[40:43], v[166:169], v[182:185], v[40:43]
	v_mfma_f32_16x16x32_bf16 v[44:47], v[158:161], v[182:185], v[44:47]
	v_mfma_f32_16x16x32_bf16 v[28:31], v[158:161], v[190:193], v[28:31]
	v_mfma_f32_16x16x32_bf16 v[24:27], v[166:169], v[190:193], v[24:27]
	v_mfma_f32_16x16x32_bf16 v[8:11], v[166:169], v[202:205], v[8:11]
	v_mfma_f32_16x16x32_bf16 v[12:15], v[158:161], v[202:205], v[12:15]
	v_mfma_f32_16x16x32_bf16 v[60:63], v[162:165], v[178:181], v[60:63]
	v_mfma_f32_16x16x32_bf16 v[56:59], v[170:173], v[178:181], v[56:59]
	v_mfma_f32_16x16x32_bf16 v[40:43], v[170:173], v[186:189], v[40:43]
	v_mfma_f32_16x16x32_bf16 v[44:47], v[162:165], v[186:189], v[44:47]
	v_mfma_f32_16x16x32_bf16 v[28:31], v[162:165], v[198:201], v[28:31]
	v_mfma_f32_16x16x32_bf16 v[24:27], v[170:173], v[198:201], v[24:27]
	v_mfma_f32_16x16x32_bf16 v[8:11], v[170:173], v[206:209], v[8:11]
	v_mfma_f32_16x16x32_bf16 v[12:15], v[162:165], v[206:209], v[12:15]
	s_barrier
	s_add_i32 s16, s31, s18
	v_lshl_add_u64 v[144:145], v[230:231], 0, s[44:45]
	s_mov_b32 m0, s16
	s_nop 0
	global_load_lds_dwordx4 v[144:145], off
	v_lshl_add_u64 v[144:145], v[232:233], 0, s[44:45]
	s_add_i32 m0, s16, 0x2000
	s_nop 0
	global_load_lds_dwordx4 v[144:145], off
	s_waitcnt vmcnt(6)
	s_barrier
	v_mfma_f32_16x16x32_bf16 v[52:55], v[210:213], v[174:177], v[52:55]
	v_mfma_f32_16x16x32_bf16 v[48:51], v[218:221], v[174:177], v[48:51]
	v_mfma_f32_16x16x32_bf16 v[32:35], v[218:221], v[182:185], v[32:35]
	v_mfma_f32_16x16x32_bf16 v[36:39], v[210:213], v[182:185], v[36:39]
	v_mfma_f32_16x16x32_bf16 v[20:23], v[210:213], v[190:193], v[20:23]
	v_mfma_f32_16x16x32_bf16 v[16:19], v[218:221], v[190:193], v[16:19]
	v_mfma_f32_16x16x32_bf16 v[0:3], v[218:221], v[202:205], v[0:3]
	v_mfma_f32_16x16x32_bf16 v[4:7], v[210:213], v[202:205], v[4:7]
	v_mfma_f32_16x16x32_bf16 v[52:55], v[214:217], v[178:181], v[52:55]
	v_mfma_f32_16x16x32_bf16 v[48:51], v[222:225], v[178:181], v[48:51]
	v_mfma_f32_16x16x32_bf16 v[32:35], v[222:225], v[186:189], v[32:35]
	v_mfma_f32_16x16x32_bf16 v[36:39], v[214:217], v[186:189], v[36:39]
	v_mfma_f32_16x16x32_bf16 v[20:23], v[214:217], v[198:201], v[20:23]
	v_mfma_f32_16x16x32_bf16 v[16:19], v[222:225], v[198:201], v[16:19]
	v_mfma_f32_16x16x32_bf16 v[0:3], v[222:225], v[206:209], v[0:3]
	v_mfma_f32_16x16x32_bf16 v[4:7], v[214:217], v[206:209], v[4:7]
	s_add_u32 s14, s14, 0x100
	s_addc_u32 s15, s15, 0
	s_add_u32 s59, s59, 0x100
	s_addc_u32 s60, s60, 0
	s_cmp_ge_i32 s61, s25
	s_mov_b32 s16, s61
	s_barrier
	s_cbranch_scc0 .LBB0_2510

; #define PG8_STAGE(bufoff, gbase, voff) do { _Pragma("unroll") for (int _i = 0; _i < 2; ++_i) \
;         __builtin_amdgcn_global_load_lds((const unsigned*)((const char*)(gbase) + (voff)[_i]), (LAS unsigned*)(lds + (bufoff) + ldsw + _i * 8192), 16, 0, 0); } while (0)
; #define PG8_LDA(dst, b, h) do { _Pragma("unroll") for (int m = 0; m < 4; ++m) _Pragma("unroll") for (int k = 0; k < 2; ++k) dst[m][k] = *(const LAS bf16x8*)(lds + PG8_SA(b, h) + aoff + m * 2048 + k * 1024); } while (0)
; #define PG8_LDB(dst, b, h) do { _Pragma("unroll") for (int n = 0; n < 2; ++n) _Pragma("unroll") for (int k = 0; k < 2; ++k) dst[n][k] = *(const LAS bf16x8*)(lds + PG8_SB(b, h) + boff + n * 2048 + k * 1024); } while (0)
; #define PG8_MMA(ai, bj, At, Bt) do { __builtin_amdgcn_s_setprio(1); _Pragma("unroll") for (int m = 0; m < 4; ++m) _Pragma("unroll") for (int n = 0; n < 2; ++n) _Pragma("unroll") for (int k = 0; k < 2; ++k) \
;         acc[ai][bj][m][n] = __builtin_amdgcn_mfma_f32_16x16x32_bf16(Bt[n][k], At[m][k], acc[ai][bj][m][n], 0, 0, 0); __builtin_amdgcn_s_setprio(0); } while (0)
; #define PG8_WAIT_L(n) asm volatile("s_waitcnt lgkmcnt(" #n ")" ::: "memory")
; #define PG8_BAR __builtin_amdgcn_s_barrier()
; #define PG8_SCHED __builtin_amdgcn_sched_barrier(0)
; template <class Epi>
; DEVI void gemm_phase(LAS unsigned char* lds, const bf16_t* gA, const bf16_t* gBt, const int lda, const int ldb, const int K, const StaticOrder S_, const Epi E) {
;     ...
;             const bool last = (t == nt - 2);
;             const char* a1 = cA + (size_t)(t + 1) * kstep;
;             const char* a2 = last ? nA : cA + (size_t)(t + 2) * kstep; const char* b2 = last ? nB : cB + (size_t)(t + 2) * kstep;
;             const char* a3 = a2 + kstep; const char* b3 = b2 + kstep;
;             PG8_LDB(B0, 0, 0); PG8_SCHED; PG8_LDA(At, 0, 0); PG8_STAGE(PG8_SA(1, 1), a1 + hstepA, voffA);
;             PG8_WAIT_L(8); PG8_BAR; PG8_WAIT_L(0); PG8_MMA(0, 0, At, B0); PG8_BAR; PG8_SCHED;
;             PG8_LDB(B1, 0, 1); PG8_STAGE(PG8_SB(0, 0), b2, voffB);
;             PG8_BAR; PG8_WAIT_L(0); PG8_MMA(0, 1, At, B1); PG8_BAR;
;             PG8_LDA(At, 0, 1); PG8_STAGE(PG8_SA(0, 0), a2, voffA);
;             PG8_BAR; PG8_WAIT_L(0); PG8_MMA(1, 0, At, B0); PG8_BAR; PG8_SCHED;
.LBB0_2589:
	ds_read_b128 v[128:131], v200
	ds_read_b128 v[132:135], v200 offset:1024
	ds_read_b128 v[136:139], v200 offset:2048
	ds_read_b128 v[140:143], v200 offset:3072
	s_add_i32 s56, s24, 2
	s_add_u32 s26, s4, 0x80
	s_addc_u32 s25, s5, 0
	s_cmp_eq_u32 s43, s24
	s_cselect_b32 s24, s22, s26
	s_cselect_b32 s25, s23, s25
	s_cselect_b32 s27, s7, s55
	s_cselect_b32 s26, s6, s54
	v_lshl_add_u64 v[164:165], s[4:5], 0, v[174:175]
	s_add_i32 m0, s34, 0xc000
	ds_read_b128 v[144:147], v201
	ds_read_b128 v[148:151], v201 offset:1024
	ds_read_b128 v[152:155], v201 offset:2048
	ds_read_b128 v[156:159], v201 offset:3072
	ds_read_b128 v[160:163], v201 offset:4096
	ds_read_b128 v[180:183], v201 offset:5120
	ds_read_b128 v[184:187], v201 offset:6144
	ds_read_b128 v[188:191], v201 offset:7168
	global_load_lds_dwordx4 v[164:165], off
	v_lshl_add_u64 v[164:165], s[4:5], 0, v[176:177]
	s_add_i32 m0, s34, 0xe000
	s_nop 0
	global_load_lds_dwordx4 v[164:165], off
	s_waitcnt lgkmcnt(8)
	s_barrier
	s_waitcnt lgkmcnt(0)
	s_waitcnt lgkmcnt(0)
	v_mfma_f32_16x16x32_bf16 v[124:127], v[128:131], v[144:147], v[124:127]
	v_mfma_f32_16x16x32_bf16 v[120:123], v[136:139], v[144:147], v[120:123]
	v_mfma_f32_16x16x32_bf16 v[104:107], v[136:139], v[152:155], v[104:107]
	v_mfma_f32_16x16x32_bf16 v[108:111], v[128:131], v[152:155], v[108:111]
	v_mfma_f32_16x16x32_bf16 v[92:95], v[128:131], v[160:163], v[92:95]
	v_mfma_f32_16x16x32_bf16 v[88:91], v[136:139], v[160:163], v[88:91]
	v_mfma_f32_16x16x32_bf16 v[72:75], v[136:139], v[184:187], v[72:75]
	v_mfma_f32_16x16x32_bf16 v[76:79], v[128:131], v[184:187], v[76:79]
	v_mfma_f32_16x16x32_bf16 v[124:127], v[132:135], v[148:151], v[124:127]
	v_mfma_f32_16x16x32_bf16 v[120:123], v[140:143], v[148:151], v[120:123]
	v_mfma_f32_16x16x32_bf16 v[104:107], v[140:143], v[156:159], v[104:107]
	v_mfma_f32_16x16x32_bf16 v[108:111], v[132:135], v[156:159], v[108:111]
	v_mfma_f32_16x16x32_bf16 v[92:95], v[132:135], v[180:183], v[92:95]
	v_mfma_f32_16x16x32_bf16 v[88:91], v[140:143], v[180:183], v[88:91]
	v_mfma_f32_16x16x32_bf16 v[72:75], v[140:143], v[188:191], v[72:75]
	v_mfma_f32_16x16x32_bf16 v[76:79], v[132:135], v[188:191], v[76:79]
	s_barrier
	s_add_i32 s57, s49, s30
	v_lshl_add_u64 v[164:165], s[26:27], 0, v[168:169]
	s_mov_b32 m0, s57
	ds_read_b128 v[192:195], v202
	ds_read_b128 v[204:207], v202 offset:1024
	ds_read_b128 v[208:211], v202 offset:2048
	ds_read_b128 v[212:215], v202 offset:3072
	global_load_lds_dwordx4 v[164:165], off
	v_lshl_add_u64 v[216:217], s[26:27], 0, v[172:173]
	s_add_i32 m0, s57, 0x2000
	s_nop 0
	global_load_lds_dwordx4 v[216:217], off
	s_barrier
	s_waitcnt lgkmcnt(0)
	s_waitcnt lgkmcnt(0)
	v_mfma_f32_16x16x32_bf16 v[116:119], v[192:195], v[144:147], v[116:119]
	v_mfma_f32_16x16x32_bf16 v[112:115], v[208:211], v[144:147], v[112:115]
	v_mfma_f32_16x16x32_bf16 v[96:99], v[208:211], v[152:155], v[96:99]
	v_mfma_f32_16x16x32_bf16 v[100:103], v[192:195], v[152:155], v[100:103]
	v_mfma_f32_16x16x32_bf16 v[84:87], v[192:195], v[160:163], v[84:87]
	v_mfma_f32_16x16x32_bf16 v[80:83], v[208:211], v[160:163], v[80:83]
	v_mfma_f32_16x16x32_bf16 v[64:67], v[208:211], v[184:187], v[64:67]
	v_mfma_f32_16x16x32_bf16 v[68:71], v[192:195], v[184:187], v[68:71]
	v_mfma_f32_16x16x32_bf16 v[116:119], v[204:207], v[148:151], v[116:119]
	v_mfma_f32_16x16x32_bf16 v[112:115], v[212:215], v[148:151], v[112:115]
	v_mfma_f32_16x16x32_bf16 v[96:99], v[212:215], v[156:159], v[96:99]
	v_mfma_f32_16x16x32_bf16 v[100:103], v[204:207], v[156:159], v[100:103]
	v_mfma_f32_16x16x32_bf16 v[84:87], v[204:207], v[180:183], v[84:87]
	v_mfma_f32_16x16x32_bf16 v[80:83], v[212:215], v[180:183], v[80:83]
	v_mfma_f32_16x16x32_bf16 v[64:67], v[212:215], v[188:191], v[64:67]
	v_mfma_f32_16x16x32_bf16 v[68:71], v[204:207], v[188:191], v[68:71]
	s_mov_b32 m0, s34
	v_lshl_add_u64 v[218:219], s[24:25], 0, v[166:167]
	s_barrier
	ds_read_b128 v[144:147], v201 offset:16384
	ds_read_b128 v[148:151], v201 offset:17408
	ds_read_b128 v[152:155], v201 offset:18432
	ds_read_b128 v[156:159], v201 offset:19456
	ds_read_b128 v[160:163], v201 offset:20480
	ds_read_b128 v[180:183], v201 offset:21504
	ds_read_b128 v[184:187], v201 offset:22528
	ds_read_b128 v[188:191], v201 offset:23552
	global_load_lds_dwordx4 v[218:219], off
	v_lshl_add_u64 v[220:221], s[24:25], 0, v[170:171]
	s_mov_b32 m0, s35
	s_nop 0
	global_load_lds_dwordx4 v[220:221], off
	s_barrier
	s_waitcnt lgkmcnt(0)
	s_waitcnt lgkmcnt(0)
	v_mfma_f32_16x16x32_bf16 v[60:63], v[128:131], v[144:147], v[60:63]
	v_mfma_f32_16x16x32_bf16 v[56:59], v[136:139], v[144:147], v[56:59]
	v_mfma_f32_16x16x32_bf16 v[40:43], v[136:139], v[152:155], v[40:43]
	v_mfma_f32_16x16x32_bf16 v[44:47], v[128:131], v[152:155], v[44:47]
	v_mfma_f32_16x16x32_bf16 v[28:31], v[128:131], v[160:163], v[28:31]
	v_mfma_f32_16x16x32_bf16 v[24:27], v[136:139], v[160:163], v[24:27]
	v_mfma_f32_16x16x32_bf16 v[8:11], v[136:139], v[184:187], v[8:11]
	v_mfma_f32_16x16x32_bf16 v[12:15], v[128:131], v[184:187], v[12:15]
	v_mfma_f32_16x16x32_bf16 v[60:63], v[132:135], v[148:151], v[60:63]
	v_mfma_f32_16x16x32_bf16 v[56:59], v[140:143], v[148:151], v[56:59]
	v_mfma_f32_16x16x32_bf16 v[40:43], v[140:143], v[156:159], v[40:43]
	v_mfma_f32_16x16x32_bf16 v[44:47], v[132:135], v[156:159], v[44:47]
	v_mfma_f32_16x16x32_bf16 v[28:31], v[132:135], v[180:183], v[28:31]
	v_mfma_f32_16x16x32_bf16 v[24:27], v[140:143], v[180:183], v[24:27]
	v_mfma_f32_16x16x32_bf16 v[8:11], v[140:143], v[188:191], v[8:11]
	v_mfma_f32_16x16x32_bf16 v[12:15], v[132:135], v[188:191], v[12:15]
	s_barrier
; #define PG8_STAGE(bufoff, gbase, voff) do { _Pragma("unroll") for (int _i = 0; _i < 2; ++_i) \
;         __builtin_amdgcn_global_load_lds((const unsigned*)((const char*)(gbase) + (voff)[_i]), (LAS unsigned*)(lds + (bufoff) + ldsw + _i * 8192), 16, 0, 0); } while (0)
; #define PG8_LDA(dst, b, h) do { _Pragma("unroll") for (int m = 0; m < 4; ++m) _Pragma("unroll") for (int k = 0; k < 2; ++k) dst[m][k] = *(const LAS bf16x8*)(lds + PG8_SA(b, h) + aoff + m * 2048 + k * 1024); } while (0)
; #define PG8_LDB(dst, b, h) do { _Pragma("unroll") for (int n = 0; n < 2; ++n) _Pragma("unroll") for (int k = 0; k < 2; ++k) dst[n][k] = *(const LAS bf16x8*)(lds + PG8_SB(b, h) + boff + n * 2048 + k * 1024); } while (0)
; #define PG8_MMA(ai, bj, At, Bt) do { __builtin_amdgcn_s_setprio(1); _Pragma("unroll") for (int m = 0; m < 4; ++m) _Pragma("unroll") for (int n = 0; n < 2; ++n) _Pragma("unroll") for (int k = 0; k < 2; ++k) \
;         acc[ai][bj][m][n] = __builtin_amdgcn_mfma_f32_16x16x32_bf16(Bt[n][k], At[m][k], acc[ai][bj][m][n], 0, 0, 0); __builtin_amdgcn_s_setprio(0); } while (0)
; #define PG8_WAIT_V(n) asm volatile("s_waitcnt vmcnt(" #n ")" ::: "memory")
; #define PG8_WAIT_L(n) asm volatile("s_waitcnt lgkmcnt(" #n ")" ::: "memory")
; #define PG8_BAR __builtin_amdgcn_s_barrier()
; #define PG8_SCHED __builtin_amdgcn_sched_barrier(0)
; template <class Epi>
; DEVI void gemm_phase(LAS unsigned char* lds, const bf16_t* gA, const bf16_t* gBt, const int lda, const int ldb, const int K, const StaticOrder S_, const Epi E) {
;     ...
;             PG8_STAGE(PG8_SB(0, 1), b2 + hstepB, voffB);
;             PG8_WAIT_V(6); PG8_BAR; PG8_MMA(1, 1, At, B1); PG8_BAR;
;             PG8_LDB(B0, 1, 0); PG8_SCHED; PG8_LDA(At, 1, 0); PG8_STAGE(PG8_SA(0, 1), a2 + hstepA, voffA);
;             PG8_WAIT_L(8); PG8_BAR; PG8_WAIT_L(0); PG8_MMA(0, 0, At, B0); PG8_BAR; PG8_SCHED;
;             PG8_LDB(B1, 1, 1); PG8_STAGE(PG8_SB(1, 0), b3, voffB);
;             PG8_BAR; PG8_WAIT_L(0); PG8_MMA(0, 1, At, B1); PG8_BAR;
	s_add_u32 s26, s26, s10
	s_addc_u32 s27, s27, s11
	s_add_i32 s57, s50, s30
	v_lshl_add_u64 v[222:223], s[26:27], 0, v[168:169]
	s_mov_b32 m0, s57
	v_lshl_add_u64 v[224:225], s[26:27], 0, v[172:173]
	global_load_lds_dwordx4 v[222:223], off
	s_add_i32 m0, s57, 0x2000
	s_nop 0
	global_load_lds_dwordx4 v[224:225], off
	s_waitcnt vmcnt(6)
	s_barrier
	v_mfma_f32_16x16x32_bf16 v[52:55], v[192:195], v[144:147], v[52:55]
	v_mfma_f32_16x16x32_bf16 v[48:51], v[208:211], v[144:147], v[48:51]
	v_mfma_f32_16x16x32_bf16 v[32:35], v[208:211], v[152:155], v[32:35]
	v_mfma_f32_16x16x32_bf16 v[36:39], v[192:195], v[152:155], v[36:39]
	v_mfma_f32_16x16x32_bf16 v[20:23], v[192:195], v[160:163], v[20:23]
	v_mfma_f32_16x16x32_bf16 v[16:19], v[208:211], v[160:163], v[16:19]
	v_mfma_f32_16x16x32_bf16 v[0:3], v[208:211], v[184:187], v[0:3]
	v_mfma_f32_16x16x32_bf16 v[4:7], v[192:195], v[184:187], v[4:7]
	v_mfma_f32_16x16x32_bf16 v[52:55], v[204:207], v[148:151], v[52:55]
	v_mfma_f32_16x16x32_bf16 v[48:51], v[212:215], v[148:151], v[48:51]
	v_mfma_f32_16x16x32_bf16 v[32:35], v[212:215], v[156:159], v[32:35]
	v_mfma_f32_16x16x32_bf16 v[36:39], v[204:207], v[156:159], v[36:39]
	v_mfma_f32_16x16x32_bf16 v[20:23], v[204:207], v[180:183], v[20:23]
	v_mfma_f32_16x16x32_bf16 v[16:19], v[212:215], v[180:183], v[16:19]
	v_mfma_f32_16x16x32_bf16 v[0:3], v[212:215], v[188:191], v[0:3]
	v_mfma_f32_16x16x32_bf16 v[4:7], v[204:207], v[188:191], v[4:7]
	s_add_i32 s26, 0, 0x18000
	v_add_u32_e32 v140, s26, v196
	s_barrier
	ds_read_b128 v[128:131], v140
	ds_read_b128 v[132:135], v140 offset:1024
	ds_read_b128 v[136:139], v140 offset:2048
	ds_read_b128 v[140:143], v140 offset:3072
	s_add_u32 s24, s24, s2
	s_addc_u32 s25, s25, s3
	s_mov_b32 m0, s36
	v_lshl_add_u64 v[192:193], s[24:25], 0, v[166:167]
	ds_read_b128 v[144:147], v201 offset:32768
	ds_read_b128 v[148:151], v201 offset:33792
	ds_read_b128 v[152:155], v201 offset:34816
	ds_read_b128 v[156:159], v201 offset:35840
	ds_read_b128 v[160:163], v201 offset:36864
	ds_read_b128 v[180:183], v201 offset:37888
	ds_read_b128 v[184:187], v201 offset:38912
	ds_read_b128 v[188:191], v201 offset:39936
	global_load_lds_dwordx4 v[192:193], off
	v_lshl_add_u64 v[192:193], s[24:25], 0, v[170:171]
	s_mov_b32 m0, s37
	s_nop 0
	global_load_lds_dwordx4 v[192:193], off
	s_waitcnt lgkmcnt(8)
	s_barrier
	s_waitcnt lgkmcnt(0)
	s_waitcnt lgkmcnt(0)
	v_mfma_f32_16x16x32_bf16 v[124:127], v[128:131], v[144:147], v[124:127]
	v_mfma_f32_16x16x32_bf16 v[120:123], v[136:139], v[144:147], v[120:123]
	v_mfma_f32_16x16x32_bf16 v[104:107], v[136:139], v[152:155], v[104:107]
	v_mfma_f32_16x16x32_bf16 v[108:111], v[128:131], v[152:155], v[108:111]
	v_mfma_f32_16x16x32_bf16 v[92:95], v[128:131], v[160:163], v[92:95]
	v_mfma_f32_16x16x32_bf16 v[88:91], v[136:139], v[160:163], v[88:91]
	v_mfma_f32_16x16x32_bf16 v[72:75], v[136:139], v[184:187], v[72:75]
	v_mfma_f32_16x16x32_bf16 v[76:79], v[128:131], v[184:187], v[76:79]
	v_mfma_f32_16x16x32_bf16 v[124:127], v[132:135], v[148:151], v[124:127]
	v_mfma_f32_16x16x32_bf16 v[120:123], v[140:143], v[148:151], v[120:123]
	v_mfma_f32_16x16x32_bf16 v[104:107], v[140:143], v[156:159], v[104:107]
	v_mfma_f32_16x16x32_bf16 v[108:111], v[132:135], v[156:159], v[108:111]
	v_mfma_f32_16x16x32_bf16 v[92:95], v[132:135], v[180:183], v[92:95]
	v_mfma_f32_16x16x32_bf16 v[88:91], v[140:143], v[180:183], v[88:91]
	v_mfma_f32_16x16x32_bf16 v[72:75], v[140:143], v[188:191], v[72:75]
	v_mfma_f32_16x16x32_bf16 v[76:79], v[132:135], v[188:191], v[76:79]
	s_barrier
	s_add_i32 s24, 0, 0x1c000
	s_add_i32 s25, s26, s30
	v_add_u32_e32 v212, s24, v196
	v_lshl_add_u64 v[164:165], v[164:165], 0, s[16:17]
	s_mov_b32 m0, s25
	ds_read_b128 v[192:195], v212
	ds_read_b128 v[204:207], v212 offset:1024
	ds_read_b128 v[208:211], v212 offset:2048
	ds_read_b128 v[212:215], v212 offset:3072
	global_load_lds_dwordx4 v[164:165], off
	v_lshl_add_u64 v[164:165], v[216:217], 0, s[16:17]
	s_add_i32 m0, s25, 0x2000
	s_nop 0
	global_load_lds_dwordx4 v[164:165], off
	s_barrier
; #define LAS __attribute__((address_space(3)))
; #define PG8_STAGE(bufoff, gbase, voff) do { _Pragma("unroll") for (int _i = 0; _i < 2; ++_i) \
;         __builtin_amdgcn_global_load_lds((const unsigned*)((const char*)(gbase) + (voff)[_i]), (LAS unsigned*)(lds + (bufoff) + ldsw + _i * 8192), 16, 0, 0); } while (0)
; #define PG8_LDA(dst, b, h) do { _Pragma("unroll") for (int m = 0; m < 4; ++m) _Pragma("unroll") for (int k = 0; k < 2; ++k) dst[m][k] = *(const LAS bf16x8*)(lds + PG8_SA(b, h) + aoff + m * 2048 + k * 1024); } while (0)
; #define PG8_MMA(ai, bj, At, Bt) do { __builtin_amdgcn_s_setprio(1); _Pragma("unroll") for (int m = 0; m < 4; ++m) _Pragma("unroll") for (int n = 0; n < 2; ++n) _Pragma("unroll") for (int k = 0; k < 2; ++k) \
;         acc[ai][bj][m][n] = __builtin_amdgcn_mfma_f32_16x16x32_bf16(Bt[n][k], At[m][k], acc[ai][bj][m][n], 0, 0, 0); __builtin_amdgcn_s_setprio(0); } while (0)
; #define PG8_WAIT_V(n) asm volatile("s_waitcnt vmcnt(" #n ")" ::: "memory")
; #define PG8_WAIT_L(n) asm volatile("s_waitcnt lgkmcnt(" #n ")" ::: "memory")
; #define PG8_BAR __builtin_amdgcn_s_barrier()
; #define PG8_SCHED __builtin_amdgcn_sched_barrier(0)
; template <class Epi>
; DEVI void gemm_phase(LAS unsigned char* lds, const bf16_t* gA, const bf16_t* gBt, const int lda, const int ldb, const int K, const StaticOrder S_, const Epi E) {
;     ...
;             PG8_BAR; PG8_WAIT_L(0); PG8_MMA(0, 1, At, B1); PG8_BAR;
;             PG8_LDA(At, 1, 1); PG8_STAGE(PG8_SA(1, 0), a3, voffA);
;             PG8_BAR; PG8_WAIT_L(0); PG8_MMA(1, 0, At, B0); PG8_BAR; PG8_SCHED;
;             PG8_STAGE(PG8_SB(1, 1), b3 + hstepB, voffB);
;             PG8_WAIT_V(6); PG8_BAR; PG8_MMA(1, 1, At, B1); PG8_BAR;
;         }
;         E(acc, cur, wr, wc, fr, fq, (const LAS float*)(lds + STAGE_BYTES + (ui & 1) * 2048));
	s_waitcnt lgkmcnt(0)
	s_waitcnt lgkmcnt(0)
	v_mfma_f32_16x16x32_bf16 v[116:119], v[192:195], v[144:147], v[116:119]
	v_mfma_f32_16x16x32_bf16 v[112:115], v[208:211], v[144:147], v[112:115]
	v_mfma_f32_16x16x32_bf16 v[96:99], v[208:211], v[152:155], v[96:99]
	v_mfma_f32_16x16x32_bf16 v[100:103], v[192:195], v[152:155], v[100:103]
	v_mfma_f32_16x16x32_bf16 v[84:87], v[192:195], v[160:163], v[84:87]
	v_mfma_f32_16x16x32_bf16 v[80:83], v[208:211], v[160:163], v[80:83]
	v_mfma_f32_16x16x32_bf16 v[64:67], v[208:211], v[184:187], v[64:67]
	v_mfma_f32_16x16x32_bf16 v[68:71], v[192:195], v[184:187], v[68:71]
	v_mfma_f32_16x16x32_bf16 v[116:119], v[204:207], v[148:151], v[116:119]
	v_mfma_f32_16x16x32_bf16 v[112:115], v[212:215], v[148:151], v[112:115]
	v_mfma_f32_16x16x32_bf16 v[96:99], v[212:215], v[156:159], v[96:99]
	v_mfma_f32_16x16x32_bf16 v[100:103], v[204:207], v[156:159], v[100:103]
	v_mfma_f32_16x16x32_bf16 v[84:87], v[204:207], v[180:183], v[84:87]
	v_mfma_f32_16x16x32_bf16 v[80:83], v[212:215], v[180:183], v[80:83]
	v_mfma_f32_16x16x32_bf16 v[64:67], v[212:215], v[188:191], v[64:67]
	v_mfma_f32_16x16x32_bf16 v[68:71], v[204:207], v[188:191], v[68:71]
	s_mov_b32 m0, s39
	v_lshl_add_u64 v[164:165], v[218:219], 0, s[16:17]
	s_barrier
	ds_read_b128 v[144:147], v201 offset:49152
	ds_read_b128 v[148:151], v201 offset:50176
	ds_read_b128 v[152:155], v201 offset:51200
	ds_read_b128 v[156:159], v201 offset:52224
	ds_read_b128 v[160:163], v201 offset:53248
	ds_read_b128 v[180:183], v201 offset:54272
	ds_read_b128 v[184:187], v201 offset:55296
	ds_read_b128 v[188:191], v201 offset:56320
	global_load_lds_dwordx4 v[164:165], off
	v_lshl_add_u64 v[164:165], v[220:221], 0, s[16:17]
	s_mov_b32 m0, s40
	s_nop 0
	global_load_lds_dwordx4 v[164:165], off
	s_barrier
	s_waitcnt lgkmcnt(0)
	s_waitcnt lgkmcnt(0)
	v_mfma_f32_16x16x32_bf16 v[60:63], v[128:131], v[144:147], v[60:63]
	v_mfma_f32_16x16x32_bf16 v[56:59], v[136:139], v[144:147], v[56:59]
	v_mfma_f32_16x16x32_bf16 v[40:43], v[136:139], v[152:155], v[40:43]
	v_mfma_f32_16x16x32_bf16 v[44:47], v[128:131], v[152:155], v[44:47]
	v_mfma_f32_16x16x32_bf16 v[28:31], v[128:131], v[160:163], v[28:31]
	v_mfma_f32_16x16x32_bf16 v[24:27], v[136:139], v[160:163], v[24:27]
	v_mfma_f32_16x16x32_bf16 v[8:11], v[136:139], v[184:187], v[8:11]
	v_mfma_f32_16x16x32_bf16 v[12:15], v[128:131], v[184:187], v[12:15]
	v_mfma_f32_16x16x32_bf16 v[60:63], v[132:135], v[148:151], v[60:63]
	v_mfma_f32_16x16x32_bf16 v[56:59], v[140:143], v[148:151], v[56:59]
	v_mfma_f32_16x16x32_bf16 v[40:43], v[140:143], v[156:159], v[40:43]
	v_mfma_f32_16x16x32_bf16 v[44:47], v[132:135], v[156:159], v[44:47]
	v_mfma_f32_16x16x32_bf16 v[28:31], v[132:135], v[180:183], v[28:31]
	v_mfma_f32_16x16x32_bf16 v[24:27], v[140:143], v[180:183], v[24:27]
	v_mfma_f32_16x16x32_bf16 v[8:11], v[140:143], v[188:191], v[8:11]
	v_mfma_f32_16x16x32_bf16 v[12:15], v[132:135], v[188:191], v[12:15]
	s_barrier
	s_add_i32 s24, s24, s30
	v_lshl_add_u64 v[128:129], v[222:223], 0, s[16:17]
	s_mov_b32 m0, s24
	s_nop 0
	global_load_lds_dwordx4 v[128:129], off
	v_lshl_add_u64 v[128:129], v[224:225], 0, s[16:17]
	s_add_i32 m0, s24, 0x2000
	s_nop 0
	global_load_lds_dwordx4 v[128:129], off
	s_waitcnt vmcnt(6)
	s_barrier
	v_mfma_f32_16x16x32_bf16 v[52:55], v[192:195], v[144:147], v[52:55]
	v_mfma_f32_16x16x32_bf16 v[48:51], v[208:211], v[144:147], v[48:51]
	v_mfma_f32_16x16x32_bf16 v[32:35], v[208:211], v[152:155], v[32:35]
	v_mfma_f32_16x16x32_bf16 v[36:39], v[192:195], v[152:155], v[36:39]
	v_mfma_f32_16x16x32_bf16 v[20:23], v[192:195], v[160:163], v[20:23]
	v_mfma_f32_16x16x32_bf16 v[16:19], v[208:211], v[160:163], v[16:19]
	v_mfma_f32_16x16x32_bf16 v[0:3], v[208:211], v[184:187], v[0:3]
	v_mfma_f32_16x16x32_bf16 v[4:7], v[192:195], v[184:187], v[4:7]
	v_mfma_f32_16x16x32_bf16 v[52:55], v[204:207], v[148:151], v[52:55]
	v_mfma_f32_16x16x32_bf16 v[48:51], v[212:215], v[148:151], v[48:51]
	v_mfma_f32_16x16x32_bf16 v[32:35], v[212:215], v[156:159], v[32:35]
	v_mfma_f32_16x16x32_bf16 v[36:39], v[204:207], v[156:159], v[36:39]
	v_mfma_f32_16x16x32_bf16 v[20:23], v[204:207], v[180:183], v[20:23]
	v_mfma_f32_16x16x32_bf16 v[16:19], v[212:215], v[180:183], v[16:19]
	v_mfma_f32_16x16x32_bf16 v[0:3], v[212:215], v[188:191], v[0:3]
	v_mfma_f32_16x16x32_bf16 v[4:7], v[204:207], v[188:191], v[4:7]
	s_add_u32 s4, s4, 0x100
	s_addc_u32 s5, s5, 0
	s_add_u32 s54, s54, 0x100
	s_addc_u32 s55, s55, 0
	s_cmp_ge_i32 s56, s41
	s_mov_b32 s24, s56
	s_barrier
	s_cbranch_scc0 .LBB0_2589
	v_readlane_b32 s56, v241, 26
	v_readlane_b32 s58, v241, 28
	v_readlane_b32 s57, v241, 27
	v_readlane_b32 s59, v241, 29
